# no grid barrier between RWKV prep and mixers: per-sequence arrival counters gate the scans, a phase-A-part-1 counter gates the work queue; sample tokens prepared first, blocks 0-63 skip the prep
# speedup vs baseline: 1.0170x; 1.0103x over previous
.La1_mine:
	v_mov_b32_e32 v238, 0x200f0
	ds_read_b64 v[236:237], v238
	s_waitcnt lgkmcnt(0)
	v_readfirstlane_b32 s20, v236
	v_readfirstlane_b32 s21, v237
	s_barrier
	v_and_b32_e32 v236, 63, v0
	v_lshrrev_b32_e32 v237, 6, v0
	v_lshrrev_b32_e32 v238, 3, v236
	v_lshrrev_b32_e32 v239, 4, v236
	s_nop 0
	v_readfirstlane_b32 s0, v237
	v_add_u32_e32 v200, 0, v239
	v_xor_b32_e32 v200, v200, v236
	v_and_b32_e32 v200, 7, v200
	v_lshlrev_b32_e32 v200, 4, v200
	v_lshl_add_u32 v130, v237, 5, v238
	v_add_u32_e32 v130, 0, v130
	v_mul_u32_u24_e32 v130, 0x800, v130
	v_add_u32_e32 v200, v200, v130
	v_add_u32_e32 v201, 4, v239
	v_xor_b32_e32 v201, v201, v236
	v_and_b32_e32 v201, 7, v201
	v_lshlrev_b32_e32 v201, 4, v201
	v_lshl_add_u32 v130, v237, 5, v238
	v_add_u32_e32 v130, 8, v130
	v_mul_u32_u24_e32 v130, 0x800, v130
	v_add_u32_e32 v201, v201, v130
	v_add_u32_e32 v202, 8, v239
	v_xor_b32_e32 v202, v202, v236
	v_and_b32_e32 v202, 7, v202
	v_lshlrev_b32_e32 v202, 4, v202
	v_lshl_add_u32 v130, v237, 5, v238
	v_add_u32_e32 v130, 16, v130
	v_mul_u32_u24_e32 v130, 0x800, v130
	v_add_u32_e32 v202, v202, v130
	v_add_u32_e32 v203, 12, v239
	v_xor_b32_e32 v203, v203, v236
	v_and_b32_e32 v203, 7, v203
	v_lshlrev_b32_e32 v203, 4, v203
	v_lshl_add_u32 v130, v237, 5, v238
	v_add_u32_e32 v130, 24, v130
	v_mul_u32_u24_e32 v130, 0x800, v130
	v_add_u32_e32 v203, v203, v130
	v_add_u32_e32 v204, 0, v239
	v_xor_b32_e32 v204, v204, v236
	v_and_b32_e32 v204, 7, v204
	v_lshlrev_b32_e32 v204, 4, v204
	v_lshl_add_u32 v130, v237, 4, v238
	v_add_u32_e32 v130, 0, v130
	v_mul_u32_u24_e32 v130, 0x800, v130
	v_add_u32_e32 v204, v204, v130
	v_add_u32_e32 v205, 4, v239
	v_xor_b32_e32 v205, v205, v236
	v_and_b32_e32 v205, 7, v205
	v_lshlrev_b32_e32 v205, 4, v205
	v_lshl_add_u32 v130, v237, 4, v238
	v_add_u32_e32 v130, 8, v130
	v_mul_u32_u24_e32 v130, 0x800, v130
	v_add_u32_e32 v205, v205, v130
	v_and_b32_e32 v238, 15, v236
	v_lshrrev_b32_e32 v130, 1, v238
	v_xor_b32_e32 v130, v130, v239
	v_lshlrev_b32_e32 v130, 4, v130
	v_lshrrev_b32_e32 v236, 1, v237
	v_lshl_add_u32 v236, v236, 6, v238
	v_lshl_add_u32 v236, v236, 7, v130
	v_and_b32_e32 v237, 1, v237
	v_lshl_add_u32 v237, v237, 6, v238
	v_lshl_add_u32 v237, v237, 7, v130
	v_add_u32_e32 v218, 0x100, v236
	v_xor_b32_e32 v225, 64, v218
	v_add_u32_e32 v230, 0x8100, v237
	v_xor_b32_e32 v233, 64, v230
	v_add_u32_e32 v219, 0xc100, v236
	v_xor_b32_e32 v228, 64, v219
	v_add_u32_e32 v231, 0x14100, v237
	v_xor_b32_e32 v234, 64, v231
	v_add_u32_e32 v224, 0x18100, v236
	v_xor_b32_e32 v229, 64, v224
	v_add_u32_e32 v232, 0x20100, v237
	v_xor_b32_e32 v235, 64, v232
	s_lshl_b32 s1, s0, 12
	s_add_u32 s8, s1, 0x100
	s_lshl_b32 s1, s0, 11
	s_add_u32 s9, s1, 0x8100
	v_and_b32_e32 v238, 63, v0
	v_lshrrev_b32_e32 v239, 6, v0
	v_and_b32_e32 v1, 15, v238
	v_lshrrev_b32_e32 v238, 4, v238
	v_lshrrev_b32_e32 v130, 1, v239
	v_lshl_add_u32 v1, v130, 6, v1
	v_and_b32_e32 v239, 1, v239
	v_lshlrev_b32_e32 v236, 11, v1
	v_lshl_add_u32 v236, v239, 7, v236
	v_lshl_add_u32 v236, v238, 3, v236
	v_mul_u32_u24_e32 v237, 0x2200, v1
	v_lshl_add_u32 v237, v239, 8, v237
	v_lshl_add_u32 v237, v238, 4, v237
	s_and_b32 s1, s2, 31
	s_lshr_b32 s22, s2, 5
	s_lshl_b32 s23, s1, 19
	s_add_u32 s4, s26, s23
	s_addc_u32 s5, s27, 0
	v_readlane_b32 s6, v254, 57
	v_readlane_b32 s7, v254, 58
	s_lshl_b32 s50, s22, 1
	s_add_u32 s50, s50, 1
	s_cmp_eq_u32 s22, 4
	s_cselect_b32 s50, 0, s50
	s_lshl_b32 s51, s50, 18
	s_add_u32 s51, s51, 0x400000
	s_add_u32 s6, s6, s51
	s_addc_u32 s7, s7, 0
	s_mov_b32 s12, 0xbfb8aa3b
	s_add_u32 s52, s28, 0x4400000
	s_addc_u32 s53, s29, 0
	s_add_u32 s52, s52, s23
	s_addc_u32 s53, s53, 0
	s_sub_u32 s51, s50, 1
	s_lshl_b32 s51, s51, 8
	s_add_u32 s52, s52, s51
	s_addc_u32 s53, s53, 0
	s_cmp_eq_u32 s22, 4
	s_cbranch_scc1 .La1_p
	s_mov_b32 m0, s8
	s_nop 0
	global_load_lds_dwordx4 v200, s[4:5]
	s_add_u32 m0, s8, 0x400
	s_nop 0
	global_load_lds_dwordx4 v201, s[4:5]
	s_add_u32 m0, s8, 0x800
	s_nop 0
	global_load_lds_dwordx4 v202, s[4:5]
	s_add_u32 m0, s8, 0xc00
	s_nop 0
	global_load_lds_dwordx4 v203, s[4:5]
	s_mov_b32 m0, s9
	s_nop 0
	global_load_lds_dwordx4 v204, s[6:7]
	s_add_u32 m0, s9, 0x400
	s_nop 0
	global_load_lds_dwordx4 v205, s[6:7]
	s_add_u32 s4, s4, 0x80
	s_addc_u32 s5, s5, 0
	s_add_u32 s6, s6, 0x80
	s_addc_u32 s7, s7, 0
	s_add_u32 m0, s8, 0xc000
	s_nop 0
	global_load_lds_dwordx4 v200, s[4:5]
	s_add_u32 m0, s8, 0xc400
	s_nop 0
	global_load_lds_dwordx4 v201, s[4:5]
	s_add_u32 m0, s8, 0xc800
	s_nop 0
	global_load_lds_dwordx4 v202, s[4:5]
	s_add_u32 m0, s8, 0xcc00
	s_nop 0
	global_load_lds_dwordx4 v203, s[4:5]
	s_add_u32 m0, s9, 0xc000
	s_nop 0
	global_load_lds_dwordx4 v204, s[6:7]
	s_add_u32 m0, s9, 0xc400
	s_nop 0
	global_load_lds_dwordx4 v205, s[6:7]
	s_add_u32 s4, s4, 0x80
	s_addc_u32 s5, s5, 0
	s_add_u32 s6, s6, 0x80
	s_addc_u32 s7, s7, 0
	s_add_u32 m0, s8, 0x18000
	s_nop 0
	global_load_lds_dwordx4 v200, s[4:5]
	s_add_u32 m0, s8, 0x18400
	s_nop 0
	global_load_lds_dwordx4 v201, s[4:5]
	s_add_u32 m0, s8, 0x18800
	s_nop 0
	global_load_lds_dwordx4 v202, s[4:5]
	s_add_u32 m0, s8, 0x18c00
	s_nop 0
	global_load_lds_dwordx4 v203, s[4:5]
	s_add_u32 m0, s9, 0x18000
	s_nop 0
	global_load_lds_dwordx4 v204, s[6:7]
	s_add_u32 m0, s9, 0x18400
	s_nop 0
	global_load_lds_dwordx4 v205, s[6:7]
	s_add_u32 s4, s4, 0x80
	s_addc_u32 s5, s5, 0
	s_add_u32 s6, s6, 0x80
	s_addc_u32 s7, s7, 0
	s_waitcnt vmcnt(12)
	s_barrier
	ds_read_b128 v[136:139], v218 offset:0
	ds_read_b128 v[140:143], v218 offset:2048
	ds_read_b128 v[144:147], v218 offset:4096
	ds_read_b128 v[148:151], v218 offset:6144
	ds_read_b128 v[152:155], v230 offset:0
	ds_read_b128 v[156:159], v230 offset:2048
	ds_read_b128 v[160:163], v230 offset:4096
	ds_read_b128 v[164:167], v230 offset:6144
	s_waitcnt lgkmcnt(0)
	v_mfma_f32_16x16x32_bf16 v[2:5], v[152:155], v[136:139], 0
	ds_read_b128 v[168:171], v225 offset:0
	v_mfma_f32_16x16x32_bf16 v[6:9], v[156:159], v[136:139], 0
	ds_read_b128 v[172:175], v225 offset:2048
	v_mfma_f32_16x16x32_bf16 v[10:13], v[160:163], v[136:139], 0
	ds_read_b128 v[176:179], v225 offset:4096
	v_mfma_f32_16x16x32_bf16 v[14:17], v[164:167], v[136:139], 0
	ds_read_b128 v[180:183], v225 offset:6144
	v_mfma_f32_16x16x32_bf16 v[18:21], v[152:155], v[140:143], 0
	ds_read_b128 v[184:187], v233 offset:0
	v_mfma_f32_16x16x32_bf16 v[22:25], v[156:159], v[140:143], 0
	ds_read_b128 v[188:191], v233 offset:2048
	v_mfma_f32_16x16x32_bf16 v[26:29], v[160:163], v[140:143], 0
	ds_read_b128 v[192:195], v233 offset:4096
	v_mfma_f32_16x16x32_bf16 v[30:33], v[164:167], v[140:143], 0
	ds_read_b128 v[196:199], v233 offset:6144
	v_mfma_f32_16x16x32_bf16 v[34:37], v[152:155], v[144:147], 0
	v_mfma_f32_16x16x32_bf16 v[38:41], v[156:159], v[144:147], 0
	v_mfma_f32_16x16x32_bf16 v[42:45], v[160:163], v[144:147], 0
	v_mfma_f32_16x16x32_bf16 v[46:49], v[164:167], v[144:147], 0
	v_mfma_f32_16x16x32_bf16 v[50:53], v[152:155], v[148:151], 0
	v_mfma_f32_16x16x32_bf16 v[54:57], v[156:159], v[148:151], 0
	v_mfma_f32_16x16x32_bf16 v[58:61], v[160:163], v[148:151], 0
	v_mfma_f32_16x16x32_bf16 v[62:65], v[164:167], v[148:151], 0
	s_waitcnt vmcnt(6) lgkmcnt(0)
	s_barrier
	v_mfma_f32_16x16x32_bf16 v[2:5], v[184:187], v[168:171], v[2:5]
	ds_read_b128 v[136:139], v219 offset:0
	v_mfma_f32_16x16x32_bf16 v[6:9], v[188:191], v[168:171], v[6:9]
	ds_read_b128 v[140:143], v219 offset:2048
	v_mfma_f32_16x16x32_bf16 v[10:13], v[192:195], v[168:171], v[10:13]
	ds_read_b128 v[144:147], v219 offset:4096
	v_mfma_f32_16x16x32_bf16 v[14:17], v[196:199], v[168:171], v[14:17]
	ds_read_b128 v[148:151], v219 offset:6144
	v_mfma_f32_16x16x32_bf16 v[18:21], v[184:187], v[172:175], v[18:21]
	ds_read_b128 v[152:155], v231 offset:0
	v_mfma_f32_16x16x32_bf16 v[22:25], v[188:191], v[172:175], v[22:25]
	ds_read_b128 v[156:159], v231 offset:2048
	v_mfma_f32_16x16x32_bf16 v[26:29], v[192:195], v[172:175], v[26:29]
	ds_read_b128 v[160:163], v231 offset:4096
	v_mfma_f32_16x16x32_bf16 v[30:33], v[196:199], v[172:175], v[30:33]
	ds_read_b128 v[164:167], v231 offset:6144
	s_mov_b32 m0, s8
	v_mfma_f32_16x16x32_bf16 v[34:37], v[184:187], v[176:179], v[34:37]
	global_load_lds_dwordx4 v200, s[4:5]
	s_add_u32 m0, s8, 0x400
	v_mfma_f32_16x16x32_bf16 v[38:41], v[188:191], v[176:179], v[38:41]
	global_load_lds_dwordx4 v201, s[4:5]
	s_add_u32 m0, s8, 0x800
	v_mfma_f32_16x16x32_bf16 v[42:45], v[192:195], v[176:179], v[42:45]
	global_load_lds_dwordx4 v202, s[4:5]
	s_add_u32 m0, s8, 0xc00
	v_mfma_f32_16x16x32_bf16 v[46:49], v[196:199], v[176:179], v[46:49]
	global_load_lds_dwordx4 v203, s[4:5]
	s_mov_b32 m0, s9
	v_mfma_f32_16x16x32_bf16 v[50:53], v[184:187], v[180:183], v[50:53]
	global_load_lds_dwordx4 v204, s[6:7]
	s_add_u32 m0, s9, 0x400
	v_mfma_f32_16x16x32_bf16 v[54:57], v[188:191], v[180:183], v[54:57]
	global_load_lds_dwordx4 v205, s[6:7]
	v_mfma_f32_16x16x32_bf16 v[58:61], v[192:195], v[180:183], v[58:61]
	s_add_u32 s4, s4, 0x80
	s_addc_u32 s5, s5, 0
	v_mfma_f32_16x16x32_bf16 v[62:65], v[196:199], v[180:183], v[62:65]
	s_add_u32 s6, s6, 0x80
	s_addc_u32 s7, s7, 0
	s_waitcnt lgkmcnt(0)
	v_mfma_f32_16x16x32_bf16 v[2:5], v[152:155], v[136:139], v[2:5]
	ds_read_b128 v[168:171], v228 offset:0
	v_mfma_f32_16x16x32_bf16 v[6:9], v[156:159], v[136:139], v[6:9]
	ds_read_b128 v[172:175], v228 offset:2048
	v_mfma_f32_16x16x32_bf16 v[10:13], v[160:163], v[136:139], v[10:13]
	ds_read_b128 v[176:179], v228 offset:4096
	v_mfma_f32_16x16x32_bf16 v[14:17], v[164:167], v[136:139], v[14:17]
	ds_read_b128 v[180:183], v228 offset:6144
	v_mfma_f32_16x16x32_bf16 v[18:21], v[152:155], v[140:143], v[18:21]
	ds_read_b128 v[184:187], v234 offset:0
	v_mfma_f32_16x16x32_bf16 v[22:25], v[156:159], v[140:143], v[22:25]
	ds_read_b128 v[188:191], v234 offset:2048
	v_mfma_f32_16x16x32_bf16 v[26:29], v[160:163], v[140:143], v[26:29]
	ds_read_b128 v[192:195], v234 offset:4096
	v_mfma_f32_16x16x32_bf16 v[30:33], v[164:167], v[140:143], v[30:33]
	ds_read_b128 v[196:199], v234 offset:6144
	v_mfma_f32_16x16x32_bf16 v[34:37], v[152:155], v[144:147], v[34:37]
	v_mfma_f32_16x16x32_bf16 v[38:41], v[156:159], v[144:147], v[38:41]
	v_mfma_f32_16x16x32_bf16 v[42:45], v[160:163], v[144:147], v[42:45]
	v_mfma_f32_16x16x32_bf16 v[46:49], v[164:167], v[144:147], v[46:49]
	v_mfma_f32_16x16x32_bf16 v[50:53], v[152:155], v[148:151], v[50:53]
	v_mfma_f32_16x16x32_bf16 v[54:57], v[156:159], v[148:151], v[54:57]
	v_mfma_f32_16x16x32_bf16 v[58:61], v[160:163], v[148:151], v[58:61]
	v_mfma_f32_16x16x32_bf16 v[62:65], v[164:167], v[148:151], v[62:65]
	s_waitcnt vmcnt(6) lgkmcnt(0)
	s_barrier
	v_mfma_f32_16x16x32_bf16 v[2:5], v[184:187], v[168:171], v[2:5]
	ds_read_b128 v[136:139], v224 offset:0
	v_mfma_f32_16x16x32_bf16 v[6:9], v[188:191], v[168:171], v[6:9]
	ds_read_b128 v[140:143], v224 offset:2048
	v_mfma_f32_16x16x32_bf16 v[10:13], v[192:195], v[168:171], v[10:13]
	ds_read_b128 v[144:147], v224 offset:4096
	v_mfma_f32_16x16x32_bf16 v[14:17], v[196:199], v[168:171], v[14:17]
	ds_read_b128 v[148:151], v224 offset:6144
	v_mfma_f32_16x16x32_bf16 v[18:21], v[184:187], v[172:175], v[18:21]
	ds_read_b128 v[152:155], v232 offset:0
	v_mfma_f32_16x16x32_bf16 v[22:25], v[188:191], v[172:175], v[22:25]
	ds_read_b128 v[156:159], v232 offset:2048
	v_mfma_f32_16x16x32_bf16 v[26:29], v[192:195], v[172:175], v[26:29]
	ds_read_b128 v[160:163], v232 offset:4096
	v_mfma_f32_16x16x32_bf16 v[30:33], v[196:199], v[172:175], v[30:33]
	ds_read_b128 v[164:167], v232 offset:6144
	s_add_u32 m0, s8, 0xc000
	v_mfma_f32_16x16x32_bf16 v[34:37], v[184:187], v[176:179], v[34:37]
	global_load_lds_dwordx4 v200, s[4:5]
	s_add_u32 m0, s8, 0xc400
	v_mfma_f32_16x16x32_bf16 v[38:41], v[188:191], v[176:179], v[38:41]
	global_load_lds_dwordx4 v201, s[4:5]
	s_add_u32 m0, s8, 0xc800
	v_mfma_f32_16x16x32_bf16 v[42:45], v[192:195], v[176:179], v[42:45]
	global_load_lds_dwordx4 v202, s[4:5]
	s_add_u32 m0, s8, 0xcc00
	v_mfma_f32_16x16x32_bf16 v[46:49], v[196:199], v[176:179], v[46:49]
	global_load_lds_dwordx4 v203, s[4:5]
	s_add_u32 m0, s9, 0xc000
	v_mfma_f32_16x16x32_bf16 v[50:53], v[184:187], v[180:183], v[50:53]
	global_load_lds_dwordx4 v204, s[6:7]
	s_add_u32 m0, s9, 0xc400
	v_mfma_f32_16x16x32_bf16 v[54:57], v[188:191], v[180:183], v[54:57]
	global_load_lds_dwordx4 v205, s[6:7]
	v_mfma_f32_16x16x32_bf16 v[58:61], v[192:195], v[180:183], v[58:61]
	s_add_u32 s4, s4, 0x80
	s_addc_u32 s5, s5, 0
	v_mfma_f32_16x16x32_bf16 v[62:65], v[196:199], v[180:183], v[62:65]
	s_add_u32 s6, s6, 0x80
	s_addc_u32 s7, s7, 0
	s_waitcnt lgkmcnt(0)
	v_mfma_f32_16x16x32_bf16 v[2:5], v[152:155], v[136:139], v[2:5]
	ds_read_b128 v[168:171], v229 offset:0
	v_mfma_f32_16x16x32_bf16 v[6:9], v[156:159], v[136:139], v[6:9]
	ds_read_b128 v[172:175], v229 offset:2048
	v_mfma_f32_16x16x32_bf16 v[10:13], v[160:163], v[136:139], v[10:13]
	ds_read_b128 v[176:179], v229 offset:4096
	v_mfma_f32_16x16x32_bf16 v[14:17], v[164:167], v[136:139], v[14:17]
	ds_read_b128 v[180:183], v229 offset:6144
	v_mfma_f32_16x16x32_bf16 v[18:21], v[152:155], v[140:143], v[18:21]
	ds_read_b128 v[184:187], v235 offset:0
	v_mfma_f32_16x16x32_bf16 v[22:25], v[156:159], v[140:143], v[22:25]
	ds_read_b128 v[188:191], v235 offset:2048
	v_mfma_f32_16x16x32_bf16 v[26:29], v[160:163], v[140:143], v[26:29]
	ds_read_b128 v[192:195], v235 offset:4096
	v_mfma_f32_16x16x32_bf16 v[30:33], v[164:167], v[140:143], v[30:33]
	ds_read_b128 v[196:199], v235 offset:6144
	v_mfma_f32_16x16x32_bf16 v[34:37], v[152:155], v[144:147], v[34:37]
	v_mfma_f32_16x16x32_bf16 v[38:41], v[156:159], v[144:147], v[38:41]
	v_mfma_f32_16x16x32_bf16 v[42:45], v[160:163], v[144:147], v[42:45]
	v_mfma_f32_16x16x32_bf16 v[46:49], v[164:167], v[144:147], v[46:49]
	v_mfma_f32_16x16x32_bf16 v[50:53], v[152:155], v[148:151], v[50:53]
	v_mfma_f32_16x16x32_bf16 v[54:57], v[156:159], v[148:151], v[54:57]
	v_mfma_f32_16x16x32_bf16 v[58:61], v[160:163], v[148:151], v[58:61]
	v_mfma_f32_16x16x32_bf16 v[62:65], v[164:167], v[148:151], v[62:65]
	s_waitcnt vmcnt(6) lgkmcnt(0)
	s_barrier
	v_mfma_f32_16x16x32_bf16 v[2:5], v[184:187], v[168:171], v[2:5]
	ds_read_b128 v[136:139], v218 offset:0
	v_mfma_f32_16x16x32_bf16 v[6:9], v[188:191], v[168:171], v[6:9]
	ds_read_b128 v[140:143], v218 offset:2048
	v_mfma_f32_16x16x32_bf16 v[10:13], v[192:195], v[168:171], v[10:13]
	ds_read_b128 v[144:147], v218 offset:4096
	v_mfma_f32_16x16x32_bf16 v[14:17], v[196:199], v[168:171], v[14:17]
	ds_read_b128 v[148:151], v218 offset:6144
	v_mfma_f32_16x16x32_bf16 v[18:21], v[184:187], v[172:175], v[18:21]
	ds_read_b128 v[152:155], v230 offset:0
	v_mfma_f32_16x16x32_bf16 v[22:25], v[188:191], v[172:175], v[22:25]
	ds_read_b128 v[156:159], v230 offset:2048
	v_mfma_f32_16x16x32_bf16 v[26:29], v[192:195], v[172:175], v[26:29]
	ds_read_b128 v[160:163], v230 offset:4096
	v_mfma_f32_16x16x32_bf16 v[30:33], v[196:199], v[172:175], v[30:33]
	ds_read_b128 v[164:167], v230 offset:6144
	s_add_u32 m0, s8, 0x18000
	v_mfma_f32_16x16x32_bf16 v[34:37], v[184:187], v[176:179], v[34:37]
	global_load_lds_dwordx4 v200, s[4:5]
	s_add_u32 m0, s8, 0x18400
	v_mfma_f32_16x16x32_bf16 v[38:41], v[188:191], v[176:179], v[38:41]
	global_load_lds_dwordx4 v201, s[4:5]
	s_add_u32 m0, s8, 0x18800
	v_mfma_f32_16x16x32_bf16 v[42:45], v[192:195], v[176:179], v[42:45]
	global_load_lds_dwordx4 v202, s[4:5]
	s_add_u32 m0, s8, 0x18c00
	v_mfma_f32_16x16x32_bf16 v[46:49], v[196:199], v[176:179], v[46:49]
	global_load_lds_dwordx4 v203, s[4:5]
	s_add_u32 m0, s9, 0x18000
	v_mfma_f32_16x16x32_bf16 v[50:53], v[184:187], v[180:183], v[50:53]
	global_load_lds_dwordx4 v204, s[6:7]
	s_add_u32 m0, s9, 0x18400
	v_mfma_f32_16x16x32_bf16 v[54:57], v[188:191], v[180:183], v[54:57]
	global_load_lds_dwordx4 v205, s[6:7]
	v_mfma_f32_16x16x32_bf16 v[58:61], v[192:195], v[180:183], v[58:61]
	s_add_u32 s4, s4, 0x80
	s_addc_u32 s5, s5, 0
	v_mfma_f32_16x16x32_bf16 v[62:65], v[196:199], v[180:183], v[62:65]
	s_add_u32 s6, s6, 0x80
	s_addc_u32 s7, s7, 0
	s_waitcnt lgkmcnt(0)
	v_mfma_f32_16x16x32_bf16 v[2:5], v[152:155], v[136:139], v[2:5]
	ds_read_b128 v[168:171], v225 offset:0
	v_mfma_f32_16x16x32_bf16 v[6:9], v[156:159], v[136:139], v[6:9]
	ds_read_b128 v[172:175], v225 offset:2048
	v_mfma_f32_16x16x32_bf16 v[10:13], v[160:163], v[136:139], v[10:13]
	ds_read_b128 v[176:179], v225 offset:4096
	v_mfma_f32_16x16x32_bf16 v[14:17], v[164:167], v[136:139], v[14:17]
	ds_read_b128 v[180:183], v225 offset:6144
	v_mfma_f32_16x16x32_bf16 v[18:21], v[152:155], v[140:143], v[18:21]
	ds_read_b128 v[184:187], v233 offset:0
	v_mfma_f32_16x16x32_bf16 v[22:25], v[156:159], v[140:143], v[22:25]
	ds_read_b128 v[188:191], v233 offset:2048
	v_mfma_f32_16x16x32_bf16 v[26:29], v[160:163], v[140:143], v[26:29]
	ds_read_b128 v[192:195], v233 offset:4096
	v_mfma_f32_16x16x32_bf16 v[30:33], v[164:167], v[140:143], v[30:33]
	ds_read_b128 v[196:199], v233 offset:6144
	v_mfma_f32_16x16x32_bf16 v[34:37], v[152:155], v[144:147], v[34:37]
	v_mfma_f32_16x16x32_bf16 v[38:41], v[156:159], v[144:147], v[38:41]
	v_mfma_f32_16x16x32_bf16 v[42:45], v[160:163], v[144:147], v[42:45]
	v_mfma_f32_16x16x32_bf16 v[46:49], v[164:167], v[144:147], v[46:49]
	v_mfma_f32_16x16x32_bf16 v[50:53], v[152:155], v[148:151], v[50:53]
	v_mfma_f32_16x16x32_bf16 v[54:57], v[156:159], v[148:151], v[54:57]
	v_mfma_f32_16x16x32_bf16 v[58:61], v[160:163], v[148:151], v[58:61]
	v_mfma_f32_16x16x32_bf16 v[62:65], v[164:167], v[148:151], v[62:65]
	s_waitcnt vmcnt(6) lgkmcnt(0)
	s_barrier
	v_mfma_f32_16x16x32_bf16 v[2:5], v[184:187], v[168:171], v[2:5]
	ds_read_b128 v[136:139], v219 offset:0
	v_mfma_f32_16x16x32_bf16 v[6:9], v[188:191], v[168:171], v[6:9]
	ds_read_b128 v[140:143], v219 offset:2048
	v_mfma_f32_16x16x32_bf16 v[10:13], v[192:195], v[168:171], v[10:13]
	ds_read_b128 v[144:147], v219 offset:4096
	v_mfma_f32_16x16x32_bf16 v[14:17], v[196:199], v[168:171], v[14:17]
	ds_read_b128 v[148:151], v219 offset:6144
	v_mfma_f32_16x16x32_bf16 v[18:21], v[184:187], v[172:175], v[18:21]
	ds_read_b128 v[152:155], v231 offset:0
	v_mfma_f32_16x16x32_bf16 v[22:25], v[188:191], v[172:175], v[22:25]
	ds_read_b128 v[156:159], v231 offset:2048
	v_mfma_f32_16x16x32_bf16 v[26:29], v[192:195], v[172:175], v[26:29]
	ds_read_b128 v[160:163], v231 offset:4096
	v_mfma_f32_16x16x32_bf16 v[30:33], v[196:199], v[172:175], v[30:33]
	ds_read_b128 v[164:167], v231 offset:6144
	s_mov_b32 m0, s8
	v_mfma_f32_16x16x32_bf16 v[34:37], v[184:187], v[176:179], v[34:37]
	global_load_lds_dwordx4 v200, s[4:5]
	s_add_u32 m0, s8, 0x400
	v_mfma_f32_16x16x32_bf16 v[38:41], v[188:191], v[176:179], v[38:41]
	global_load_lds_dwordx4 v201, s[4:5]
	s_add_u32 m0, s8, 0x800
	v_mfma_f32_16x16x32_bf16 v[42:45], v[192:195], v[176:179], v[42:45]
	global_load_lds_dwordx4 v202, s[4:5]
	s_add_u32 m0, s8, 0xc00
	v_mfma_f32_16x16x32_bf16 v[46:49], v[196:199], v[176:179], v[46:49]
	global_load_lds_dwordx4 v203, s[4:5]
	s_mov_b32 m0, s9
	v_mfma_f32_16x16x32_bf16 v[50:53], v[184:187], v[180:183], v[50:53]
	global_load_lds_dwordx4 v204, s[6:7]
	s_add_u32 m0, s9, 0x400
	v_mfma_f32_16x16x32_bf16 v[54:57], v[188:191], v[180:183], v[54:57]
	global_load_lds_dwordx4 v205, s[6:7]
	v_mfma_f32_16x16x32_bf16 v[58:61], v[192:195], v[180:183], v[58:61]
	s_add_u32 s4, s4, 0x80
	s_addc_u32 s5, s5, 0
	v_mfma_f32_16x16x32_bf16 v[62:65], v[196:199], v[180:183], v[62:65]
	s_add_u32 s6, s6, 0x80
	s_addc_u32 s7, s7, 0
	s_waitcnt lgkmcnt(0)
	v_mfma_f32_16x16x32_bf16 v[2:5], v[152:155], v[136:139], v[2:5]
	ds_read_b128 v[168:171], v228 offset:0
	v_mfma_f32_16x16x32_bf16 v[6:9], v[156:159], v[136:139], v[6:9]
	ds_read_b128 v[172:175], v228 offset:2048
	v_mfma_f32_16x16x32_bf16 v[10:13], v[160:163], v[136:139], v[10:13]
	ds_read_b128 v[176:179], v228 offset:4096
	v_mfma_f32_16x16x32_bf16 v[14:17], v[164:167], v[136:139], v[14:17]
	ds_read_b128 v[180:183], v228 offset:6144
	v_mfma_f32_16x16x32_bf16 v[18:21], v[152:155], v[140:143], v[18:21]
	ds_read_b128 v[184:187], v234 offset:0
	v_mfma_f32_16x16x32_bf16 v[22:25], v[156:159], v[140:143], v[22:25]
	ds_read_b128 v[188:191], v234 offset:2048
	v_mfma_f32_16x16x32_bf16 v[26:29], v[160:163], v[140:143], v[26:29]
	ds_read_b128 v[192:195], v234 offset:4096
	v_mfma_f32_16x16x32_bf16 v[30:33], v[164:167], v[140:143], v[30:33]
	ds_read_b128 v[196:199], v234 offset:6144
	v_mfma_f32_16x16x32_bf16 v[34:37], v[152:155], v[144:147], v[34:37]
	v_mfma_f32_16x16x32_bf16 v[38:41], v[156:159], v[144:147], v[38:41]
	v_mfma_f32_16x16x32_bf16 v[42:45], v[160:163], v[144:147], v[42:45]
	v_mfma_f32_16x16x32_bf16 v[46:49], v[164:167], v[144:147], v[46:49]
	v_mfma_f32_16x16x32_bf16 v[50:53], v[152:155], v[148:151], v[50:53]
	v_mfma_f32_16x16x32_bf16 v[54:57], v[156:159], v[148:151], v[54:57]
	v_mfma_f32_16x16x32_bf16 v[58:61], v[160:163], v[148:151], v[58:61]
	v_mfma_f32_16x16x32_bf16 v[62:65], v[164:167], v[148:151], v[62:65]
	s_waitcnt vmcnt(6) lgkmcnt(0)
	s_barrier
	v_mfma_f32_16x16x32_bf16 v[2:5], v[184:187], v[168:171], v[2:5]
	ds_read_b128 v[136:139], v224 offset:0
	v_mfma_f32_16x16x32_bf16 v[6:9], v[188:191], v[168:171], v[6:9]
	ds_read_b128 v[140:143], v224 offset:2048
	v_mfma_f32_16x16x32_bf16 v[10:13], v[192:195], v[168:171], v[10:13]
	ds_read_b128 v[144:147], v224 offset:4096
	v_mfma_f32_16x16x32_bf16 v[14:17], v[196:199], v[168:171], v[14:17]
	ds_read_b128 v[148:151], v224 offset:6144
	v_mfma_f32_16x16x32_bf16 v[18:21], v[184:187], v[172:175], v[18:21]
	ds_read_b128 v[152:155], v232 offset:0
	v_mfma_f32_16x16x32_bf16 v[22:25], v[188:191], v[172:175], v[22:25]
	ds_read_b128 v[156:159], v232 offset:2048
	v_mfma_f32_16x16x32_bf16 v[26:29], v[192:195], v[172:175], v[26:29]
	ds_read_b128 v[160:163], v232 offset:4096
	v_mfma_f32_16x16x32_bf16 v[30:33], v[196:199], v[172:175], v[30:33]
	ds_read_b128 v[164:167], v232 offset:6144
	s_add_u32 m0, s8, 0xc000
	v_mfma_f32_16x16x32_bf16 v[34:37], v[184:187], v[176:179], v[34:37]
	global_load_lds_dwordx4 v200, s[4:5]
	s_add_u32 m0, s8, 0xc400
	v_mfma_f32_16x16x32_bf16 v[38:41], v[188:191], v[176:179], v[38:41]
	global_load_lds_dwordx4 v201, s[4:5]
	s_add_u32 m0, s8, 0xc800
	v_mfma_f32_16x16x32_bf16 v[42:45], v[192:195], v[176:179], v[42:45]
	global_load_lds_dwordx4 v202, s[4:5]
	s_add_u32 m0, s8, 0xcc00
	v_mfma_f32_16x16x32_bf16 v[46:49], v[196:199], v[176:179], v[46:49]
	global_load_lds_dwordx4 v203, s[4:5]
	s_add_u32 m0, s9, 0xc000
	v_mfma_f32_16x16x32_bf16 v[50:53], v[184:187], v[180:183], v[50:53]
	global_load_lds_dwordx4 v204, s[6:7]
	s_add_u32 m0, s9, 0xc400
	v_mfma_f32_16x16x32_bf16 v[54:57], v[188:191], v[180:183], v[54:57]
	global_load_lds_dwordx4 v205, s[6:7]
	v_mfma_f32_16x16x32_bf16 v[58:61], v[192:195], v[180:183], v[58:61]
	s_add_u32 s4, s4, 0x80
	s_addc_u32 s5, s5, 0
	v_mfma_f32_16x16x32_bf16 v[62:65], v[196:199], v[180:183], v[62:65]
	s_add_u32 s6, s6, 0x80
	s_addc_u32 s7, s7, 0
	s_waitcnt lgkmcnt(0)
	v_mfma_f32_16x16x32_bf16 v[2:5], v[152:155], v[136:139], v[2:5]
	ds_read_b128 v[168:171], v229 offset:0
	v_mfma_f32_16x16x32_bf16 v[6:9], v[156:159], v[136:139], v[6:9]
	ds_read_b128 v[172:175], v229 offset:2048
	v_mfma_f32_16x16x32_bf16 v[10:13], v[160:163], v[136:139], v[10:13]
	ds_read_b128 v[176:179], v229 offset:4096
	v_mfma_f32_16x16x32_bf16 v[14:17], v[164:167], v[136:139], v[14:17]
	ds_read_b128 v[180:183], v229 offset:6144
	v_mfma_f32_16x16x32_bf16 v[18:21], v[152:155], v[140:143], v[18:21]
	ds_read_b128 v[184:187], v235 offset:0
	v_mfma_f32_16x16x32_bf16 v[22:25], v[156:159], v[140:143], v[22:25]
	ds_read_b128 v[188:191], v235 offset:2048
	v_mfma_f32_16x16x32_bf16 v[26:29], v[160:163], v[140:143], v[26:29]
	ds_read_b128 v[192:195], v235 offset:4096
	v_mfma_f32_16x16x32_bf16 v[30:33], v[164:167], v[140:143], v[30:33]
	ds_read_b128 v[196:199], v235 offset:6144
	v_mfma_f32_16x16x32_bf16 v[34:37], v[152:155], v[144:147], v[34:37]
	v_mfma_f32_16x16x32_bf16 v[38:41], v[156:159], v[144:147], v[38:41]
	v_mfma_f32_16x16x32_bf16 v[42:45], v[160:163], v[144:147], v[42:45]
	v_mfma_f32_16x16x32_bf16 v[46:49], v[164:167], v[144:147], v[46:49]
	v_mfma_f32_16x16x32_bf16 v[50:53], v[152:155], v[148:151], v[50:53]
	v_mfma_f32_16x16x32_bf16 v[54:57], v[156:159], v[148:151], v[54:57]
	v_mfma_f32_16x16x32_bf16 v[58:61], v[160:163], v[148:151], v[58:61]
	v_mfma_f32_16x16x32_bf16 v[62:65], v[164:167], v[148:151], v[62:65]
	s_waitcnt vmcnt(6) lgkmcnt(0)
	s_barrier
	v_mfma_f32_16x16x32_bf16 v[2:5], v[184:187], v[168:171], v[2:5]
	ds_read_b128 v[136:139], v218 offset:0
	v_mfma_f32_16x16x32_bf16 v[6:9], v[188:191], v[168:171], v[6:9]
	ds_read_b128 v[140:143], v218 offset:2048
	v_mfma_f32_16x16x32_bf16 v[10:13], v[192:195], v[168:171], v[10:13]
	ds_read_b128 v[144:147], v218 offset:4096
	v_mfma_f32_16x16x32_bf16 v[14:17], v[196:199], v[168:171], v[14:17]
	ds_read_b128 v[148:151], v218 offset:6144
	v_mfma_f32_16x16x32_bf16 v[18:21], v[184:187], v[172:175], v[18:21]
	ds_read_b128 v[152:155], v230 offset:0
	v_mfma_f32_16x16x32_bf16 v[22:25], v[188:191], v[172:175], v[22:25]
	ds_read_b128 v[156:159], v230 offset:2048
	v_mfma_f32_16x16x32_bf16 v[26:29], v[192:195], v[172:175], v[26:29]
	ds_read_b128 v[160:163], v230 offset:4096
	v_mfma_f32_16x16x32_bf16 v[30:33], v[196:199], v[172:175], v[30:33]
	ds_read_b128 v[164:167], v230 offset:6144
	s_add_u32 m0, s8, 0x18000
	v_mfma_f32_16x16x32_bf16 v[34:37], v[184:187], v[176:179], v[34:37]
	global_load_lds_dwordx4 v200, s[4:5]
	s_add_u32 m0, s8, 0x18400
	v_mfma_f32_16x16x32_bf16 v[38:41], v[188:191], v[176:179], v[38:41]
	global_load_lds_dwordx4 v201, s[4:5]
	s_add_u32 m0, s8, 0x18800
	v_mfma_f32_16x16x32_bf16 v[42:45], v[192:195], v[176:179], v[42:45]
	global_load_lds_dwordx4 v202, s[4:5]
	s_add_u32 m0, s8, 0x18c00
	v_mfma_f32_16x16x32_bf16 v[46:49], v[196:199], v[176:179], v[46:49]
	global_load_lds_dwordx4 v203, s[4:5]
	s_add_u32 m0, s9, 0x18000
	v_mfma_f32_16x16x32_bf16 v[50:53], v[184:187], v[180:183], v[50:53]
	global_load_lds_dwordx4 v204, s[6:7]
	s_add_u32 m0, s9, 0x18400
	v_mfma_f32_16x16x32_bf16 v[54:57], v[188:191], v[180:183], v[54:57]
	global_load_lds_dwordx4 v205, s[6:7]
	v_mfma_f32_16x16x32_bf16 v[58:61], v[192:195], v[180:183], v[58:61]
	s_add_u32 s4, s4, 0x80
	s_addc_u32 s5, s5, 0
	v_mfma_f32_16x16x32_bf16 v[62:65], v[196:199], v[180:183], v[62:65]
	s_add_u32 s6, s6, 0x80
	s_addc_u32 s7, s7, 0
	s_waitcnt lgkmcnt(0)
	v_mfma_f32_16x16x32_bf16 v[2:5], v[152:155], v[136:139], v[2:5]
	ds_read_b128 v[168:171], v225 offset:0
	v_mfma_f32_16x16x32_bf16 v[6:9], v[156:159], v[136:139], v[6:9]
	ds_read_b128 v[172:175], v225 offset:2048
	v_mfma_f32_16x16x32_bf16 v[10:13], v[160:163], v[136:139], v[10:13]
	ds_read_b128 v[176:179], v225 offset:4096
	v_mfma_f32_16x16x32_bf16 v[14:17], v[164:167], v[136:139], v[14:17]
	ds_read_b128 v[180:183], v225 offset:6144
	v_mfma_f32_16x16x32_bf16 v[18:21], v[152:155], v[140:143], v[18:21]
	ds_read_b128 v[184:187], v233 offset:0
	v_mfma_f32_16x16x32_bf16 v[22:25], v[156:159], v[140:143], v[22:25]
	ds_read_b128 v[188:191], v233 offset:2048
	v_mfma_f32_16x16x32_bf16 v[26:29], v[160:163], v[140:143], v[26:29]
	ds_read_b128 v[192:195], v233 offset:4096
	v_mfma_f32_16x16x32_bf16 v[30:33], v[164:167], v[140:143], v[30:33]
	ds_read_b128 v[196:199], v233 offset:6144
	v_mfma_f32_16x16x32_bf16 v[34:37], v[152:155], v[144:147], v[34:37]
	v_mfma_f32_16x16x32_bf16 v[38:41], v[156:159], v[144:147], v[38:41]
	v_mfma_f32_16x16x32_bf16 v[42:45], v[160:163], v[144:147], v[42:45]
	v_mfma_f32_16x16x32_bf16 v[46:49], v[164:167], v[144:147], v[46:49]
	v_mfma_f32_16x16x32_bf16 v[50:53], v[152:155], v[148:151], v[50:53]
	v_mfma_f32_16x16x32_bf16 v[54:57], v[156:159], v[148:151], v[54:57]
	v_mfma_f32_16x16x32_bf16 v[58:61], v[160:163], v[148:151], v[58:61]
	v_mfma_f32_16x16x32_bf16 v[62:65], v[164:167], v[148:151], v[62:65]
	s_waitcnt vmcnt(6) lgkmcnt(0)
	s_barrier
	v_mfma_f32_16x16x32_bf16 v[2:5], v[184:187], v[168:171], v[2:5]
	ds_read_b128 v[136:139], v219 offset:0
	v_mfma_f32_16x16x32_bf16 v[6:9], v[188:191], v[168:171], v[6:9]
	ds_read_b128 v[140:143], v219 offset:2048
	v_mfma_f32_16x16x32_bf16 v[10:13], v[192:195], v[168:171], v[10:13]
	ds_read_b128 v[144:147], v219 offset:4096
	v_mfma_f32_16x16x32_bf16 v[14:17], v[196:199], v[168:171], v[14:17]
	ds_read_b128 v[148:151], v219 offset:6144
	v_mfma_f32_16x16x32_bf16 v[18:21], v[184:187], v[172:175], v[18:21]
	ds_read_b128 v[152:155], v231 offset:0
	v_mfma_f32_16x16x32_bf16 v[22:25], v[188:191], v[172:175], v[22:25]
	ds_read_b128 v[156:159], v231 offset:2048
	v_mfma_f32_16x16x32_bf16 v[26:29], v[192:195], v[172:175], v[26:29]
	ds_read_b128 v[160:163], v231 offset:4096
	v_mfma_f32_16x16x32_bf16 v[30:33], v[196:199], v[172:175], v[30:33]
	ds_read_b128 v[164:167], v231 offset:6144
	s_mov_b32 m0, s8
	v_mfma_f32_16x16x32_bf16 v[34:37], v[184:187], v[176:179], v[34:37]
	global_load_lds_dwordx4 v200, s[4:5]
	s_add_u32 m0, s8, 0x400
	v_mfma_f32_16x16x32_bf16 v[38:41], v[188:191], v[176:179], v[38:41]
	global_load_lds_dwordx4 v201, s[4:5]
	s_add_u32 m0, s8, 0x800
	v_mfma_f32_16x16x32_bf16 v[42:45], v[192:195], v[176:179], v[42:45]
	global_load_lds_dwordx4 v202, s[4:5]
	s_add_u32 m0, s8, 0xc00
	v_mfma_f32_16x16x32_bf16 v[46:49], v[196:199], v[176:179], v[46:49]
	global_load_lds_dwordx4 v203, s[4:5]
	s_mov_b32 m0, s9
	v_mfma_f32_16x16x32_bf16 v[50:53], v[184:187], v[180:183], v[50:53]
	global_load_lds_dwordx4 v204, s[6:7]
	s_add_u32 m0, s9, 0x400
	v_mfma_f32_16x16x32_bf16 v[54:57], v[188:191], v[180:183], v[54:57]
	global_load_lds_dwordx4 v205, s[6:7]
	v_mfma_f32_16x16x32_bf16 v[58:61], v[192:195], v[180:183], v[58:61]
	s_add_u32 s4, s4, 0x80
	s_addc_u32 s5, s5, 0
	v_mfma_f32_16x16x32_bf16 v[62:65], v[196:199], v[180:183], v[62:65]
	s_add_u32 s6, s6, 0x80
	s_addc_u32 s7, s7, 0
	s_waitcnt lgkmcnt(0)
	v_mfma_f32_16x16x32_bf16 v[2:5], v[152:155], v[136:139], v[2:5]
	ds_read_b128 v[168:171], v228 offset:0
	v_mfma_f32_16x16x32_bf16 v[6:9], v[156:159], v[136:139], v[6:9]
	ds_read_b128 v[172:175], v228 offset:2048
	v_mfma_f32_16x16x32_bf16 v[10:13], v[160:163], v[136:139], v[10:13]
	ds_read_b128 v[176:179], v228 offset:4096
	v_mfma_f32_16x16x32_bf16 v[14:17], v[164:167], v[136:139], v[14:17]
	ds_read_b128 v[180:183], v228 offset:6144
	v_mfma_f32_16x16x32_bf16 v[18:21], v[152:155], v[140:143], v[18:21]
	ds_read_b128 v[184:187], v234 offset:0
	v_mfma_f32_16x16x32_bf16 v[22:25], v[156:159], v[140:143], v[22:25]
	ds_read_b128 v[188:191], v234 offset:2048
	v_mfma_f32_16x16x32_bf16 v[26:29], v[160:163], v[140:143], v[26:29]
	ds_read_b128 v[192:195], v234 offset:4096
	v_mfma_f32_16x16x32_bf16 v[30:33], v[164:167], v[140:143], v[30:33]
	ds_read_b128 v[196:199], v234 offset:6144
	v_mfma_f32_16x16x32_bf16 v[34:37], v[152:155], v[144:147], v[34:37]
	v_mfma_f32_16x16x32_bf16 v[38:41], v[156:159], v[144:147], v[38:41]
	v_mfma_f32_16x16x32_bf16 v[42:45], v[160:163], v[144:147], v[42:45]
	v_mfma_f32_16x16x32_bf16 v[46:49], v[164:167], v[144:147], v[46:49]
	v_mfma_f32_16x16x32_bf16 v[50:53], v[152:155], v[148:151], v[50:53]
	v_mfma_f32_16x16x32_bf16 v[54:57], v[156:159], v[148:151], v[54:57]
	v_mfma_f32_16x16x32_bf16 v[58:61], v[160:163], v[148:151], v[58:61]
	v_mfma_f32_16x16x32_bf16 v[62:65], v[164:167], v[148:151], v[62:65]
	s_waitcnt vmcnt(6) lgkmcnt(0)
	s_barrier
	v_mfma_f32_16x16x32_bf16 v[2:5], v[184:187], v[168:171], v[2:5]
	ds_read_b128 v[136:139], v224 offset:0
	v_mfma_f32_16x16x32_bf16 v[6:9], v[188:191], v[168:171], v[6:9]
	ds_read_b128 v[140:143], v224 offset:2048
	v_mfma_f32_16x16x32_bf16 v[10:13], v[192:195], v[168:171], v[10:13]
	ds_read_b128 v[144:147], v224 offset:4096
	v_mfma_f32_16x16x32_bf16 v[14:17], v[196:199], v[168:171], v[14:17]
	ds_read_b128 v[148:151], v224 offset:6144
	v_mfma_f32_16x16x32_bf16 v[18:21], v[184:187], v[172:175], v[18:21]
	ds_read_b128 v[152:155], v232 offset:0
	v_mfma_f32_16x16x32_bf16 v[22:25], v[188:191], v[172:175], v[22:25]
	ds_read_b128 v[156:159], v232 offset:2048
	v_mfma_f32_16x16x32_bf16 v[26:29], v[192:195], v[172:175], v[26:29]
	ds_read_b128 v[160:163], v232 offset:4096
	v_mfma_f32_16x16x32_bf16 v[30:33], v[196:199], v[172:175], v[30:33]
	ds_read_b128 v[164:167], v232 offset:6144
	s_add_u32 m0, s8, 0xc000
	v_mfma_f32_16x16x32_bf16 v[34:37], v[184:187], v[176:179], v[34:37]
	global_load_lds_dwordx4 v200, s[4:5]
	s_add_u32 m0, s8, 0xc400
	v_mfma_f32_16x16x32_bf16 v[38:41], v[188:191], v[176:179], v[38:41]
	global_load_lds_dwordx4 v201, s[4:5]
	s_add_u32 m0, s8, 0xc800
	v_mfma_f32_16x16x32_bf16 v[42:45], v[192:195], v[176:179], v[42:45]
	global_load_lds_dwordx4 v202, s[4:5]
	s_add_u32 m0, s8, 0xcc00
	v_mfma_f32_16x16x32_bf16 v[46:49], v[196:199], v[176:179], v[46:49]
	global_load_lds_dwordx4 v203, s[4:5]
	s_add_u32 m0, s9, 0xc000
	v_mfma_f32_16x16x32_bf16 v[50:53], v[184:187], v[180:183], v[50:53]
	global_load_lds_dwordx4 v204, s[6:7]
	s_add_u32 m0, s9, 0xc400
	v_mfma_f32_16x16x32_bf16 v[54:57], v[188:191], v[180:183], v[54:57]
	global_load_lds_dwordx4 v205, s[6:7]
	v_mfma_f32_16x16x32_bf16 v[58:61], v[192:195], v[180:183], v[58:61]
	s_add_u32 s4, s4, 0x80
	s_addc_u32 s5, s5, 0
	v_mfma_f32_16x16x32_bf16 v[62:65], v[196:199], v[180:183], v[62:65]
	s_add_u32 s6, s6, 0x80
	s_addc_u32 s7, s7, 0
	s_waitcnt lgkmcnt(0)
	v_mfma_f32_16x16x32_bf16 v[2:5], v[152:155], v[136:139], v[2:5]
	ds_read_b128 v[168:171], v229 offset:0
	v_mfma_f32_16x16x32_bf16 v[6:9], v[156:159], v[136:139], v[6:9]
	ds_read_b128 v[172:175], v229 offset:2048
	v_mfma_f32_16x16x32_bf16 v[10:13], v[160:163], v[136:139], v[10:13]
	ds_read_b128 v[176:179], v229 offset:4096
	v_mfma_f32_16x16x32_bf16 v[14:17], v[164:167], v[136:139], v[14:17]
	ds_read_b128 v[180:183], v229 offset:6144
	v_mfma_f32_16x16x32_bf16 v[18:21], v[152:155], v[140:143], v[18:21]
	ds_read_b128 v[184:187], v235 offset:0
	v_mfma_f32_16x16x32_bf16 v[22:25], v[156:159], v[140:143], v[22:25]
	ds_read_b128 v[188:191], v235 offset:2048
	v_mfma_f32_16x16x32_bf16 v[26:29], v[160:163], v[140:143], v[26:29]
	ds_read_b128 v[192:195], v235 offset:4096
	v_mfma_f32_16x16x32_bf16 v[30:33], v[164:167], v[140:143], v[30:33]
	ds_read_b128 v[196:199], v235 offset:6144
	v_mfma_f32_16x16x32_bf16 v[34:37], v[152:155], v[144:147], v[34:37]
	v_mfma_f32_16x16x32_bf16 v[38:41], v[156:159], v[144:147], v[38:41]
	v_mfma_f32_16x16x32_bf16 v[42:45], v[160:163], v[144:147], v[42:45]
	v_mfma_f32_16x16x32_bf16 v[46:49], v[164:167], v[144:147], v[46:49]
	v_mfma_f32_16x16x32_bf16 v[50:53], v[152:155], v[148:151], v[50:53]
	v_mfma_f32_16x16x32_bf16 v[54:57], v[156:159], v[148:151], v[54:57]
	v_mfma_f32_16x16x32_bf16 v[58:61], v[160:163], v[148:151], v[58:61]
	v_mfma_f32_16x16x32_bf16 v[62:65], v[164:167], v[148:151], v[62:65]
	s_waitcnt vmcnt(6) lgkmcnt(0)
	s_barrier
	v_mfma_f32_16x16x32_bf16 v[2:5], v[184:187], v[168:171], v[2:5]
	ds_read_b128 v[136:139], v218 offset:0
	v_mfma_f32_16x16x32_bf16 v[6:9], v[188:191], v[168:171], v[6:9]
	ds_read_b128 v[140:143], v218 offset:2048
	v_mfma_f32_16x16x32_bf16 v[10:13], v[192:195], v[168:171], v[10:13]
	ds_read_b128 v[144:147], v218 offset:4096
	v_mfma_f32_16x16x32_bf16 v[14:17], v[196:199], v[168:171], v[14:17]
	ds_read_b128 v[148:151], v218 offset:6144
	v_mfma_f32_16x16x32_bf16 v[18:21], v[184:187], v[172:175], v[18:21]
	ds_read_b128 v[152:155], v230 offset:0
	v_mfma_f32_16x16x32_bf16 v[22:25], v[188:191], v[172:175], v[22:25]
	ds_read_b128 v[156:159], v230 offset:2048
	v_mfma_f32_16x16x32_bf16 v[26:29], v[192:195], v[172:175], v[26:29]
	ds_read_b128 v[160:163], v230 offset:4096
	v_mfma_f32_16x16x32_bf16 v[30:33], v[196:199], v[172:175], v[30:33]
	ds_read_b128 v[164:167], v230 offset:6144
	s_add_u32 m0, s8, 0x18000
	v_mfma_f32_16x16x32_bf16 v[34:37], v[184:187], v[176:179], v[34:37]
	global_load_lds_dwordx4 v200, s[4:5]
	s_add_u32 m0, s8, 0x18400
	v_mfma_f32_16x16x32_bf16 v[38:41], v[188:191], v[176:179], v[38:41]
	global_load_lds_dwordx4 v201, s[4:5]
	s_add_u32 m0, s8, 0x18800
	v_mfma_f32_16x16x32_bf16 v[42:45], v[192:195], v[176:179], v[42:45]
	global_load_lds_dwordx4 v202, s[4:5]
	s_add_u32 m0, s8, 0x18c00
	v_mfma_f32_16x16x32_bf16 v[46:49], v[196:199], v[176:179], v[46:49]
	global_load_lds_dwordx4 v203, s[4:5]
	s_add_u32 m0, s9, 0x18000
	v_mfma_f32_16x16x32_bf16 v[50:53], v[184:187], v[180:183], v[50:53]
	global_load_lds_dwordx4 v204, s[6:7]
	s_add_u32 m0, s9, 0x18400
	v_mfma_f32_16x16x32_bf16 v[54:57], v[188:191], v[180:183], v[54:57]
	global_load_lds_dwordx4 v205, s[6:7]
	v_mfma_f32_16x16x32_bf16 v[58:61], v[192:195], v[180:183], v[58:61]
	s_add_u32 s4, s4, 0x80
	s_addc_u32 s5, s5, 0
	v_mfma_f32_16x16x32_bf16 v[62:65], v[196:199], v[180:183], v[62:65]
	s_add_u32 s6, s6, 0x80
	s_addc_u32 s7, s7, 0
	s_waitcnt lgkmcnt(0)
	v_mfma_f32_16x16x32_bf16 v[2:5], v[152:155], v[136:139], v[2:5]
	ds_read_b128 v[168:171], v225 offset:0
	v_mfma_f32_16x16x32_bf16 v[6:9], v[156:159], v[136:139], v[6:9]
	ds_read_b128 v[172:175], v225 offset:2048
	v_mfma_f32_16x16x32_bf16 v[10:13], v[160:163], v[136:139], v[10:13]
	ds_read_b128 v[176:179], v225 offset:4096
	v_mfma_f32_16x16x32_bf16 v[14:17], v[164:167], v[136:139], v[14:17]
	ds_read_b128 v[180:183], v225 offset:6144
	v_mfma_f32_16x16x32_bf16 v[18:21], v[152:155], v[140:143], v[18:21]
	ds_read_b128 v[184:187], v233 offset:0
	v_mfma_f32_16x16x32_bf16 v[22:25], v[156:159], v[140:143], v[22:25]
	ds_read_b128 v[188:191], v233 offset:2048
	v_mfma_f32_16x16x32_bf16 v[26:29], v[160:163], v[140:143], v[26:29]
	ds_read_b128 v[192:195], v233 offset:4096
	v_mfma_f32_16x16x32_bf16 v[30:33], v[164:167], v[140:143], v[30:33]
	ds_read_b128 v[196:199], v233 offset:6144
	v_mfma_f32_16x16x32_bf16 v[34:37], v[152:155], v[144:147], v[34:37]
	v_mfma_f32_16x16x32_bf16 v[38:41], v[156:159], v[144:147], v[38:41]
	v_mfma_f32_16x16x32_bf16 v[42:45], v[160:163], v[144:147], v[42:45]
	v_mfma_f32_16x16x32_bf16 v[46:49], v[164:167], v[144:147], v[46:49]
	v_mfma_f32_16x16x32_bf16 v[50:53], v[152:155], v[148:151], v[50:53]
	v_mfma_f32_16x16x32_bf16 v[54:57], v[156:159], v[148:151], v[54:57]
	v_mfma_f32_16x16x32_bf16 v[58:61], v[160:163], v[148:151], v[58:61]
	v_mfma_f32_16x16x32_bf16 v[62:65], v[164:167], v[148:151], v[62:65]
	s_waitcnt vmcnt(6) lgkmcnt(0)
	s_barrier
	v_mfma_f32_16x16x32_bf16 v[2:5], v[184:187], v[168:171], v[2:5]
	ds_read_b128 v[136:139], v219 offset:0
	v_mfma_f32_16x16x32_bf16 v[6:9], v[188:191], v[168:171], v[6:9]
	ds_read_b128 v[140:143], v219 offset:2048
	v_mfma_f32_16x16x32_bf16 v[10:13], v[192:195], v[168:171], v[10:13]
	ds_read_b128 v[144:147], v219 offset:4096
	v_mfma_f32_16x16x32_bf16 v[14:17], v[196:199], v[168:171], v[14:17]
	ds_read_b128 v[148:151], v219 offset:6144
	v_mfma_f32_16x16x32_bf16 v[18:21], v[184:187], v[172:175], v[18:21]
	ds_read_b128 v[152:155], v231 offset:0
	v_mfma_f32_16x16x32_bf16 v[22:25], v[188:191], v[172:175], v[22:25]
	ds_read_b128 v[156:159], v231 offset:2048
	v_mfma_f32_16x16x32_bf16 v[26:29], v[192:195], v[172:175], v[26:29]
	ds_read_b128 v[160:163], v231 offset:4096
	v_mfma_f32_16x16x32_bf16 v[30:33], v[196:199], v[172:175], v[30:33]
	ds_read_b128 v[164:167], v231 offset:6144
	s_mov_b32 m0, s8
	v_mfma_f32_16x16x32_bf16 v[34:37], v[184:187], v[176:179], v[34:37]
	global_load_lds_dwordx4 v200, s[4:5]
	s_add_u32 m0, s8, 0x400
	v_mfma_f32_16x16x32_bf16 v[38:41], v[188:191], v[176:179], v[38:41]
	global_load_lds_dwordx4 v201, s[4:5]
	s_add_u32 m0, s8, 0x800
	v_mfma_f32_16x16x32_bf16 v[42:45], v[192:195], v[176:179], v[42:45]
	global_load_lds_dwordx4 v202, s[4:5]
	s_add_u32 m0, s8, 0xc00
	v_mfma_f32_16x16x32_bf16 v[46:49], v[196:199], v[176:179], v[46:49]
	global_load_lds_dwordx4 v203, s[4:5]
	s_mov_b32 m0, s9
	v_mfma_f32_16x16x32_bf16 v[50:53], v[184:187], v[180:183], v[50:53]
	global_load_lds_dwordx4 v204, s[6:7]
	s_add_u32 m0, s9, 0x400
	v_mfma_f32_16x16x32_bf16 v[54:57], v[188:191], v[180:183], v[54:57]
	global_load_lds_dwordx4 v205, s[6:7]
	v_mfma_f32_16x16x32_bf16 v[58:61], v[192:195], v[180:183], v[58:61]
	s_add_u32 s4, s4, 0x80
	s_addc_u32 s5, s5, 0
	v_mfma_f32_16x16x32_bf16 v[62:65], v[196:199], v[180:183], v[62:65]
	s_add_u32 s6, s6, 0x80
	s_addc_u32 s7, s7, 0
	s_waitcnt lgkmcnt(0)
	v_mfma_f32_16x16x32_bf16 v[2:5], v[152:155], v[136:139], v[2:5]
	ds_read_b128 v[168:171], v228 offset:0
	v_mfma_f32_16x16x32_bf16 v[6:9], v[156:159], v[136:139], v[6:9]
	ds_read_b128 v[172:175], v228 offset:2048
	v_mfma_f32_16x16x32_bf16 v[10:13], v[160:163], v[136:139], v[10:13]
	ds_read_b128 v[176:179], v228 offset:4096
	v_mfma_f32_16x16x32_bf16 v[14:17], v[164:167], v[136:139], v[14:17]
	ds_read_b128 v[180:183], v228 offset:6144
	v_mfma_f32_16x16x32_bf16 v[18:21], v[152:155], v[140:143], v[18:21]
	ds_read_b128 v[184:187], v234 offset:0
	v_mfma_f32_16x16x32_bf16 v[22:25], v[156:159], v[140:143], v[22:25]
	ds_read_b128 v[188:191], v234 offset:2048
	v_mfma_f32_16x16x32_bf16 v[26:29], v[160:163], v[140:143], v[26:29]
	ds_read_b128 v[192:195], v234 offset:4096
	v_mfma_f32_16x16x32_bf16 v[30:33], v[164:167], v[140:143], v[30:33]
	ds_read_b128 v[196:199], v234 offset:6144
	v_mfma_f32_16x16x32_bf16 v[34:37], v[152:155], v[144:147], v[34:37]
	v_mfma_f32_16x16x32_bf16 v[38:41], v[156:159], v[144:147], v[38:41]
	v_mfma_f32_16x16x32_bf16 v[42:45], v[160:163], v[144:147], v[42:45]
	v_mfma_f32_16x16x32_bf16 v[46:49], v[164:167], v[144:147], v[46:49]
	v_mfma_f32_16x16x32_bf16 v[50:53], v[152:155], v[148:151], v[50:53]
	v_mfma_f32_16x16x32_bf16 v[54:57], v[156:159], v[148:151], v[54:57]
	v_mfma_f32_16x16x32_bf16 v[58:61], v[160:163], v[148:151], v[58:61]
	v_mfma_f32_16x16x32_bf16 v[62:65], v[164:167], v[148:151], v[62:65]
	s_waitcnt vmcnt(6) lgkmcnt(0)
	s_barrier
	v_mfma_f32_16x16x32_bf16 v[2:5], v[184:187], v[168:171], v[2:5]
	ds_read_b128 v[136:139], v224 offset:0
	v_mfma_f32_16x16x32_bf16 v[6:9], v[188:191], v[168:171], v[6:9]
	ds_read_b128 v[140:143], v224 offset:2048
	v_mfma_f32_16x16x32_bf16 v[10:13], v[192:195], v[168:171], v[10:13]
	ds_read_b128 v[144:147], v224 offset:4096
	v_mfma_f32_16x16x32_bf16 v[14:17], v[196:199], v[168:171], v[14:17]
	ds_read_b128 v[148:151], v224 offset:6144
	v_mfma_f32_16x16x32_bf16 v[18:21], v[184:187], v[172:175], v[18:21]
	ds_read_b128 v[152:155], v232 offset:0
	v_mfma_f32_16x16x32_bf16 v[22:25], v[188:191], v[172:175], v[22:25]
	ds_read_b128 v[156:159], v232 offset:2048
	v_mfma_f32_16x16x32_bf16 v[26:29], v[192:195], v[172:175], v[26:29]
	ds_read_b128 v[160:163], v232 offset:4096
	v_mfma_f32_16x16x32_bf16 v[30:33], v[196:199], v[172:175], v[30:33]
	ds_read_b128 v[164:167], v232 offset:6144
	s_add_u32 m0, s8, 0xc000
	v_mfma_f32_16x16x32_bf16 v[34:37], v[184:187], v[176:179], v[34:37]
	global_load_lds_dwordx4 v200, s[4:5]
	s_add_u32 m0, s8, 0xc400
	v_mfma_f32_16x16x32_bf16 v[38:41], v[188:191], v[176:179], v[38:41]
	global_load_lds_dwordx4 v201, s[4:5]
	s_add_u32 m0, s8, 0xc800
	v_mfma_f32_16x16x32_bf16 v[42:45], v[192:195], v[176:179], v[42:45]
	global_load_lds_dwordx4 v202, s[4:5]
	s_add_u32 m0, s8, 0xcc00
	v_mfma_f32_16x16x32_bf16 v[46:49], v[196:199], v[176:179], v[46:49]
	global_load_lds_dwordx4 v203, s[4:5]
	s_add_u32 m0, s9, 0xc000
	v_mfma_f32_16x16x32_bf16 v[50:53], v[184:187], v[180:183], v[50:53]
	global_load_lds_dwordx4 v204, s[6:7]
	s_add_u32 m0, s9, 0xc400
	v_mfma_f32_16x16x32_bf16 v[54:57], v[188:191], v[180:183], v[54:57]
	global_load_lds_dwordx4 v205, s[6:7]
	v_mfma_f32_16x16x32_bf16 v[58:61], v[192:195], v[180:183], v[58:61]
	s_add_u32 s4, s4, 0x80
	s_addc_u32 s5, s5, 0
	v_mfma_f32_16x16x32_bf16 v[62:65], v[196:199], v[180:183], v[62:65]
	s_add_u32 s6, s6, 0x80
	s_addc_u32 s7, s7, 0
	s_waitcnt lgkmcnt(0)
	v_mfma_f32_16x16x32_bf16 v[2:5], v[152:155], v[136:139], v[2:5]
	ds_read_b128 v[168:171], v229 offset:0
	v_mfma_f32_16x16x32_bf16 v[6:9], v[156:159], v[136:139], v[6:9]
	ds_read_b128 v[172:175], v229 offset:2048
	v_mfma_f32_16x16x32_bf16 v[10:13], v[160:163], v[136:139], v[10:13]
	ds_read_b128 v[176:179], v229 offset:4096
	v_mfma_f32_16x16x32_bf16 v[14:17], v[164:167], v[136:139], v[14:17]
	ds_read_b128 v[180:183], v229 offset:6144
	v_mfma_f32_16x16x32_bf16 v[18:21], v[152:155], v[140:143], v[18:21]
	ds_read_b128 v[184:187], v235 offset:0
	v_mfma_f32_16x16x32_bf16 v[22:25], v[156:159], v[140:143], v[22:25]
	ds_read_b128 v[188:191], v235 offset:2048
	v_mfma_f32_16x16x32_bf16 v[26:29], v[160:163], v[140:143], v[26:29]
	ds_read_b128 v[192:195], v235 offset:4096
	v_mfma_f32_16x16x32_bf16 v[30:33], v[164:167], v[140:143], v[30:33]
	ds_read_b128 v[196:199], v235 offset:6144
	v_mfma_f32_16x16x32_bf16 v[34:37], v[152:155], v[144:147], v[34:37]
	v_mfma_f32_16x16x32_bf16 v[38:41], v[156:159], v[144:147], v[38:41]
	v_mfma_f32_16x16x32_bf16 v[42:45], v[160:163], v[144:147], v[42:45]
	v_mfma_f32_16x16x32_bf16 v[46:49], v[164:167], v[144:147], v[46:49]
	v_mfma_f32_16x16x32_bf16 v[50:53], v[152:155], v[148:151], v[50:53]
	v_mfma_f32_16x16x32_bf16 v[54:57], v[156:159], v[148:151], v[54:57]
	v_mfma_f32_16x16x32_bf16 v[58:61], v[160:163], v[148:151], v[58:61]
	v_mfma_f32_16x16x32_bf16 v[62:65], v[164:167], v[148:151], v[62:65]
	s_waitcnt vmcnt(6) lgkmcnt(0)
	s_barrier
	v_mfma_f32_16x16x32_bf16 v[2:5], v[184:187], v[168:171], v[2:5]
	ds_read_b128 v[136:139], v218 offset:0
	v_mfma_f32_16x16x32_bf16 v[6:9], v[188:191], v[168:171], v[6:9]
	ds_read_b128 v[140:143], v218 offset:2048
	v_mfma_f32_16x16x32_bf16 v[10:13], v[192:195], v[168:171], v[10:13]
	ds_read_b128 v[144:147], v218 offset:4096
	v_mfma_f32_16x16x32_bf16 v[14:17], v[196:199], v[168:171], v[14:17]
	ds_read_b128 v[148:151], v218 offset:6144
	v_mfma_f32_16x16x32_bf16 v[18:21], v[184:187], v[172:175], v[18:21]
	ds_read_b128 v[152:155], v230 offset:0
	v_mfma_f32_16x16x32_bf16 v[22:25], v[188:191], v[172:175], v[22:25]
	ds_read_b128 v[156:159], v230 offset:2048
	v_mfma_f32_16x16x32_bf16 v[26:29], v[192:195], v[172:175], v[26:29]
	ds_read_b128 v[160:163], v230 offset:4096
	v_mfma_f32_16x16x32_bf16 v[30:33], v[196:199], v[172:175], v[30:33]
	ds_read_b128 v[164:167], v230 offset:6144
	s_add_u32 m0, s8, 0x18000
	v_mfma_f32_16x16x32_bf16 v[34:37], v[184:187], v[176:179], v[34:37]
	global_load_lds_dwordx4 v200, s[4:5]
	s_add_u32 m0, s8, 0x18400
	v_mfma_f32_16x16x32_bf16 v[38:41], v[188:191], v[176:179], v[38:41]
	global_load_lds_dwordx4 v201, s[4:5]
	s_add_u32 m0, s8, 0x18800
	v_mfma_f32_16x16x32_bf16 v[42:45], v[192:195], v[176:179], v[42:45]
	global_load_lds_dwordx4 v202, s[4:5]
	s_add_u32 m0, s8, 0x18c00
	v_mfma_f32_16x16x32_bf16 v[46:49], v[196:199], v[176:179], v[46:49]
	global_load_lds_dwordx4 v203, s[4:5]
	s_add_u32 m0, s9, 0x18000
	v_mfma_f32_16x16x32_bf16 v[50:53], v[184:187], v[180:183], v[50:53]
	global_load_lds_dwordx4 v204, s[6:7]
	s_add_u32 m0, s9, 0x18400
	v_mfma_f32_16x16x32_bf16 v[54:57], v[188:191], v[180:183], v[54:57]
	global_load_lds_dwordx4 v205, s[6:7]
	v_mfma_f32_16x16x32_bf16 v[58:61], v[192:195], v[180:183], v[58:61]
	s_add_u32 s4, s4, 0x80
	s_addc_u32 s5, s5, 0
	v_mfma_f32_16x16x32_bf16 v[62:65], v[196:199], v[180:183], v[62:65]
	s_add_u32 s6, s6, 0x80
	s_addc_u32 s7, s7, 0
	s_waitcnt lgkmcnt(0)
	v_mfma_f32_16x16x32_bf16 v[2:5], v[152:155], v[136:139], v[2:5]
	ds_read_b128 v[168:171], v225 offset:0
	v_mfma_f32_16x16x32_bf16 v[6:9], v[156:159], v[136:139], v[6:9]
	ds_read_b128 v[172:175], v225 offset:2048
	v_mfma_f32_16x16x32_bf16 v[10:13], v[160:163], v[136:139], v[10:13]
	ds_read_b128 v[176:179], v225 offset:4096
	v_mfma_f32_16x16x32_bf16 v[14:17], v[164:167], v[136:139], v[14:17]
	ds_read_b128 v[180:183], v225 offset:6144
	v_mfma_f32_16x16x32_bf16 v[18:21], v[152:155], v[140:143], v[18:21]
	ds_read_b128 v[184:187], v233 offset:0
	v_mfma_f32_16x16x32_bf16 v[22:25], v[156:159], v[140:143], v[22:25]
	ds_read_b128 v[188:191], v233 offset:2048
	v_mfma_f32_16x16x32_bf16 v[26:29], v[160:163], v[140:143], v[26:29]
	ds_read_b128 v[192:195], v233 offset:4096
	v_mfma_f32_16x16x32_bf16 v[30:33], v[164:167], v[140:143], v[30:33]
	ds_read_b128 v[196:199], v233 offset:6144
	v_mfma_f32_16x16x32_bf16 v[34:37], v[152:155], v[144:147], v[34:37]
	v_mfma_f32_16x16x32_bf16 v[38:41], v[156:159], v[144:147], v[38:41]
	v_mfma_f32_16x16x32_bf16 v[42:45], v[160:163], v[144:147], v[42:45]
	v_mfma_f32_16x16x32_bf16 v[46:49], v[164:167], v[144:147], v[46:49]
	v_mfma_f32_16x16x32_bf16 v[50:53], v[152:155], v[148:151], v[50:53]
	v_mfma_f32_16x16x32_bf16 v[54:57], v[156:159], v[148:151], v[54:57]
	v_mfma_f32_16x16x32_bf16 v[58:61], v[160:163], v[148:151], v[58:61]
	v_mfma_f32_16x16x32_bf16 v[62:65], v[164:167], v[148:151], v[62:65]
	s_waitcnt vmcnt(6) lgkmcnt(0)
	s_barrier
	v_mfma_f32_16x16x32_bf16 v[2:5], v[184:187], v[168:171], v[2:5]
	ds_read_b128 v[136:139], v219 offset:0
	v_mfma_f32_16x16x32_bf16 v[6:9], v[188:191], v[168:171], v[6:9]
	ds_read_b128 v[140:143], v219 offset:2048
	v_mfma_f32_16x16x32_bf16 v[10:13], v[192:195], v[168:171], v[10:13]
	ds_read_b128 v[144:147], v219 offset:4096
	v_mfma_f32_16x16x32_bf16 v[14:17], v[196:199], v[168:171], v[14:17]
	ds_read_b128 v[148:151], v219 offset:6144
	v_mfma_f32_16x16x32_bf16 v[18:21], v[184:187], v[172:175], v[18:21]
	ds_read_b128 v[152:155], v231 offset:0
	v_mfma_f32_16x16x32_bf16 v[22:25], v[188:191], v[172:175], v[22:25]
	ds_read_b128 v[156:159], v231 offset:2048
	v_mfma_f32_16x16x32_bf16 v[26:29], v[192:195], v[172:175], v[26:29]
	ds_read_b128 v[160:163], v231 offset:4096
	v_mfma_f32_16x16x32_bf16 v[30:33], v[196:199], v[172:175], v[30:33]
	ds_read_b128 v[164:167], v231 offset:6144
	s_mov_b32 m0, s8
	v_mfma_f32_16x16x32_bf16 v[34:37], v[184:187], v[176:179], v[34:37]
	global_load_lds_dwordx4 v200, s[4:5]
	s_add_u32 m0, s8, 0x400
	v_mfma_f32_16x16x32_bf16 v[38:41], v[188:191], v[176:179], v[38:41]
	global_load_lds_dwordx4 v201, s[4:5]
	s_add_u32 m0, s8, 0x800
	v_mfma_f32_16x16x32_bf16 v[42:45], v[192:195], v[176:179], v[42:45]
	global_load_lds_dwordx4 v202, s[4:5]
	s_add_u32 m0, s8, 0xc00
	v_mfma_f32_16x16x32_bf16 v[46:49], v[196:199], v[176:179], v[46:49]
	global_load_lds_dwordx4 v203, s[4:5]
	s_mov_b32 m0, s9
	v_mfma_f32_16x16x32_bf16 v[50:53], v[184:187], v[180:183], v[50:53]
	global_load_lds_dwordx4 v204, s[6:7]
	s_add_u32 m0, s9, 0x400
	v_mfma_f32_16x16x32_bf16 v[54:57], v[188:191], v[180:183], v[54:57]
	global_load_lds_dwordx4 v205, s[6:7]
	v_mfma_f32_16x16x32_bf16 v[58:61], v[192:195], v[180:183], v[58:61]
	s_sub_u32 s4, s4, 0x780
	s_subb_u32 s5, s5, 0
	v_mfma_f32_16x16x32_bf16 v[62:65], v[196:199], v[180:183], v[62:65]
	s_add_u32 s6, s6, 0x3f880
	s_addc_u32 s7, s7, 0
	s_waitcnt lgkmcnt(0)
	v_mfma_f32_16x16x32_bf16 v[2:5], v[152:155], v[136:139], v[2:5]
	ds_read_b128 v[168:171], v228 offset:0
	v_mfma_f32_16x16x32_bf16 v[6:9], v[156:159], v[136:139], v[6:9]
	ds_read_b128 v[172:175], v228 offset:2048
	v_mfma_f32_16x16x32_bf16 v[10:13], v[160:163], v[136:139], v[10:13]
	ds_read_b128 v[176:179], v228 offset:4096
	v_mfma_f32_16x16x32_bf16 v[14:17], v[164:167], v[136:139], v[14:17]
	ds_read_b128 v[180:183], v228 offset:6144
	v_mfma_f32_16x16x32_bf16 v[18:21], v[152:155], v[140:143], v[18:21]
	ds_read_b128 v[184:187], v234 offset:0
	v_mfma_f32_16x16x32_bf16 v[22:25], v[156:159], v[140:143], v[22:25]
	ds_read_b128 v[188:191], v234 offset:2048
	v_mfma_f32_16x16x32_bf16 v[26:29], v[160:163], v[140:143], v[26:29]
	ds_read_b128 v[192:195], v234 offset:4096
	v_mfma_f32_16x16x32_bf16 v[30:33], v[164:167], v[140:143], v[30:33]
	ds_read_b128 v[196:199], v234 offset:6144
	v_mfma_f32_16x16x32_bf16 v[34:37], v[152:155], v[144:147], v[34:37]
	v_mfma_f32_16x16x32_bf16 v[38:41], v[156:159], v[144:147], v[38:41]
	v_mfma_f32_16x16x32_bf16 v[42:45], v[160:163], v[144:147], v[42:45]
	v_mfma_f32_16x16x32_bf16 v[46:49], v[164:167], v[144:147], v[46:49]
	v_mfma_f32_16x16x32_bf16 v[50:53], v[152:155], v[148:151], v[50:53]
	v_mfma_f32_16x16x32_bf16 v[54:57], v[156:159], v[148:151], v[54:57]
	v_mfma_f32_16x16x32_bf16 v[58:61], v[160:163], v[148:151], v[58:61]
	v_mfma_f32_16x16x32_bf16 v[62:65], v[164:167], v[148:151], v[62:65]
	s_waitcnt vmcnt(6) lgkmcnt(0)
	s_barrier
	v_mfma_f32_16x16x32_bf16 v[2:5], v[184:187], v[168:171], v[2:5]
	ds_read_b128 v[136:139], v224 offset:0
	v_mfma_f32_16x16x32_bf16 v[6:9], v[188:191], v[168:171], v[6:9]
	ds_read_b128 v[140:143], v224 offset:2048
	v_mfma_f32_16x16x32_bf16 v[10:13], v[192:195], v[168:171], v[10:13]
	ds_read_b128 v[144:147], v224 offset:4096
	v_mfma_f32_16x16x32_bf16 v[14:17], v[196:199], v[168:171], v[14:17]
	ds_read_b128 v[148:151], v224 offset:6144
	v_mfma_f32_16x16x32_bf16 v[18:21], v[184:187], v[172:175], v[18:21]
	ds_read_b128 v[152:155], v232 offset:0
	v_mfma_f32_16x16x32_bf16 v[22:25], v[188:191], v[172:175], v[22:25]
	ds_read_b128 v[156:159], v232 offset:2048
	v_mfma_f32_16x16x32_bf16 v[26:29], v[192:195], v[172:175], v[26:29]
	ds_read_b128 v[160:163], v232 offset:4096
	v_mfma_f32_16x16x32_bf16 v[30:33], v[196:199], v[172:175], v[30:33]
	ds_read_b128 v[164:167], v232 offset:6144
	s_add_u32 m0, s8, 0xc000
	v_mfma_f32_16x16x32_bf16 v[34:37], v[184:187], v[176:179], v[34:37]
	global_load_lds_dwordx4 v200, s[4:5]
	s_add_u32 m0, s8, 0xc400
	v_mfma_f32_16x16x32_bf16 v[38:41], v[188:191], v[176:179], v[38:41]
	global_load_lds_dwordx4 v201, s[4:5]
	s_add_u32 m0, s8, 0xc800
	v_mfma_f32_16x16x32_bf16 v[42:45], v[192:195], v[176:179], v[42:45]
	global_load_lds_dwordx4 v202, s[4:5]
	s_add_u32 m0, s8, 0xcc00
	v_mfma_f32_16x16x32_bf16 v[46:49], v[196:199], v[176:179], v[46:49]
	global_load_lds_dwordx4 v203, s[4:5]
	s_add_u32 m0, s9, 0xc000
	v_mfma_f32_16x16x32_bf16 v[50:53], v[184:187], v[180:183], v[50:53]
	global_load_lds_dwordx4 v204, s[6:7]
	s_add_u32 m0, s9, 0xc400
	v_mfma_f32_16x16x32_bf16 v[54:57], v[188:191], v[180:183], v[54:57]
	global_load_lds_dwordx4 v205, s[6:7]
	v_mfma_f32_16x16x32_bf16 v[58:61], v[192:195], v[180:183], v[58:61]
	s_add_u32 s4, s4, 0x80
	s_addc_u32 s5, s5, 0
	v_mfma_f32_16x16x32_bf16 v[62:65], v[196:199], v[180:183], v[62:65]
	s_add_u32 s6, s6, 0x80
	s_addc_u32 s7, s7, 0
	s_waitcnt lgkmcnt(0)
	v_mfma_f32_16x16x32_bf16 v[2:5], v[152:155], v[136:139], v[2:5]
	ds_read_b128 v[168:171], v229 offset:0
	v_mfma_f32_16x16x32_bf16 v[6:9], v[156:159], v[136:139], v[6:9]
	ds_read_b128 v[172:175], v229 offset:2048
	v_mfma_f32_16x16x32_bf16 v[10:13], v[160:163], v[136:139], v[10:13]
	ds_read_b128 v[176:179], v229 offset:4096
	v_mfma_f32_16x16x32_bf16 v[14:17], v[164:167], v[136:139], v[14:17]
	ds_read_b128 v[180:183], v229 offset:6144
	v_mfma_f32_16x16x32_bf16 v[18:21], v[152:155], v[140:143], v[18:21]
	ds_read_b128 v[184:187], v235 offset:0
	v_mfma_f32_16x16x32_bf16 v[22:25], v[156:159], v[140:143], v[22:25]
	ds_read_b128 v[188:191], v235 offset:2048
	v_mfma_f32_16x16x32_bf16 v[26:29], v[160:163], v[140:143], v[26:29]
	ds_read_b128 v[192:195], v235 offset:4096
	v_mfma_f32_16x16x32_bf16 v[30:33], v[164:167], v[140:143], v[30:33]
	ds_read_b128 v[196:199], v235 offset:6144
	v_mfma_f32_16x16x32_bf16 v[34:37], v[152:155], v[144:147], v[34:37]
	v_mfma_f32_16x16x32_bf16 v[38:41], v[156:159], v[144:147], v[38:41]
	v_mfma_f32_16x16x32_bf16 v[42:45], v[160:163], v[144:147], v[42:45]
	v_mfma_f32_16x16x32_bf16 v[46:49], v[164:167], v[144:147], v[46:49]
	v_mfma_f32_16x16x32_bf16 v[50:53], v[152:155], v[148:151], v[50:53]
	v_mfma_f32_16x16x32_bf16 v[54:57], v[156:159], v[148:151], v[54:57]
	v_mfma_f32_16x16x32_bf16 v[58:61], v[160:163], v[148:151], v[58:61]
	v_mfma_f32_16x16x32_bf16 v[62:65], v[164:167], v[148:151], v[62:65]
	s_waitcnt vmcnt(6) lgkmcnt(0)
	s_barrier
	v_mfma_f32_16x16x32_bf16 v[2:5], v[184:187], v[168:171], v[2:5]
	ds_read_b128 v[136:139], v218 offset:0
	v_mfma_f32_16x16x32_bf16 v[6:9], v[188:191], v[168:171], v[6:9]
	ds_read_b128 v[140:143], v218 offset:2048
	v_mfma_f32_16x16x32_bf16 v[10:13], v[192:195], v[168:171], v[10:13]
	ds_read_b128 v[144:147], v218 offset:4096
	v_mfma_f32_16x16x32_bf16 v[14:17], v[196:199], v[168:171], v[14:17]
	ds_read_b128 v[148:151], v218 offset:6144
	v_mfma_f32_16x16x32_bf16 v[18:21], v[184:187], v[172:175], v[18:21]
	ds_read_b128 v[152:155], v230 offset:0
	v_mfma_f32_16x16x32_bf16 v[22:25], v[188:191], v[172:175], v[22:25]
	ds_read_b128 v[156:159], v230 offset:2048
	v_mfma_f32_16x16x32_bf16 v[26:29], v[192:195], v[172:175], v[26:29]
	ds_read_b128 v[160:163], v230 offset:4096
	v_mfma_f32_16x16x32_bf16 v[30:33], v[196:199], v[172:175], v[30:33]
	ds_read_b128 v[164:167], v230 offset:6144
	s_add_u32 m0, s8, 0x18000
	v_mfma_f32_16x16x32_bf16 v[34:37], v[184:187], v[176:179], v[34:37]
	global_load_lds_dwordx4 v200, s[4:5]
	s_add_u32 m0, s8, 0x18400
	v_mfma_f32_16x16x32_bf16 v[38:41], v[188:191], v[176:179], v[38:41]
	global_load_lds_dwordx4 v201, s[4:5]
	s_add_u32 m0, s8, 0x18800
	v_mfma_f32_16x16x32_bf16 v[42:45], v[192:195], v[176:179], v[42:45]
	global_load_lds_dwordx4 v202, s[4:5]
	s_add_u32 m0, s8, 0x18c00
	v_mfma_f32_16x16x32_bf16 v[46:49], v[196:199], v[176:179], v[46:49]
	global_load_lds_dwordx4 v203, s[4:5]
	s_add_u32 m0, s9, 0x18000
	v_mfma_f32_16x16x32_bf16 v[50:53], v[184:187], v[180:183], v[50:53]
	global_load_lds_dwordx4 v204, s[6:7]
	s_add_u32 m0, s9, 0x18400
	v_mfma_f32_16x16x32_bf16 v[54:57], v[188:191], v[180:183], v[54:57]
	global_load_lds_dwordx4 v205, s[6:7]
	v_mfma_f32_16x16x32_bf16 v[58:61], v[192:195], v[180:183], v[58:61]
	s_add_u32 s4, s4, 0x80
	s_addc_u32 s5, s5, 0
	v_mfma_f32_16x16x32_bf16 v[62:65], v[196:199], v[180:183], v[62:65]
	s_add_u32 s6, s6, 0x80
	s_addc_u32 s7, s7, 0
	s_waitcnt lgkmcnt(0)
	v_mfma_f32_16x16x32_bf16 v[2:5], v[152:155], v[136:139], v[2:5]
	ds_read_b128 v[168:171], v225 offset:0
	v_mfma_f32_16x16x32_bf16 v[6:9], v[156:159], v[136:139], v[6:9]
	ds_read_b128 v[172:175], v225 offset:2048
	v_mfma_f32_16x16x32_bf16 v[10:13], v[160:163], v[136:139], v[10:13]
	ds_read_b128 v[176:179], v225 offset:4096
	v_mfma_f32_16x16x32_bf16 v[14:17], v[164:167], v[136:139], v[14:17]
	ds_read_b128 v[180:183], v225 offset:6144
	v_mfma_f32_16x16x32_bf16 v[18:21], v[152:155], v[140:143], v[18:21]
	ds_read_b128 v[184:187], v233 offset:0
	v_mfma_f32_16x16x32_bf16 v[22:25], v[156:159], v[140:143], v[22:25]
	ds_read_b128 v[188:191], v233 offset:2048
	v_mfma_f32_16x16x32_bf16 v[26:29], v[160:163], v[140:143], v[26:29]
	ds_read_b128 v[192:195], v233 offset:4096
	v_mfma_f32_16x16x32_bf16 v[30:33], v[164:167], v[140:143], v[30:33]
	ds_read_b128 v[196:199], v233 offset:6144
	v_mfma_f32_16x16x32_bf16 v[34:37], v[152:155], v[144:147], v[34:37]
	v_mfma_f32_16x16x32_bf16 v[38:41], v[156:159], v[144:147], v[38:41]
	v_mfma_f32_16x16x32_bf16 v[42:45], v[160:163], v[144:147], v[42:45]
	v_mfma_f32_16x16x32_bf16 v[46:49], v[164:167], v[144:147], v[46:49]
	v_mfma_f32_16x16x32_bf16 v[50:53], v[152:155], v[148:151], v[50:53]
	v_mfma_f32_16x16x32_bf16 v[54:57], v[156:159], v[148:151], v[54:57]
	v_mfma_f32_16x16x32_bf16 v[58:61], v[160:163], v[148:151], v[58:61]
	v_mfma_f32_16x16x32_bf16 v[62:65], v[164:167], v[148:151], v[62:65]
	s_waitcnt vmcnt(6) lgkmcnt(0)
	s_barrier
	v_mfma_f32_16x16x32_bf16 v[2:5], v[184:187], v[168:171], v[2:5]
	ds_read_b128 v[136:139], v219 offset:0
	v_mfma_f32_16x16x32_bf16 v[6:9], v[188:191], v[168:171], v[6:9]
	ds_read_b128 v[140:143], v219 offset:2048
	v_mfma_f32_16x16x32_bf16 v[10:13], v[192:195], v[168:171], v[10:13]
	ds_read_b128 v[144:147], v219 offset:4096
	v_mfma_f32_16x16x32_bf16 v[14:17], v[196:199], v[168:171], v[14:17]
	ds_read_b128 v[148:151], v219 offset:6144
	v_mfma_f32_16x16x32_bf16 v[18:21], v[184:187], v[172:175], v[18:21]
	ds_read_b128 v[152:155], v231 offset:0
	v_mfma_f32_16x16x32_bf16 v[22:25], v[188:191], v[172:175], v[22:25]
	ds_read_b128 v[156:159], v231 offset:2048
	v_mfma_f32_16x16x32_bf16 v[26:29], v[192:195], v[172:175], v[26:29]
	ds_read_b128 v[160:163], v231 offset:4096
	v_mfma_f32_16x16x32_bf16 v[30:33], v[196:199], v[172:175], v[30:33]
	ds_read_b128 v[164:167], v231 offset:6144
	s_mov_b32 m0, s8
	v_mfma_f32_16x16x32_bf16 v[34:37], v[184:187], v[176:179], v[34:37]
	global_load_lds_dwordx4 v200, s[4:5]
	s_add_u32 m0, s8, 0x400
	v_mfma_f32_16x16x32_bf16 v[38:41], v[188:191], v[176:179], v[38:41]
	global_load_lds_dwordx4 v201, s[4:5]
	s_add_u32 m0, s8, 0x800
	v_mfma_f32_16x16x32_bf16 v[42:45], v[192:195], v[176:179], v[42:45]
	global_load_lds_dwordx4 v202, s[4:5]
	s_add_u32 m0, s8, 0xc00
	v_mfma_f32_16x16x32_bf16 v[46:49], v[196:199], v[176:179], v[46:49]
	global_load_lds_dwordx4 v203, s[4:5]
	s_mov_b32 m0, s9
	v_mfma_f32_16x16x32_bf16 v[50:53], v[184:187], v[180:183], v[50:53]
	global_load_lds_dwordx4 v204, s[6:7]
	s_add_u32 m0, s9, 0x400
	v_mfma_f32_16x16x32_bf16 v[54:57], v[188:191], v[180:183], v[54:57]
	global_load_lds_dwordx4 v205, s[6:7]
	v_mfma_f32_16x16x32_bf16 v[58:61], v[192:195], v[180:183], v[58:61]
	s_add_u32 s4, s4, 0x80
	s_addc_u32 s5, s5, 0
	v_mfma_f32_16x16x32_bf16 v[62:65], v[196:199], v[180:183], v[62:65]
	s_add_u32 s6, s6, 0x80
	s_addc_u32 s7, s7, 0
	s_waitcnt lgkmcnt(0)
	v_mfma_f32_16x16x32_bf16 v[66:69], v[152:155], v[136:139], 0
	ds_read_b128 v[168:171], v228 offset:0
	v_mfma_f32_16x16x32_bf16 v[70:73], v[156:159], v[136:139], 0
	ds_read_b128 v[172:175], v228 offset:2048
	s_add_u32 s10, s52, 0x0
	s_addc_u32 s11, s53, 0
	v_mfma_f32_16x16x32_bf16 v[74:77], v[160:163], v[136:139], 0
	ds_read_b128 v[176:179], v228 offset:4096
	v_mul_f32_e32 v1, s12, v2
	v_mfma_f32_16x16x32_bf16 v[78:81], v[164:167], v[136:139], 0
	ds_read_b128 v[180:183], v228 offset:6144
	v_mul_f32_e32 v130, s12, v3
	v_mfma_f32_16x16x32_bf16 v[82:85], v[152:155], v[140:143], 0
	ds_read_b128 v[184:187], v234 offset:0
	v_mul_f32_e32 v238, s12, v4
	v_mfma_f32_16x16x32_bf16 v[86:89], v[156:159], v[140:143], 0
	ds_read_b128 v[188:191], v234 offset:2048
	v_mul_f32_e32 v239, s12, v5
	v_mfma_f32_16x16x32_bf16 v[90:93], v[160:163], v[140:143], 0
	ds_read_b128 v[192:195], v234 offset:4096
	v_exp_f32_e32 v1, v1
	v_mfma_f32_16x16x32_bf16 v[94:97], v[164:167], v[140:143], 0
	ds_read_b128 v[196:199], v234 offset:6144
	v_exp_f32_e32 v130, v130
	v_mfma_f32_16x16x32_bf16 v[98:101], v[152:155], v[144:147], 0
	v_mfma_f32_16x16x32_bf16 v[102:105], v[156:159], v[144:147], 0
	v_exp_f32_e32 v238, v238
	v_mfma_f32_16x16x32_bf16 v[106:109], v[160:163], v[144:147], 0
	v_exp_f32_e32 v239, v239
	v_mfma_f32_16x16x32_bf16 v[110:113], v[164:167], v[144:147], 0
	v_add_f32_e32 v1, 1.0, v1
	v_mfma_f32_16x16x32_bf16 v[114:117], v[152:155], v[148:151], 0
	v_add_f32_e32 v130, 1.0, v130
	v_mfma_f32_16x16x32_bf16 v[118:121], v[156:159], v[148:151], 0
	v_add_f32_e32 v238, 1.0, v238
	v_mfma_f32_16x16x32_bf16 v[122:125], v[160:163], v[148:151], 0
	v_add_f32_e32 v239, 1.0, v239
	v_mfma_f32_16x16x32_bf16 v[126:129], v[164:167], v[148:151], 0
	v_rcp_f32_e32 v1, v1
	s_waitcnt vmcnt(6) lgkmcnt(0)
	s_barrier
	v_mfma_f32_16x16x32_bf16 v[66:69], v[184:187], v[168:171], v[66:69]
	ds_read_b128 v[136:139], v224 offset:0
	v_mfma_f32_16x16x32_bf16 v[70:73], v[188:191], v[168:171], v[70:73]
	ds_read_b128 v[140:143], v224 offset:2048
	v_rcp_f32_e32 v130, v130
	v_mfma_f32_16x16x32_bf16 v[74:77], v[192:195], v[168:171], v[74:77]
	ds_read_b128 v[144:147], v224 offset:4096
	v_mfma_f32_16x16x32_bf16 v[78:81], v[196:199], v[168:171], v[78:81]
	ds_read_b128 v[148:151], v224 offset:6144
	v_rcp_f32_e32 v238, v238
	v_mfma_f32_16x16x32_bf16 v[82:85], v[184:187], v[172:175], v[82:85]
	ds_read_b128 v[152:155], v232 offset:0
	v_rcp_f32_e32 v239, v239
	v_mfma_f32_16x16x32_bf16 v[86:89], v[188:191], v[172:175], v[86:89]
	ds_read_b128 v[156:159], v232 offset:2048
	v_mfma_f32_16x16x32_bf16 v[90:93], v[192:195], v[172:175], v[90:93]
	ds_read_b128 v[160:163], v232 offset:4096
	v_mul_f32_e32 v2, v2, v1
	v_mfma_f32_16x16x32_bf16 v[94:97], v[196:199], v[172:175], v[94:97]
	ds_read_b128 v[164:167], v232 offset:6144
	v_mul_f32_e32 v3, v3, v130
	s_add_u32 m0, s8, 0xc000
	v_mfma_f32_16x16x32_bf16 v[98:101], v[184:187], v[176:179], v[98:101]
	global_load_lds_dwordx4 v200, s[4:5]
	s_add_u32 m0, s8, 0xc400
	v_mfma_f32_16x16x32_bf16 v[102:105], v[188:191], v[176:179], v[102:105]
	global_load_lds_dwordx4 v201, s[4:5]
	v_mul_f32_e32 v4, v4, v238
	s_add_u32 m0, s8, 0xc800
	v_mfma_f32_16x16x32_bf16 v[106:109], v[192:195], v[176:179], v[106:109]
	global_load_lds_dwordx4 v202, s[4:5]
	s_add_u32 m0, s8, 0xcc00
	v_mfma_f32_16x16x32_bf16 v[110:113], v[196:199], v[176:179], v[110:113]
	global_load_lds_dwordx4 v203, s[4:5]
	v_mul_f32_e32 v5, v5, v239
	s_add_u32 m0, s9, 0xc000
	v_mfma_f32_16x16x32_bf16 v[114:117], v[184:187], v[180:183], v[114:117]
	global_load_lds_dwordx4 v204, s[6:7]
	v_cvt_pk_bf16_f32 v2, v2, v3
	s_add_u32 m0, s9, 0xc400
	v_mfma_f32_16x16x32_bf16 v[118:121], v[188:191], v[180:183], v[118:121]
	global_load_lds_dwordx4 v205, s[6:7]
	v_mfma_f32_16x16x32_bf16 v[122:125], v[192:195], v[180:183], v[122:125]
	s_add_u32 s4, s4, 0x80
	s_addc_u32 s5, s5, 0
	v_cvt_pk_bf16_f32 v3, v4, v5
	v_mfma_f32_16x16x32_bf16 v[126:129], v[196:199], v[180:183], v[126:129]
	s_add_u32 s6, s6, 0x80
	s_addc_u32 s7, s7, 0
	global_store_dwordx2 v236, v[2:3], s[10:11] offset:0 sc1
	s_waitcnt lgkmcnt(0)
	v_mfma_f32_16x16x32_bf16 v[66:69], v[152:155], v[136:139], v[66:69]
	ds_read_b128 v[168:171], v229 offset:0
	v_mfma_f32_16x16x32_bf16 v[70:73], v[156:159], v[136:139], v[70:73]
	ds_read_b128 v[172:175], v229 offset:2048
	v_mul_f32_e32 v1, s12, v6
	v_mfma_f32_16x16x32_bf16 v[74:77], v[160:163], v[136:139], v[74:77]
	ds_read_b128 v[176:179], v229 offset:4096
	v_mul_f32_e32 v130, s12, v7
	v_mfma_f32_16x16x32_bf16 v[78:81], v[164:167], v[136:139], v[78:81]
	ds_read_b128 v[180:183], v229 offset:6144
	v_mul_f32_e32 v238, s12, v8
	v_mfma_f32_16x16x32_bf16 v[82:85], v[152:155], v[140:143], v[82:85]
	ds_read_b128 v[184:187], v235 offset:0
	v_mul_f32_e32 v239, s12, v9
	v_mfma_f32_16x16x32_bf16 v[86:89], v[156:159], v[140:143], v[86:89]
	ds_read_b128 v[188:191], v235 offset:2048
	v_exp_f32_e32 v1, v1
	v_mfma_f32_16x16x32_bf16 v[90:93], v[160:163], v[140:143], v[90:93]
	ds_read_b128 v[192:195], v235 offset:4096
	v_exp_f32_e32 v130, v130
	v_mfma_f32_16x16x32_bf16 v[94:97], v[164:167], v[140:143], v[94:97]
	ds_read_b128 v[196:199], v235 offset:6144
	v_exp_f32_e32 v238, v238
	v_mfma_f32_16x16x32_bf16 v[98:101], v[152:155], v[144:147], v[98:101]
	v_mfma_f32_16x16x32_bf16 v[102:105], v[156:159], v[144:147], v[102:105]
	v_exp_f32_e32 v239, v239
	v_mfma_f32_16x16x32_bf16 v[106:109], v[160:163], v[144:147], v[106:109]
	v_add_f32_e32 v1, 1.0, v1
	v_mfma_f32_16x16x32_bf16 v[110:113], v[164:167], v[144:147], v[110:113]
	v_add_f32_e32 v130, 1.0, v130
	v_mfma_f32_16x16x32_bf16 v[114:117], v[152:155], v[148:151], v[114:117]
	v_add_f32_e32 v238, 1.0, v238
	v_mfma_f32_16x16x32_bf16 v[118:121], v[156:159], v[148:151], v[118:121]
	v_add_f32_e32 v239, 1.0, v239
	v_mfma_f32_16x16x32_bf16 v[122:125], v[160:163], v[148:151], v[122:125]
	v_rcp_f32_e32 v1, v1
	v_mfma_f32_16x16x32_bf16 v[126:129], v[164:167], v[148:151], v[126:129]
	v_rcp_f32_e32 v130, v130
	s_waitcnt vmcnt(7) lgkmcnt(0)
	s_barrier
	v_mfma_f32_16x16x32_bf16 v[66:69], v[184:187], v[168:171], v[66:69]
	ds_read_b128 v[136:139], v218 offset:0
	v_mfma_f32_16x16x32_bf16 v[70:73], v[188:191], v[168:171], v[70:73]
	ds_read_b128 v[140:143], v218 offset:2048
	v_rcp_f32_e32 v238, v238
	v_mfma_f32_16x16x32_bf16 v[74:77], v[192:195], v[168:171], v[74:77]
	ds_read_b128 v[144:147], v218 offset:4096
	v_mfma_f32_16x16x32_bf16 v[78:81], v[196:199], v[168:171], v[78:81]
	ds_read_b128 v[148:151], v218 offset:6144
	v_rcp_f32_e32 v239, v239
	v_mfma_f32_16x16x32_bf16 v[82:85], v[184:187], v[172:175], v[82:85]
	ds_read_b128 v[152:155], v230 offset:0
	v_mul_f32_e32 v6, v6, v1
	v_mfma_f32_16x16x32_bf16 v[86:89], v[188:191], v[172:175], v[86:89]
	ds_read_b128 v[156:159], v230 offset:2048
	v_mfma_f32_16x16x32_bf16 v[90:93], v[192:195], v[172:175], v[90:93]
	ds_read_b128 v[160:163], v230 offset:4096
	v_mul_f32_e32 v7, v7, v130
	v_mfma_f32_16x16x32_bf16 v[94:97], v[196:199], v[172:175], v[94:97]
	ds_read_b128 v[164:167], v230 offset:6144
	v_mul_f32_e32 v8, v8, v238
	s_add_u32 m0, s8, 0x18000
	v_mfma_f32_16x16x32_bf16 v[98:101], v[184:187], v[176:179], v[98:101]
	global_load_lds_dwordx4 v200, s[4:5]
	s_add_u32 m0, s8, 0x18400
	v_mfma_f32_16x16x32_bf16 v[102:105], v[188:191], v[176:179], v[102:105]
	global_load_lds_dwordx4 v201, s[4:5]
	v_mul_f32_e32 v9, v9, v239
	s_add_u32 m0, s8, 0x18800
	v_mfma_f32_16x16x32_bf16 v[106:109], v[192:195], v[176:179], v[106:109]
	global_load_lds_dwordx4 v202, s[4:5]
	s_add_u32 m0, s8, 0x18c00
	v_mfma_f32_16x16x32_bf16 v[110:113], v[196:199], v[176:179], v[110:113]
	global_load_lds_dwordx4 v203, s[4:5]
	v_cvt_pk_bf16_f32 v6, v6, v7
	s_add_u32 m0, s9, 0x18000
	v_mfma_f32_16x16x32_bf16 v[114:117], v[184:187], v[180:183], v[114:117]
	global_load_lds_dwordx4 v204, s[6:7]
	v_cvt_pk_bf16_f32 v7, v8, v9
	s_add_u32 m0, s9, 0x18400
	v_mfma_f32_16x16x32_bf16 v[118:121], v[188:191], v[180:183], v[118:121]
	global_load_lds_dwordx4 v205, s[6:7]
	v_mfma_f32_16x16x32_bf16 v[122:125], v[192:195], v[180:183], v[122:125]
	s_add_u32 s4, s4, 0x80
	s_addc_u32 s5, s5, 0
	global_store_dwordx2 v236, v[6:7], s[10:11] offset:32 sc1
	v_mfma_f32_16x16x32_bf16 v[126:129], v[196:199], v[180:183], v[126:129]
	s_add_u32 s6, s6, 0x80
	s_addc_u32 s7, s7, 0
	v_mul_f32_e32 v1, s12, v10
	s_waitcnt lgkmcnt(0)
	v_mfma_f32_16x16x32_bf16 v[66:69], v[152:155], v[136:139], v[66:69]
	ds_read_b128 v[168:171], v225 offset:0
	v_mfma_f32_16x16x32_bf16 v[70:73], v[156:159], v[136:139], v[70:73]
	ds_read_b128 v[172:175], v225 offset:2048
	v_mul_f32_e32 v130, s12, v11
	v_mfma_f32_16x16x32_bf16 v[74:77], v[160:163], v[136:139], v[74:77]
	ds_read_b128 v[176:179], v225 offset:4096
	v_mul_f32_e32 v238, s12, v12
	v_mfma_f32_16x16x32_bf16 v[78:81], v[164:167], v[136:139], v[78:81]
	ds_read_b128 v[180:183], v225 offset:6144
	v_mul_f32_e32 v239, s12, v13
	v_mfma_f32_16x16x32_bf16 v[82:85], v[152:155], v[140:143], v[82:85]
	ds_read_b128 v[184:187], v233 offset:0
	v_exp_f32_e32 v1, v1
	v_mfma_f32_16x16x32_bf16 v[86:89], v[156:159], v[140:143], v[86:89]
	ds_read_b128 v[188:191], v233 offset:2048
	v_exp_f32_e32 v130, v130
	v_mfma_f32_16x16x32_bf16 v[90:93], v[160:163], v[140:143], v[90:93]
	ds_read_b128 v[192:195], v233 offset:4096
	v_exp_f32_e32 v238, v238
	v_mfma_f32_16x16x32_bf16 v[94:97], v[164:167], v[140:143], v[94:97]
	ds_read_b128 v[196:199], v233 offset:6144
	v_exp_f32_e32 v239, v239
	v_mfma_f32_16x16x32_bf16 v[98:101], v[152:155], v[144:147], v[98:101]
	v_mfma_f32_16x16x32_bf16 v[102:105], v[156:159], v[144:147], v[102:105]
	v_add_f32_e32 v1, 1.0, v1
	v_mfma_f32_16x16x32_bf16 v[106:109], v[160:163], v[144:147], v[106:109]
	v_add_f32_e32 v130, 1.0, v130
	v_mfma_f32_16x16x32_bf16 v[110:113], v[164:167], v[144:147], v[110:113]
	v_add_f32_e32 v238, 1.0, v238
	v_mfma_f32_16x16x32_bf16 v[114:117], v[152:155], v[148:151], v[114:117]
	v_add_f32_e32 v239, 1.0, v239
	v_mfma_f32_16x16x32_bf16 v[118:121], v[156:159], v[148:151], v[118:121]
	v_rcp_f32_e32 v1, v1
	v_mfma_f32_16x16x32_bf16 v[122:125], v[160:163], v[148:151], v[122:125]
	v_rcp_f32_e32 v130, v130
	v_mfma_f32_16x16x32_bf16 v[126:129], v[164:167], v[148:151], v[126:129]
	v_rcp_f32_e32 v238, v238
	s_waitcnt vmcnt(8) lgkmcnt(0)
	s_barrier
	v_mfma_f32_16x16x32_bf16 v[66:69], v[184:187], v[168:171], v[66:69]
	ds_read_b128 v[136:139], v219 offset:0
	v_mfma_f32_16x16x32_bf16 v[70:73], v[188:191], v[168:171], v[70:73]
	ds_read_b128 v[140:143], v219 offset:2048
	v_rcp_f32_e32 v239, v239
	v_mfma_f32_16x16x32_bf16 v[74:77], v[192:195], v[168:171], v[74:77]
	ds_read_b128 v[144:147], v219 offset:4096
	v_mfma_f32_16x16x32_bf16 v[78:81], v[196:199], v[168:171], v[78:81]
	ds_read_b128 v[148:151], v219 offset:6144
	v_mul_f32_e32 v10, v10, v1
	v_mfma_f32_16x16x32_bf16 v[82:85], v[184:187], v[172:175], v[82:85]
	ds_read_b128 v[152:155], v231 offset:0
	v_mul_f32_e32 v11, v11, v130
	v_mfma_f32_16x16x32_bf16 v[86:89], v[188:191], v[172:175], v[86:89]
	ds_read_b128 v[156:159], v231 offset:2048
	v_mfma_f32_16x16x32_bf16 v[90:93], v[192:195], v[172:175], v[90:93]
	ds_read_b128 v[160:163], v231 offset:4096
	v_mul_f32_e32 v12, v12, v238
	v_mfma_f32_16x16x32_bf16 v[94:97], v[196:199], v[172:175], v[94:97]
	ds_read_b128 v[164:167], v231 offset:6144
	v_mul_f32_e32 v13, v13, v239
	s_mov_b32 m0, s8
	v_mfma_f32_16x16x32_bf16 v[98:101], v[184:187], v[176:179], v[98:101]
	global_load_lds_dwordx4 v200, s[4:5]
	s_add_u32 m0, s8, 0x400
	v_mfma_f32_16x16x32_bf16 v[102:105], v[188:191], v[176:179], v[102:105]
	global_load_lds_dwordx4 v201, s[4:5]
	v_cvt_pk_bf16_f32 v10, v10, v11
	s_add_u32 m0, s8, 0x800
	v_mfma_f32_16x16x32_bf16 v[106:109], v[192:195], v[176:179], v[106:109]
	global_load_lds_dwordx4 v202, s[4:5]
	s_add_u32 m0, s8, 0xc00
	v_mfma_f32_16x16x32_bf16 v[110:113], v[196:199], v[176:179], v[110:113]
	global_load_lds_dwordx4 v203, s[4:5]
	v_cvt_pk_bf16_f32 v11, v12, v13
	s_mov_b32 m0, s9
	v_mfma_f32_16x16x32_bf16 v[114:117], v[184:187], v[180:183], v[114:117]
	global_load_lds_dwordx4 v204, s[6:7]
	global_store_dwordx2 v236, v[10:11], s[10:11] offset:64 sc1
	s_add_u32 m0, s9, 0x400
	v_mfma_f32_16x16x32_bf16 v[118:121], v[188:191], v[180:183], v[118:121]
	global_load_lds_dwordx4 v205, s[6:7]
	v_mfma_f32_16x16x32_bf16 v[122:125], v[192:195], v[180:183], v[122:125]
	s_add_u32 s4, s4, 0x80
	s_addc_u32 s5, s5, 0
	v_mul_f32_e32 v1, s12, v14
	v_mfma_f32_16x16x32_bf16 v[126:129], v[196:199], v[180:183], v[126:129]
	s_add_u32 s6, s6, 0x80
	s_addc_u32 s7, s7, 0
	v_mul_f32_e32 v130, s12, v15
	s_waitcnt lgkmcnt(0)
	v_mfma_f32_16x16x32_bf16 v[66:69], v[152:155], v[136:139], v[66:69]
	ds_read_b128 v[168:171], v228 offset:0
	v_mfma_f32_16x16x32_bf16 v[70:73], v[156:159], v[136:139], v[70:73]
	ds_read_b128 v[172:175], v228 offset:2048
	v_mul_f32_e32 v238, s12, v16
	v_mfma_f32_16x16x32_bf16 v[74:77], v[160:163], v[136:139], v[74:77]
	ds_read_b128 v[176:179], v228 offset:4096
	v_mul_f32_e32 v239, s12, v17
	v_mfma_f32_16x16x32_bf16 v[78:81], v[164:167], v[136:139], v[78:81]
	ds_read_b128 v[180:183], v228 offset:6144
	v_exp_f32_e32 v1, v1
	v_mfma_f32_16x16x32_bf16 v[82:85], v[152:155], v[140:143], v[82:85]
	ds_read_b128 v[184:187], v234 offset:0
	v_exp_f32_e32 v130, v130
	v_mfma_f32_16x16x32_bf16 v[86:89], v[156:159], v[140:143], v[86:89]
	ds_read_b128 v[188:191], v234 offset:2048
	v_exp_f32_e32 v238, v238
	v_mfma_f32_16x16x32_bf16 v[90:93], v[160:163], v[140:143], v[90:93]
	ds_read_b128 v[192:195], v234 offset:4096
	v_exp_f32_e32 v239, v239
	v_mfma_f32_16x16x32_bf16 v[94:97], v[164:167], v[140:143], v[94:97]
	ds_read_b128 v[196:199], v234 offset:6144
	v_add_f32_e32 v1, 1.0, v1
	v_mfma_f32_16x16x32_bf16 v[98:101], v[152:155], v[144:147], v[98:101]
	v_mfma_f32_16x16x32_bf16 v[102:105], v[156:159], v[144:147], v[102:105]
	v_add_f32_e32 v130, 1.0, v130
	v_mfma_f32_16x16x32_bf16 v[106:109], v[160:163], v[144:147], v[106:109]
	v_add_f32_e32 v238, 1.0, v238
	v_mfma_f32_16x16x32_bf16 v[110:113], v[164:167], v[144:147], v[110:113]
	v_add_f32_e32 v239, 1.0, v239
	v_mfma_f32_16x16x32_bf16 v[114:117], v[152:155], v[148:151], v[114:117]
	v_rcp_f32_e32 v1, v1
	v_mfma_f32_16x16x32_bf16 v[118:121], v[156:159], v[148:151], v[118:121]
	v_rcp_f32_e32 v130, v130
	v_mfma_f32_16x16x32_bf16 v[122:125], v[160:163], v[148:151], v[122:125]
	v_rcp_f32_e32 v238, v238
	v_mfma_f32_16x16x32_bf16 v[126:129], v[164:167], v[148:151], v[126:129]
	v_rcp_f32_e32 v239, v239
	s_waitcnt vmcnt(8) lgkmcnt(0)
	s_barrier
	v_mfma_f32_16x16x32_bf16 v[66:69], v[184:187], v[168:171], v[66:69]
	ds_read_b128 v[136:139], v224 offset:0
	v_mfma_f32_16x16x32_bf16 v[70:73], v[188:191], v[168:171], v[70:73]
	ds_read_b128 v[140:143], v224 offset:2048
	v_mul_f32_e32 v14, v14, v1
	v_mfma_f32_16x16x32_bf16 v[74:77], v[192:195], v[168:171], v[74:77]
	ds_read_b128 v[144:147], v224 offset:4096
	v_mfma_f32_16x16x32_bf16 v[78:81], v[196:199], v[168:171], v[78:81]
	ds_read_b128 v[148:151], v224 offset:6144
	v_mul_f32_e32 v15, v15, v130
	v_mfma_f32_16x16x32_bf16 v[82:85], v[184:187], v[172:175], v[82:85]
	ds_read_b128 v[152:155], v232 offset:0
	v_mul_f32_e32 v16, v16, v238
	v_mfma_f32_16x16x32_bf16 v[86:89], v[188:191], v[172:175], v[86:89]
	ds_read_b128 v[156:159], v232 offset:2048
	v_mfma_f32_16x16x32_bf16 v[90:93], v[192:195], v[172:175], v[90:93]
	ds_read_b128 v[160:163], v232 offset:4096
	v_mul_f32_e32 v17, v17, v239
	v_mfma_f32_16x16x32_bf16 v[94:97], v[196:199], v[172:175], v[94:97]
	ds_read_b128 v[164:167], v232 offset:6144
	v_cvt_pk_bf16_f32 v14, v14, v15
	s_add_u32 m0, s8, 0xc000
	v_mfma_f32_16x16x32_bf16 v[98:101], v[184:187], v[176:179], v[98:101]
	global_load_lds_dwordx4 v200, s[4:5]
	s_add_u32 m0, s8, 0xc400
	v_mfma_f32_16x16x32_bf16 v[102:105], v[188:191], v[176:179], v[102:105]
	global_load_lds_dwordx4 v201, s[4:5]
	v_cvt_pk_bf16_f32 v15, v16, v17
	s_add_u32 m0, s8, 0xc800
	v_mfma_f32_16x16x32_bf16 v[106:109], v[192:195], v[176:179], v[106:109]
	global_load_lds_dwordx4 v202, s[4:5]
	s_add_u32 m0, s8, 0xcc00
	v_mfma_f32_16x16x32_bf16 v[110:113], v[196:199], v[176:179], v[110:113]
	global_load_lds_dwordx4 v203, s[4:5]
	global_store_dwordx2 v236, v[14:15], s[10:11] offset:96 sc1
	s_add_u32 m0, s9, 0xc000
	v_mfma_f32_16x16x32_bf16 v[114:117], v[184:187], v[180:183], v[114:117]
	global_load_lds_dwordx4 v204, s[6:7]
	s_add_u32 s10, s10, 0x8000
	s_addc_u32 s11, s11, 0
	s_add_u32 m0, s9, 0xc400
	v_mfma_f32_16x16x32_bf16 v[118:121], v[188:191], v[180:183], v[118:121]
	global_load_lds_dwordx4 v205, s[6:7]
	v_mfma_f32_16x16x32_bf16 v[122:125], v[192:195], v[180:183], v[122:125]
	s_add_u32 s4, s4, 0x80
	s_addc_u32 s5, s5, 0
	v_mul_f32_e32 v1, s12, v18
	v_mfma_f32_16x16x32_bf16 v[126:129], v[196:199], v[180:183], v[126:129]
	s_add_u32 s6, s6, 0x80
	s_addc_u32 s7, s7, 0
	v_mul_f32_e32 v130, s12, v19
	s_waitcnt lgkmcnt(0)
	v_mfma_f32_16x16x32_bf16 v[66:69], v[152:155], v[136:139], v[66:69]
	ds_read_b128 v[168:171], v229 offset:0
	v_mfma_f32_16x16x32_bf16 v[70:73], v[156:159], v[136:139], v[70:73]
	ds_read_b128 v[172:175], v229 offset:2048
	v_mul_f32_e32 v238, s12, v20
	v_mfma_f32_16x16x32_bf16 v[74:77], v[160:163], v[136:139], v[74:77]
	ds_read_b128 v[176:179], v229 offset:4096
	v_mul_f32_e32 v239, s12, v21
	v_mfma_f32_16x16x32_bf16 v[78:81], v[164:167], v[136:139], v[78:81]
	ds_read_b128 v[180:183], v229 offset:6144
	v_exp_f32_e32 v1, v1
	v_mfma_f32_16x16x32_bf16 v[82:85], v[152:155], v[140:143], v[82:85]
	ds_read_b128 v[184:187], v235 offset:0
	v_exp_f32_e32 v130, v130
	v_mfma_f32_16x16x32_bf16 v[86:89], v[156:159], v[140:143], v[86:89]
	ds_read_b128 v[188:191], v235 offset:2048
	v_exp_f32_e32 v238, v238
	v_mfma_f32_16x16x32_bf16 v[90:93], v[160:163], v[140:143], v[90:93]
	ds_read_b128 v[192:195], v235 offset:4096
	v_exp_f32_e32 v239, v239
	v_mfma_f32_16x16x32_bf16 v[94:97], v[164:167], v[140:143], v[94:97]
	ds_read_b128 v[196:199], v235 offset:6144
	v_add_f32_e32 v1, 1.0, v1
	v_mfma_f32_16x16x32_bf16 v[98:101], v[152:155], v[144:147], v[98:101]
	v_mfma_f32_16x16x32_bf16 v[102:105], v[156:159], v[144:147], v[102:105]
	v_add_f32_e32 v130, 1.0, v130
	v_mfma_f32_16x16x32_bf16 v[106:109], v[160:163], v[144:147], v[106:109]
	v_add_f32_e32 v238, 1.0, v238
	v_mfma_f32_16x16x32_bf16 v[110:113], v[164:167], v[144:147], v[110:113]
	v_add_f32_e32 v239, 1.0, v239
	v_mfma_f32_16x16x32_bf16 v[114:117], v[152:155], v[148:151], v[114:117]
	v_rcp_f32_e32 v1, v1
	v_mfma_f32_16x16x32_bf16 v[118:121], v[156:159], v[148:151], v[118:121]
	v_rcp_f32_e32 v130, v130
	v_mfma_f32_16x16x32_bf16 v[122:125], v[160:163], v[148:151], v[122:125]
	v_rcp_f32_e32 v238, v238
	v_mfma_f32_16x16x32_bf16 v[126:129], v[164:167], v[148:151], v[126:129]
	v_rcp_f32_e32 v239, v239
	s_waitcnt vmcnt(7) lgkmcnt(0)
	s_barrier
	v_mfma_f32_16x16x32_bf16 v[66:69], v[184:187], v[168:171], v[66:69]
	ds_read_b128 v[136:139], v218 offset:0
	v_mfma_f32_16x16x32_bf16 v[70:73], v[188:191], v[168:171], v[70:73]
	ds_read_b128 v[140:143], v218 offset:2048
	v_mul_f32_e32 v18, v18, v1
	v_mfma_f32_16x16x32_bf16 v[74:77], v[192:195], v[168:171], v[74:77]
	ds_read_b128 v[144:147], v218 offset:4096
	v_mfma_f32_16x16x32_bf16 v[78:81], v[196:199], v[168:171], v[78:81]
	ds_read_b128 v[148:151], v218 offset:6144
	v_mul_f32_e32 v19, v19, v130
	v_mfma_f32_16x16x32_bf16 v[82:85], v[184:187], v[172:175], v[82:85]
	ds_read_b128 v[152:155], v230 offset:0
	v_mul_f32_e32 v20, v20, v238
	v_mfma_f32_16x16x32_bf16 v[86:89], v[188:191], v[172:175], v[86:89]
	ds_read_b128 v[156:159], v230 offset:2048
	v_mfma_f32_16x16x32_bf16 v[90:93], v[192:195], v[172:175], v[90:93]
	ds_read_b128 v[160:163], v230 offset:4096
	v_mul_f32_e32 v21, v21, v239
	v_mfma_f32_16x16x32_bf16 v[94:97], v[196:199], v[172:175], v[94:97]
	ds_read_b128 v[164:167], v230 offset:6144
	v_cvt_pk_bf16_f32 v18, v18, v19
	s_add_u32 m0, s8, 0x18000
	v_mfma_f32_16x16x32_bf16 v[98:101], v[184:187], v[176:179], v[98:101]
	global_load_lds_dwordx4 v200, s[4:5]
	s_add_u32 m0, s8, 0x18400
	v_mfma_f32_16x16x32_bf16 v[102:105], v[188:191], v[176:179], v[102:105]
	global_load_lds_dwordx4 v201, s[4:5]
	v_cvt_pk_bf16_f32 v19, v20, v21
	s_add_u32 m0, s8, 0x18800
	v_mfma_f32_16x16x32_bf16 v[106:109], v[192:195], v[176:179], v[106:109]
	global_load_lds_dwordx4 v202, s[4:5]
	s_add_u32 m0, s8, 0x18c00
	v_mfma_f32_16x16x32_bf16 v[110:113], v[196:199], v[176:179], v[110:113]
	global_load_lds_dwordx4 v203, s[4:5]
	global_store_dwordx2 v236, v[18:19], s[10:11] offset:0 sc1
	s_add_u32 m0, s9, 0x18000
	v_mfma_f32_16x16x32_bf16 v[114:117], v[184:187], v[180:183], v[114:117]
	global_load_lds_dwordx4 v204, s[6:7]
	v_mul_f32_e32 v1, s12, v22
	s_add_u32 m0, s9, 0x18400
	v_mfma_f32_16x16x32_bf16 v[118:121], v[188:191], v[180:183], v[118:121]
	global_load_lds_dwordx4 v205, s[6:7]
	v_mfma_f32_16x16x32_bf16 v[122:125], v[192:195], v[180:183], v[122:125]
	s_add_u32 s4, s4, 0x80
	s_addc_u32 s5, s5, 0
	v_mul_f32_e32 v130, s12, v23
	v_mfma_f32_16x16x32_bf16 v[126:129], v[196:199], v[180:183], v[126:129]
	s_add_u32 s6, s6, 0x80
	s_addc_u32 s7, s7, 0
	v_mul_f32_e32 v238, s12, v24
	s_waitcnt lgkmcnt(0)
	v_mfma_f32_16x16x32_bf16 v[66:69], v[152:155], v[136:139], v[66:69]
	ds_read_b128 v[168:171], v225 offset:0
	v_mfma_f32_16x16x32_bf16 v[70:73], v[156:159], v[136:139], v[70:73]
	ds_read_b128 v[172:175], v225 offset:2048
	v_mul_f32_e32 v239, s12, v25
	v_mfma_f32_16x16x32_bf16 v[74:77], v[160:163], v[136:139], v[74:77]
	ds_read_b128 v[176:179], v225 offset:4096
	v_exp_f32_e32 v1, v1
	v_mfma_f32_16x16x32_bf16 v[78:81], v[164:167], v[136:139], v[78:81]
	ds_read_b128 v[180:183], v225 offset:6144
	v_exp_f32_e32 v130, v130
	v_mfma_f32_16x16x32_bf16 v[82:85], v[152:155], v[140:143], v[82:85]
	ds_read_b128 v[184:187], v233 offset:0
	v_exp_f32_e32 v238, v238
	v_mfma_f32_16x16x32_bf16 v[86:89], v[156:159], v[140:143], v[86:89]
	ds_read_b128 v[188:191], v233 offset:2048
	v_exp_f32_e32 v239, v239
	v_mfma_f32_16x16x32_bf16 v[90:93], v[160:163], v[140:143], v[90:93]
	ds_read_b128 v[192:195], v233 offset:4096
	v_add_f32_e32 v1, 1.0, v1
	v_mfma_f32_16x16x32_bf16 v[94:97], v[164:167], v[140:143], v[94:97]
	ds_read_b128 v[196:199], v233 offset:6144
	v_add_f32_e32 v130, 1.0, v130
	v_mfma_f32_16x16x32_bf16 v[98:101], v[152:155], v[144:147], v[98:101]
	v_mfma_f32_16x16x32_bf16 v[102:105], v[156:159], v[144:147], v[102:105]
	v_add_f32_e32 v238, 1.0, v238
	v_mfma_f32_16x16x32_bf16 v[106:109], v[160:163], v[144:147], v[106:109]
	v_add_f32_e32 v239, 1.0, v239
	v_mfma_f32_16x16x32_bf16 v[110:113], v[164:167], v[144:147], v[110:113]
	v_rcp_f32_e32 v1, v1
	v_mfma_f32_16x16x32_bf16 v[114:117], v[152:155], v[148:151], v[114:117]
	v_rcp_f32_e32 v130, v130
	v_mfma_f32_16x16x32_bf16 v[118:121], v[156:159], v[148:151], v[118:121]
	v_rcp_f32_e32 v238, v238
	v_mfma_f32_16x16x32_bf16 v[122:125], v[160:163], v[148:151], v[122:125]
	v_rcp_f32_e32 v239, v239
	v_mfma_f32_16x16x32_bf16 v[126:129], v[164:167], v[148:151], v[126:129]
	v_mul_f32_e32 v22, v22, v1
	s_waitcnt vmcnt(7) lgkmcnt(0)
	s_barrier
	v_mfma_f32_16x16x32_bf16 v[66:69], v[184:187], v[168:171], v[66:69]
	ds_read_b128 v[136:139], v219 offset:0
	v_mfma_f32_16x16x32_bf16 v[70:73], v[188:191], v[168:171], v[70:73]
	ds_read_b128 v[140:143], v219 offset:2048
	v_mul_f32_e32 v23, v23, v130
	v_mfma_f32_16x16x32_bf16 v[74:77], v[192:195], v[168:171], v[74:77]
	ds_read_b128 v[144:147], v219 offset:4096
	v_mfma_f32_16x16x32_bf16 v[78:81], v[196:199], v[168:171], v[78:81]
	ds_read_b128 v[148:151], v219 offset:6144
	v_mul_f32_e32 v24, v24, v238
	v_mfma_f32_16x16x32_bf16 v[82:85], v[184:187], v[172:175], v[82:85]
	ds_read_b128 v[152:155], v231 offset:0
	v_mul_f32_e32 v25, v25, v239
	v_mfma_f32_16x16x32_bf16 v[86:89], v[188:191], v[172:175], v[86:89]
	ds_read_b128 v[156:159], v231 offset:2048
	v_mfma_f32_16x16x32_bf16 v[90:93], v[192:195], v[172:175], v[90:93]
	ds_read_b128 v[160:163], v231 offset:4096
	v_cvt_pk_bf16_f32 v22, v22, v23
	v_mfma_f32_16x16x32_bf16 v[94:97], v[196:199], v[172:175], v[94:97]
	ds_read_b128 v[164:167], v231 offset:6144
	v_cvt_pk_bf16_f32 v23, v24, v25
	s_mov_b32 m0, s8
	v_mfma_f32_16x16x32_bf16 v[98:101], v[184:187], v[176:179], v[98:101]
	global_load_lds_dwordx4 v200, s[4:5]
	s_add_u32 m0, s8, 0x400
	v_mfma_f32_16x16x32_bf16 v[102:105], v[188:191], v[176:179], v[102:105]
	global_load_lds_dwordx4 v201, s[4:5]
	global_store_dwordx2 v236, v[22:23], s[10:11] offset:32 sc1
	s_add_u32 m0, s8, 0x800
	v_mfma_f32_16x16x32_bf16 v[106:109], v[192:195], v[176:179], v[106:109]
	global_load_lds_dwordx4 v202, s[4:5]
	s_add_u32 m0, s8, 0xc00
	v_mfma_f32_16x16x32_bf16 v[110:113], v[196:199], v[176:179], v[110:113]
	global_load_lds_dwordx4 v203, s[4:5]
	v_mul_f32_e32 v1, s12, v26
	s_mov_b32 m0, s9
	v_mfma_f32_16x16x32_bf16 v[114:117], v[184:187], v[180:183], v[114:117]
	global_load_lds_dwordx4 v204, s[6:7]
	v_mul_f32_e32 v130, s12, v27
	s_add_u32 m0, s9, 0x400
	v_mfma_f32_16x16x32_bf16 v[118:121], v[188:191], v[180:183], v[118:121]
	global_load_lds_dwordx4 v205, s[6:7]
	v_mfma_f32_16x16x32_bf16 v[122:125], v[192:195], v[180:183], v[122:125]
	s_add_u32 s4, s4, 0x80
	s_addc_u32 s5, s5, 0
	v_mul_f32_e32 v238, s12, v28
	v_mfma_f32_16x16x32_bf16 v[126:129], v[196:199], v[180:183], v[126:129]
	s_add_u32 s6, s6, 0x80
	s_addc_u32 s7, s7, 0
	v_mul_f32_e32 v239, s12, v29
	s_waitcnt lgkmcnt(0)
	v_mfma_f32_16x16x32_bf16 v[66:69], v[152:155], v[136:139], v[66:69]
	ds_read_b128 v[168:171], v228 offset:0
	v_mfma_f32_16x16x32_bf16 v[70:73], v[156:159], v[136:139], v[70:73]
	ds_read_b128 v[172:175], v228 offset:2048
	v_exp_f32_e32 v1, v1
	v_mfma_f32_16x16x32_bf16 v[74:77], v[160:163], v[136:139], v[74:77]
	ds_read_b128 v[176:179], v228 offset:4096
	v_exp_f32_e32 v130, v130
	v_mfma_f32_16x16x32_bf16 v[78:81], v[164:167], v[136:139], v[78:81]
	ds_read_b128 v[180:183], v228 offset:6144
	v_exp_f32_e32 v238, v238
	v_mfma_f32_16x16x32_bf16 v[82:85], v[152:155], v[140:143], v[82:85]
	ds_read_b128 v[184:187], v234 offset:0
	v_exp_f32_e32 v239, v239
	v_mfma_f32_16x16x32_bf16 v[86:89], v[156:159], v[140:143], v[86:89]
	ds_read_b128 v[188:191], v234 offset:2048
	v_add_f32_e32 v1, 1.0, v1
	v_mfma_f32_16x16x32_bf16 v[90:93], v[160:163], v[140:143], v[90:93]
	ds_read_b128 v[192:195], v234 offset:4096
	v_add_f32_e32 v130, 1.0, v130
	v_mfma_f32_16x16x32_bf16 v[94:97], v[164:167], v[140:143], v[94:97]
	ds_read_b128 v[196:199], v234 offset:6144
	v_add_f32_e32 v238, 1.0, v238
	v_mfma_f32_16x16x32_bf16 v[98:101], v[152:155], v[144:147], v[98:101]
	v_mfma_f32_16x16x32_bf16 v[102:105], v[156:159], v[144:147], v[102:105]
	v_add_f32_e32 v239, 1.0, v239
	v_mfma_f32_16x16x32_bf16 v[106:109], v[160:163], v[144:147], v[106:109]
	v_rcp_f32_e32 v1, v1
	v_mfma_f32_16x16x32_bf16 v[110:113], v[164:167], v[144:147], v[110:113]
	v_rcp_f32_e32 v130, v130
	v_mfma_f32_16x16x32_bf16 v[114:117], v[152:155], v[148:151], v[114:117]
	v_rcp_f32_e32 v238, v238
	v_mfma_f32_16x16x32_bf16 v[118:121], v[156:159], v[148:151], v[118:121]
	v_rcp_f32_e32 v239, v239
	v_mfma_f32_16x16x32_bf16 v[122:125], v[160:163], v[148:151], v[122:125]
	v_mul_f32_e32 v26, v26, v1
	v_mfma_f32_16x16x32_bf16 v[126:129], v[164:167], v[148:151], v[126:129]
	v_mul_f32_e32 v27, v27, v130
	s_waitcnt vmcnt(7) lgkmcnt(0)
	s_barrier
	v_mfma_f32_16x16x32_bf16 v[66:69], v[184:187], v[168:171], v[66:69]
	ds_read_b128 v[136:139], v224 offset:0
	v_mfma_f32_16x16x32_bf16 v[70:73], v[188:191], v[168:171], v[70:73]
	ds_read_b128 v[140:143], v224 offset:2048
	v_mul_f32_e32 v28, v28, v238
	v_mfma_f32_16x16x32_bf16 v[74:77], v[192:195], v[168:171], v[74:77]
	ds_read_b128 v[144:147], v224 offset:4096
	v_mfma_f32_16x16x32_bf16 v[78:81], v[196:199], v[168:171], v[78:81]
	ds_read_b128 v[148:151], v224 offset:6144
	v_mul_f32_e32 v29, v29, v239
	v_mfma_f32_16x16x32_bf16 v[82:85], v[184:187], v[172:175], v[82:85]
	ds_read_b128 v[152:155], v232 offset:0
	v_cvt_pk_bf16_f32 v26, v26, v27
	v_mfma_f32_16x16x32_bf16 v[86:89], v[188:191], v[172:175], v[86:89]
	ds_read_b128 v[156:159], v232 offset:2048
	v_mfma_f32_16x16x32_bf16 v[90:93], v[192:195], v[172:175], v[90:93]
	ds_read_b128 v[160:163], v232 offset:4096
	v_cvt_pk_bf16_f32 v27, v28, v29
	v_mfma_f32_16x16x32_bf16 v[94:97], v[196:199], v[172:175], v[94:97]
	ds_read_b128 v[164:167], v232 offset:6144
	global_store_dwordx2 v236, v[26:27], s[10:11] offset:64 sc1
	s_add_u32 m0, s8, 0xc000
	v_mfma_f32_16x16x32_bf16 v[98:101], v[184:187], v[176:179], v[98:101]
	global_load_lds_dwordx4 v200, s[4:5]
	s_add_u32 m0, s8, 0xc400
	v_mfma_f32_16x16x32_bf16 v[102:105], v[188:191], v[176:179], v[102:105]
	global_load_lds_dwordx4 v201, s[4:5]
	v_mul_f32_e32 v1, s12, v30
	s_add_u32 m0, s8, 0xc800
	v_mfma_f32_16x16x32_bf16 v[106:109], v[192:195], v[176:179], v[106:109]
	global_load_lds_dwordx4 v202, s[4:5]
	s_add_u32 m0, s8, 0xcc00
	v_mfma_f32_16x16x32_bf16 v[110:113], v[196:199], v[176:179], v[110:113]
	global_load_lds_dwordx4 v203, s[4:5]
	v_mul_f32_e32 v130, s12, v31
	s_add_u32 m0, s9, 0xc000
	v_mfma_f32_16x16x32_bf16 v[114:117], v[184:187], v[180:183], v[114:117]
	global_load_lds_dwordx4 v204, s[6:7]
	v_mul_f32_e32 v238, s12, v32
	s_add_u32 m0, s9, 0xc400
	v_mfma_f32_16x16x32_bf16 v[118:121], v[188:191], v[180:183], v[118:121]
	global_load_lds_dwordx4 v205, s[6:7]
	v_mfma_f32_16x16x32_bf16 v[122:125], v[192:195], v[180:183], v[122:125]
	s_add_u32 s4, s4, 0x80
	s_addc_u32 s5, s5, 0
	v_mul_f32_e32 v239, s12, v33
	v_mfma_f32_16x16x32_bf16 v[126:129], v[196:199], v[180:183], v[126:129]
	s_add_u32 s6, s6, 0x80
	s_addc_u32 s7, s7, 0
	v_exp_f32_e32 v1, v1
	s_waitcnt lgkmcnt(0)
	v_mfma_f32_16x16x32_bf16 v[66:69], v[152:155], v[136:139], v[66:69]
	ds_read_b128 v[168:171], v229 offset:0
	v_mfma_f32_16x16x32_bf16 v[70:73], v[156:159], v[136:139], v[70:73]
	ds_read_b128 v[172:175], v229 offset:2048
	v_exp_f32_e32 v130, v130
	v_mfma_f32_16x16x32_bf16 v[74:77], v[160:163], v[136:139], v[74:77]
	ds_read_b128 v[176:179], v229 offset:4096
	v_exp_f32_e32 v238, v238
	v_mfma_f32_16x16x32_bf16 v[78:81], v[164:167], v[136:139], v[78:81]
	ds_read_b128 v[180:183], v229 offset:6144
	v_exp_f32_e32 v239, v239
	v_mfma_f32_16x16x32_bf16 v[82:85], v[152:155], v[140:143], v[82:85]
	ds_read_b128 v[184:187], v235 offset:0
	v_add_f32_e32 v1, 1.0, v1
	v_mfma_f32_16x16x32_bf16 v[86:89], v[156:159], v[140:143], v[86:89]
	ds_read_b128 v[188:191], v235 offset:2048
	v_add_f32_e32 v130, 1.0, v130
	v_mfma_f32_16x16x32_bf16 v[90:93], v[160:163], v[140:143], v[90:93]
	ds_read_b128 v[192:195], v235 offset:4096
	v_add_f32_e32 v238, 1.0, v238
	v_mfma_f32_16x16x32_bf16 v[94:97], v[164:167], v[140:143], v[94:97]
	ds_read_b128 v[196:199], v235 offset:6144
	v_add_f32_e32 v239, 1.0, v239
	v_mfma_f32_16x16x32_bf16 v[98:101], v[152:155], v[144:147], v[98:101]
	v_mfma_f32_16x16x32_bf16 v[102:105], v[156:159], v[144:147], v[102:105]
	v_rcp_f32_e32 v1, v1
	v_mfma_f32_16x16x32_bf16 v[106:109], v[160:163], v[144:147], v[106:109]
	v_rcp_f32_e32 v130, v130
	v_mfma_f32_16x16x32_bf16 v[110:113], v[164:167], v[144:147], v[110:113]
	v_rcp_f32_e32 v238, v238
	v_mfma_f32_16x16x32_bf16 v[114:117], v[152:155], v[148:151], v[114:117]
	v_rcp_f32_e32 v239, v239
	v_mfma_f32_16x16x32_bf16 v[118:121], v[156:159], v[148:151], v[118:121]
	v_mul_f32_e32 v30, v30, v1
	v_mfma_f32_16x16x32_bf16 v[122:125], v[160:163], v[148:151], v[122:125]
	v_mul_f32_e32 v31, v31, v130
	v_mfma_f32_16x16x32_bf16 v[126:129], v[164:167], v[148:151], v[126:129]
	v_mul_f32_e32 v32, v32, v238
	s_waitcnt vmcnt(7) lgkmcnt(0)
	s_barrier
	v_mfma_f32_16x16x32_bf16 v[66:69], v[184:187], v[168:171], v[66:69]
	ds_read_b128 v[136:139], v218 offset:0
	v_mfma_f32_16x16x32_bf16 v[70:73], v[188:191], v[168:171], v[70:73]
	ds_read_b128 v[140:143], v218 offset:2048
	v_mul_f32_e32 v33, v33, v239
	v_mfma_f32_16x16x32_bf16 v[74:77], v[192:195], v[168:171], v[74:77]
	ds_read_b128 v[144:147], v218 offset:4096
	v_mfma_f32_16x16x32_bf16 v[78:81], v[196:199], v[168:171], v[78:81]
	ds_read_b128 v[148:151], v218 offset:6144
	v_cvt_pk_bf16_f32 v30, v30, v31
	v_mfma_f32_16x16x32_bf16 v[82:85], v[184:187], v[172:175], v[82:85]
	ds_read_b128 v[152:155], v230 offset:0
	v_cvt_pk_bf16_f32 v31, v32, v33
	v_mfma_f32_16x16x32_bf16 v[86:89], v[188:191], v[172:175], v[86:89]
	ds_read_b128 v[156:159], v230 offset:2048
	v_mfma_f32_16x16x32_bf16 v[90:93], v[192:195], v[172:175], v[90:93]
	ds_read_b128 v[160:163], v230 offset:4096
	global_store_dwordx2 v236, v[30:31], s[10:11] offset:96 sc1
	v_mfma_f32_16x16x32_bf16 v[94:97], v[196:199], v[172:175], v[94:97]
	ds_read_b128 v[164:167], v230 offset:6144
	s_add_u32 s10, s10, 0x8000
	s_addc_u32 s11, s11, 0
	s_add_u32 m0, s8, 0x18000
	v_mfma_f32_16x16x32_bf16 v[98:101], v[184:187], v[176:179], v[98:101]
	global_load_lds_dwordx4 v200, s[4:5]
	s_add_u32 m0, s8, 0x18400
	v_mfma_f32_16x16x32_bf16 v[102:105], v[188:191], v[176:179], v[102:105]
	global_load_lds_dwordx4 v201, s[4:5]
	v_mul_f32_e32 v1, s12, v34
	s_add_u32 m0, s8, 0x18800
	v_mfma_f32_16x16x32_bf16 v[106:109], v[192:195], v[176:179], v[106:109]
	global_load_lds_dwordx4 v202, s[4:5]
	s_add_u32 m0, s8, 0x18c00
	v_mfma_f32_16x16x32_bf16 v[110:113], v[196:199], v[176:179], v[110:113]
	global_load_lds_dwordx4 v203, s[4:5]
	v_mul_f32_e32 v130, s12, v35
	s_add_u32 m0, s9, 0x18000
	v_mfma_f32_16x16x32_bf16 v[114:117], v[184:187], v[180:183], v[114:117]
	global_load_lds_dwordx4 v204, s[6:7]
	v_mul_f32_e32 v238, s12, v36
	s_add_u32 m0, s9, 0x18400
	v_mfma_f32_16x16x32_bf16 v[118:121], v[188:191], v[180:183], v[118:121]
	global_load_lds_dwordx4 v205, s[6:7]
	v_mfma_f32_16x16x32_bf16 v[122:125], v[192:195], v[180:183], v[122:125]
	s_add_u32 s4, s4, 0x80
	s_addc_u32 s5, s5, 0
	v_mul_f32_e32 v239, s12, v37
	v_mfma_f32_16x16x32_bf16 v[126:129], v[196:199], v[180:183], v[126:129]
	s_add_u32 s6, s6, 0x80
	s_addc_u32 s7, s7, 0
	v_exp_f32_e32 v1, v1
	s_waitcnt lgkmcnt(0)
	v_mfma_f32_16x16x32_bf16 v[66:69], v[152:155], v[136:139], v[66:69]
	ds_read_b128 v[168:171], v225 offset:0
	v_mfma_f32_16x16x32_bf16 v[70:73], v[156:159], v[136:139], v[70:73]
	ds_read_b128 v[172:175], v225 offset:2048
	v_exp_f32_e32 v130, v130
	v_mfma_f32_16x16x32_bf16 v[74:77], v[160:163], v[136:139], v[74:77]
	ds_read_b128 v[176:179], v225 offset:4096
	v_exp_f32_e32 v238, v238
	v_mfma_f32_16x16x32_bf16 v[78:81], v[164:167], v[136:139], v[78:81]
	ds_read_b128 v[180:183], v225 offset:6144
	v_exp_f32_e32 v239, v239
	v_mfma_f32_16x16x32_bf16 v[82:85], v[152:155], v[140:143], v[82:85]
	ds_read_b128 v[184:187], v233 offset:0
	v_add_f32_e32 v1, 1.0, v1
	v_mfma_f32_16x16x32_bf16 v[86:89], v[156:159], v[140:143], v[86:89]
	ds_read_b128 v[188:191], v233 offset:2048
	v_add_f32_e32 v130, 1.0, v130
	v_mfma_f32_16x16x32_bf16 v[90:93], v[160:163], v[140:143], v[90:93]
	ds_read_b128 v[192:195], v233 offset:4096
	v_add_f32_e32 v238, 1.0, v238
	v_mfma_f32_16x16x32_bf16 v[94:97], v[164:167], v[140:143], v[94:97]
	ds_read_b128 v[196:199], v233 offset:6144
	v_add_f32_e32 v239, 1.0, v239
	v_mfma_f32_16x16x32_bf16 v[98:101], v[152:155], v[144:147], v[98:101]
	v_mfma_f32_16x16x32_bf16 v[102:105], v[156:159], v[144:147], v[102:105]
	v_rcp_f32_e32 v1, v1
	v_mfma_f32_16x16x32_bf16 v[106:109], v[160:163], v[144:147], v[106:109]
	v_rcp_f32_e32 v130, v130
	v_mfma_f32_16x16x32_bf16 v[110:113], v[164:167], v[144:147], v[110:113]
	v_rcp_f32_e32 v238, v238
	v_mfma_f32_16x16x32_bf16 v[114:117], v[152:155], v[148:151], v[114:117]
	v_rcp_f32_e32 v239, v239
	v_mfma_f32_16x16x32_bf16 v[118:121], v[156:159], v[148:151], v[118:121]
	v_mul_f32_e32 v34, v34, v1
	v_mfma_f32_16x16x32_bf16 v[122:125], v[160:163], v[148:151], v[122:125]
	v_mul_f32_e32 v35, v35, v130
	v_mfma_f32_16x16x32_bf16 v[126:129], v[164:167], v[148:151], v[126:129]
	v_mul_f32_e32 v36, v36, v238
	s_waitcnt vmcnt(7) lgkmcnt(0)
	s_barrier
	v_mfma_f32_16x16x32_bf16 v[66:69], v[184:187], v[168:171], v[66:69]
	ds_read_b128 v[136:139], v219 offset:0
	v_mfma_f32_16x16x32_bf16 v[70:73], v[188:191], v[168:171], v[70:73]
	ds_read_b128 v[140:143], v219 offset:2048
	v_mul_f32_e32 v37, v37, v239
	v_mfma_f32_16x16x32_bf16 v[74:77], v[192:195], v[168:171], v[74:77]
	ds_read_b128 v[144:147], v219 offset:4096
	v_mfma_f32_16x16x32_bf16 v[78:81], v[196:199], v[168:171], v[78:81]
	ds_read_b128 v[148:151], v219 offset:6144
	v_cvt_pk_bf16_f32 v34, v34, v35
	v_mfma_f32_16x16x32_bf16 v[82:85], v[184:187], v[172:175], v[82:85]
	ds_read_b128 v[152:155], v231 offset:0
	v_cvt_pk_bf16_f32 v35, v36, v37
	v_mfma_f32_16x16x32_bf16 v[86:89], v[188:191], v[172:175], v[86:89]
	ds_read_b128 v[156:159], v231 offset:2048
	v_mfma_f32_16x16x32_bf16 v[90:93], v[192:195], v[172:175], v[90:93]
	ds_read_b128 v[160:163], v231 offset:4096
	global_store_dwordx2 v236, v[34:35], s[10:11] offset:0 sc1
	v_mfma_f32_16x16x32_bf16 v[94:97], v[196:199], v[172:175], v[94:97]
	ds_read_b128 v[164:167], v231 offset:6144
	v_mul_f32_e32 v1, s12, v38
	s_mov_b32 m0, s8
	v_mfma_f32_16x16x32_bf16 v[98:101], v[184:187], v[176:179], v[98:101]
	global_load_lds_dwordx4 v200, s[4:5]
	s_add_u32 m0, s8, 0x400
	v_mfma_f32_16x16x32_bf16 v[102:105], v[188:191], v[176:179], v[102:105]
	global_load_lds_dwordx4 v201, s[4:5]
	v_mul_f32_e32 v130, s12, v39
	s_add_u32 m0, s8, 0x800
	v_mfma_f32_16x16x32_bf16 v[106:109], v[192:195], v[176:179], v[106:109]
	global_load_lds_dwordx4 v202, s[4:5]
	s_add_u32 m0, s8, 0xc00
	v_mfma_f32_16x16x32_bf16 v[110:113], v[196:199], v[176:179], v[110:113]
	global_load_lds_dwordx4 v203, s[4:5]
	v_mul_f32_e32 v238, s12, v40
	s_mov_b32 m0, s9
	v_mfma_f32_16x16x32_bf16 v[114:117], v[184:187], v[180:183], v[114:117]
	global_load_lds_dwordx4 v204, s[6:7]
	v_mul_f32_e32 v239, s12, v41
	s_add_u32 m0, s9, 0x400
	v_mfma_f32_16x16x32_bf16 v[118:121], v[188:191], v[180:183], v[118:121]
	global_load_lds_dwordx4 v205, s[6:7]
	v_mfma_f32_16x16x32_bf16 v[122:125], v[192:195], v[180:183], v[122:125]
	s_add_u32 s4, s4, 0x80
	s_addc_u32 s5, s5, 0
	v_exp_f32_e32 v1, v1
	v_mfma_f32_16x16x32_bf16 v[126:129], v[196:199], v[180:183], v[126:129]
	s_add_u32 s6, s6, 0x80
	s_addc_u32 s7, s7, 0
	v_exp_f32_e32 v130, v130
	s_waitcnt lgkmcnt(0)
	v_mfma_f32_16x16x32_bf16 v[66:69], v[152:155], v[136:139], v[66:69]
	ds_read_b128 v[168:171], v228 offset:0
	v_mfma_f32_16x16x32_bf16 v[70:73], v[156:159], v[136:139], v[70:73]
	ds_read_b128 v[172:175], v228 offset:2048
	v_exp_f32_e32 v238, v238
	v_mfma_f32_16x16x32_bf16 v[74:77], v[160:163], v[136:139], v[74:77]
	ds_read_b128 v[176:179], v228 offset:4096
	v_exp_f32_e32 v239, v239
	v_mfma_f32_16x16x32_bf16 v[78:81], v[164:167], v[136:139], v[78:81]
	ds_read_b128 v[180:183], v228 offset:6144
	v_add_f32_e32 v1, 1.0, v1
	v_mfma_f32_16x16x32_bf16 v[82:85], v[152:155], v[140:143], v[82:85]
	ds_read_b128 v[184:187], v234 offset:0
	v_add_f32_e32 v130, 1.0, v130
	v_mfma_f32_16x16x32_bf16 v[86:89], v[156:159], v[140:143], v[86:89]
	ds_read_b128 v[188:191], v234 offset:2048
	v_add_f32_e32 v238, 1.0, v238
	v_mfma_f32_16x16x32_bf16 v[90:93], v[160:163], v[140:143], v[90:93]
	ds_read_b128 v[192:195], v234 offset:4096
	v_add_f32_e32 v239, 1.0, v239
	v_mfma_f32_16x16x32_bf16 v[94:97], v[164:167], v[140:143], v[94:97]
	ds_read_b128 v[196:199], v234 offset:6144
	v_rcp_f32_e32 v1, v1
	v_mfma_f32_16x16x32_bf16 v[98:101], v[152:155], v[144:147], v[98:101]
	v_mfma_f32_16x16x32_bf16 v[102:105], v[156:159], v[144:147], v[102:105]
	v_rcp_f32_e32 v130, v130
	v_mfma_f32_16x16x32_bf16 v[106:109], v[160:163], v[144:147], v[106:109]
	v_rcp_f32_e32 v238, v238
	v_mfma_f32_16x16x32_bf16 v[110:113], v[164:167], v[144:147], v[110:113]
	v_rcp_f32_e32 v239, v239
	v_mfma_f32_16x16x32_bf16 v[114:117], v[152:155], v[148:151], v[114:117]
	v_mul_f32_e32 v38, v38, v1
	v_mfma_f32_16x16x32_bf16 v[118:121], v[156:159], v[148:151], v[118:121]
	v_mul_f32_e32 v39, v39, v130
	v_mfma_f32_16x16x32_bf16 v[122:125], v[160:163], v[148:151], v[122:125]
	v_mul_f32_e32 v40, v40, v238
	v_mfma_f32_16x16x32_bf16 v[126:129], v[164:167], v[148:151], v[126:129]
	v_mul_f32_e32 v41, v41, v239
	s_waitcnt vmcnt(7) lgkmcnt(0)
	s_barrier
	v_mfma_f32_16x16x32_bf16 v[66:69], v[184:187], v[168:171], v[66:69]
	ds_read_b128 v[136:139], v224 offset:0
	v_mfma_f32_16x16x32_bf16 v[70:73], v[188:191], v[168:171], v[70:73]
	ds_read_b128 v[140:143], v224 offset:2048
	v_cvt_pk_bf16_f32 v38, v38, v39
	v_mfma_f32_16x16x32_bf16 v[74:77], v[192:195], v[168:171], v[74:77]
	ds_read_b128 v[144:147], v224 offset:4096
	v_mfma_f32_16x16x32_bf16 v[78:81], v[196:199], v[168:171], v[78:81]
	ds_read_b128 v[148:151], v224 offset:6144
	v_cvt_pk_bf16_f32 v39, v40, v41
	v_mfma_f32_16x16x32_bf16 v[82:85], v[184:187], v[172:175], v[82:85]
	ds_read_b128 v[152:155], v232 offset:0
	global_store_dwordx2 v236, v[38:39], s[10:11] offset:32 sc1
	v_mfma_f32_16x16x32_bf16 v[86:89], v[188:191], v[172:175], v[86:89]
	ds_read_b128 v[156:159], v232 offset:2048
	v_mfma_f32_16x16x32_bf16 v[90:93], v[192:195], v[172:175], v[90:93]
	ds_read_b128 v[160:163], v232 offset:4096
	v_mul_f32_e32 v1, s12, v42
	v_mfma_f32_16x16x32_bf16 v[94:97], v[196:199], v[172:175], v[94:97]
	ds_read_b128 v[164:167], v232 offset:6144
	v_mul_f32_e32 v130, s12, v43
	s_add_u32 m0, s8, 0xc000
	v_mfma_f32_16x16x32_bf16 v[98:101], v[184:187], v[176:179], v[98:101]
	global_load_lds_dwordx4 v200, s[4:5]
	s_add_u32 m0, s8, 0xc400
	v_mfma_f32_16x16x32_bf16 v[102:105], v[188:191], v[176:179], v[102:105]
	global_load_lds_dwordx4 v201, s[4:5]
	v_mul_f32_e32 v238, s12, v44
	s_add_u32 m0, s8, 0xc800
	v_mfma_f32_16x16x32_bf16 v[106:109], v[192:195], v[176:179], v[106:109]
	global_load_lds_dwordx4 v202, s[4:5]
	s_add_u32 m0, s8, 0xcc00
	v_mfma_f32_16x16x32_bf16 v[110:113], v[196:199], v[176:179], v[110:113]
	global_load_lds_dwordx4 v203, s[4:5]
	v_mul_f32_e32 v239, s12, v45
	s_add_u32 m0, s9, 0xc000
	v_mfma_f32_16x16x32_bf16 v[114:117], v[184:187], v[180:183], v[114:117]
	global_load_lds_dwordx4 v204, s[6:7]
	v_exp_f32_e32 v1, v1
	s_add_u32 m0, s9, 0xc400
	v_mfma_f32_16x16x32_bf16 v[118:121], v[188:191], v[180:183], v[118:121]
	global_load_lds_dwordx4 v205, s[6:7]
	v_mfma_f32_16x16x32_bf16 v[122:125], v[192:195], v[180:183], v[122:125]
	s_add_u32 s4, s4, 0x80
	s_addc_u32 s5, s5, 0
	v_exp_f32_e32 v130, v130
	v_mfma_f32_16x16x32_bf16 v[126:129], v[196:199], v[180:183], v[126:129]
	s_add_u32 s6, s6, 0x80
	s_addc_u32 s7, s7, 0
	v_exp_f32_e32 v238, v238
	s_waitcnt lgkmcnt(0)
	v_mfma_f32_16x16x32_bf16 v[66:69], v[152:155], v[136:139], v[66:69]
	ds_read_b128 v[168:171], v229 offset:0
	v_mfma_f32_16x16x32_bf16 v[70:73], v[156:159], v[136:139], v[70:73]
	ds_read_b128 v[172:175], v229 offset:2048
	v_exp_f32_e32 v239, v239
	v_mfma_f32_16x16x32_bf16 v[74:77], v[160:163], v[136:139], v[74:77]
	ds_read_b128 v[176:179], v229 offset:4096
	v_add_f32_e32 v1, 1.0, v1
	v_mfma_f32_16x16x32_bf16 v[78:81], v[164:167], v[136:139], v[78:81]
	ds_read_b128 v[180:183], v229 offset:6144
	v_add_f32_e32 v130, 1.0, v130
	v_mfma_f32_16x16x32_bf16 v[82:85], v[152:155], v[140:143], v[82:85]
	ds_read_b128 v[184:187], v235 offset:0
	v_add_f32_e32 v238, 1.0, v238
	v_mfma_f32_16x16x32_bf16 v[86:89], v[156:159], v[140:143], v[86:89]
	ds_read_b128 v[188:191], v235 offset:2048
	v_add_f32_e32 v239, 1.0, v239
	v_mfma_f32_16x16x32_bf16 v[90:93], v[160:163], v[140:143], v[90:93]
	ds_read_b128 v[192:195], v235 offset:4096
	v_rcp_f32_e32 v1, v1
	v_mfma_f32_16x16x32_bf16 v[94:97], v[164:167], v[140:143], v[94:97]
	ds_read_b128 v[196:199], v235 offset:6144
	v_rcp_f32_e32 v130, v130
	v_mfma_f32_16x16x32_bf16 v[98:101], v[152:155], v[144:147], v[98:101]
	v_mfma_f32_16x16x32_bf16 v[102:105], v[156:159], v[144:147], v[102:105]
	v_rcp_f32_e32 v238, v238
	v_mfma_f32_16x16x32_bf16 v[106:109], v[160:163], v[144:147], v[106:109]
	v_rcp_f32_e32 v239, v239
	v_mfma_f32_16x16x32_bf16 v[110:113], v[164:167], v[144:147], v[110:113]
	v_mul_f32_e32 v42, v42, v1
	v_mfma_f32_16x16x32_bf16 v[114:117], v[152:155], v[148:151], v[114:117]
	v_mul_f32_e32 v43, v43, v130
	v_mfma_f32_16x16x32_bf16 v[118:121], v[156:159], v[148:151], v[118:121]
	v_mul_f32_e32 v44, v44, v238
	v_mfma_f32_16x16x32_bf16 v[122:125], v[160:163], v[148:151], v[122:125]
	v_mul_f32_e32 v45, v45, v239
	v_mfma_f32_16x16x32_bf16 v[126:129], v[164:167], v[148:151], v[126:129]
	v_cvt_pk_bf16_f32 v42, v42, v43
	s_waitcnt vmcnt(7) lgkmcnt(0)
	s_barrier
	v_mfma_f32_16x16x32_bf16 v[66:69], v[184:187], v[168:171], v[66:69]
	ds_read_b128 v[136:139], v218 offset:0
	v_mfma_f32_16x16x32_bf16 v[70:73], v[188:191], v[168:171], v[70:73]
	ds_read_b128 v[140:143], v218 offset:2048
	v_cvt_pk_bf16_f32 v43, v44, v45
	v_mfma_f32_16x16x32_bf16 v[74:77], v[192:195], v[168:171], v[74:77]
	ds_read_b128 v[144:147], v218 offset:4096
	v_mfma_f32_16x16x32_bf16 v[78:81], v[196:199], v[168:171], v[78:81]
	ds_read_b128 v[148:151], v218 offset:6144
	global_store_dwordx2 v236, v[42:43], s[10:11] offset:64 sc1
	v_mfma_f32_16x16x32_bf16 v[82:85], v[184:187], v[172:175], v[82:85]
	ds_read_b128 v[152:155], v230 offset:0
	v_mul_f32_e32 v1, s12, v46
	v_mfma_f32_16x16x32_bf16 v[86:89], v[188:191], v[172:175], v[86:89]
	ds_read_b128 v[156:159], v230 offset:2048
	v_mfma_f32_16x16x32_bf16 v[90:93], v[192:195], v[172:175], v[90:93]
	ds_read_b128 v[160:163], v230 offset:4096
	v_mul_f32_e32 v130, s12, v47
	v_mfma_f32_16x16x32_bf16 v[94:97], v[196:199], v[172:175], v[94:97]
	ds_read_b128 v[164:167], v230 offset:6144
	v_mul_f32_e32 v238, s12, v48
	s_add_u32 m0, s8, 0x18000
	v_mfma_f32_16x16x32_bf16 v[98:101], v[184:187], v[176:179], v[98:101]
	global_load_lds_dwordx4 v200, s[4:5]
	s_add_u32 m0, s8, 0x18400
	v_mfma_f32_16x16x32_bf16 v[102:105], v[188:191], v[176:179], v[102:105]
	global_load_lds_dwordx4 v201, s[4:5]
	v_mul_f32_e32 v239, s12, v49
	s_add_u32 m0, s8, 0x18800
	v_mfma_f32_16x16x32_bf16 v[106:109], v[192:195], v[176:179], v[106:109]
	global_load_lds_dwordx4 v202, s[4:5]
	s_add_u32 m0, s8, 0x18c00
	v_mfma_f32_16x16x32_bf16 v[110:113], v[196:199], v[176:179], v[110:113]
	global_load_lds_dwordx4 v203, s[4:5]
	v_exp_f32_e32 v1, v1
	s_add_u32 m0, s9, 0x18000
	v_mfma_f32_16x16x32_bf16 v[114:117], v[184:187], v[180:183], v[114:117]
	global_load_lds_dwordx4 v204, s[6:7]
	v_exp_f32_e32 v130, v130
	s_add_u32 m0, s9, 0x18400
	v_mfma_f32_16x16x32_bf16 v[118:121], v[188:191], v[180:183], v[118:121]
	global_load_lds_dwordx4 v205, s[6:7]
	v_mfma_f32_16x16x32_bf16 v[122:125], v[192:195], v[180:183], v[122:125]
	s_add_u32 s4, s4, 0x80
	s_addc_u32 s5, s5, 0
	v_exp_f32_e32 v238, v238
	v_mfma_f32_16x16x32_bf16 v[126:129], v[196:199], v[180:183], v[126:129]
	s_add_u32 s6, s6, 0x80
	s_addc_u32 s7, s7, 0
	v_exp_f32_e32 v239, v239
	s_waitcnt lgkmcnt(0)
	v_mfma_f32_16x16x32_bf16 v[66:69], v[152:155], v[136:139], v[66:69]
	ds_read_b128 v[168:171], v225 offset:0
	v_mfma_f32_16x16x32_bf16 v[70:73], v[156:159], v[136:139], v[70:73]
	ds_read_b128 v[172:175], v225 offset:2048
	v_add_f32_e32 v1, 1.0, v1
	v_mfma_f32_16x16x32_bf16 v[74:77], v[160:163], v[136:139], v[74:77]
	ds_read_b128 v[176:179], v225 offset:4096
	v_add_f32_e32 v130, 1.0, v130
	v_mfma_f32_16x16x32_bf16 v[78:81], v[164:167], v[136:139], v[78:81]
	ds_read_b128 v[180:183], v225 offset:6144
	v_add_f32_e32 v238, 1.0, v238
	v_mfma_f32_16x16x32_bf16 v[82:85], v[152:155], v[140:143], v[82:85]
	ds_read_b128 v[184:187], v233 offset:0
	v_add_f32_e32 v239, 1.0, v239
	v_mfma_f32_16x16x32_bf16 v[86:89], v[156:159], v[140:143], v[86:89]
	ds_read_b128 v[188:191], v233 offset:2048
	v_rcp_f32_e32 v1, v1
	v_mfma_f32_16x16x32_bf16 v[90:93], v[160:163], v[140:143], v[90:93]
	ds_read_b128 v[192:195], v233 offset:4096
	v_rcp_f32_e32 v130, v130
	v_mfma_f32_16x16x32_bf16 v[94:97], v[164:167], v[140:143], v[94:97]
	ds_read_b128 v[196:199], v233 offset:6144
	v_rcp_f32_e32 v238, v238
	v_mfma_f32_16x16x32_bf16 v[98:101], v[152:155], v[144:147], v[98:101]
	v_mfma_f32_16x16x32_bf16 v[102:105], v[156:159], v[144:147], v[102:105]
	v_rcp_f32_e32 v239, v239
	v_mfma_f32_16x16x32_bf16 v[106:109], v[160:163], v[144:147], v[106:109]
	v_mul_f32_e32 v46, v46, v1
	v_mfma_f32_16x16x32_bf16 v[110:113], v[164:167], v[144:147], v[110:113]
	v_mul_f32_e32 v47, v47, v130
	v_mfma_f32_16x16x32_bf16 v[114:117], v[152:155], v[148:151], v[114:117]
	v_mul_f32_e32 v48, v48, v238
	v_mfma_f32_16x16x32_bf16 v[118:121], v[156:159], v[148:151], v[118:121]
	v_mul_f32_e32 v49, v49, v239
	v_mfma_f32_16x16x32_bf16 v[122:125], v[160:163], v[148:151], v[122:125]
	v_cvt_pk_bf16_f32 v46, v46, v47
	v_mfma_f32_16x16x32_bf16 v[126:129], v[164:167], v[148:151], v[126:129]
	v_cvt_pk_bf16_f32 v47, v48, v49
	s_waitcnt vmcnt(7) lgkmcnt(0)
	s_barrier
	v_mfma_f32_16x16x32_bf16 v[66:69], v[184:187], v[168:171], v[66:69]
	ds_read_b128 v[136:139], v219 offset:0
	v_mfma_f32_16x16x32_bf16 v[70:73], v[188:191], v[168:171], v[70:73]
	ds_read_b128 v[140:143], v219 offset:2048
	global_store_dwordx2 v236, v[46:47], s[10:11] offset:96 sc1
	v_mfma_f32_16x16x32_bf16 v[74:77], v[192:195], v[168:171], v[74:77]
	ds_read_b128 v[144:147], v219 offset:4096
	v_mfma_f32_16x16x32_bf16 v[78:81], v[196:199], v[168:171], v[78:81]
	ds_read_b128 v[148:151], v219 offset:6144
	s_add_u32 s10, s10, 0x8000
	s_addc_u32 s11, s11, 0
	v_mfma_f32_16x16x32_bf16 v[82:85], v[184:187], v[172:175], v[82:85]
	ds_read_b128 v[152:155], v231 offset:0
	v_mul_f32_e32 v1, s12, v50
	v_mfma_f32_16x16x32_bf16 v[86:89], v[188:191], v[172:175], v[86:89]
	ds_read_b128 v[156:159], v231 offset:2048
	v_mfma_f32_16x16x32_bf16 v[90:93], v[192:195], v[172:175], v[90:93]
	ds_read_b128 v[160:163], v231 offset:4096
	v_mul_f32_e32 v130, s12, v51
	v_mfma_f32_16x16x32_bf16 v[94:97], v[196:199], v[172:175], v[94:97]
	ds_read_b128 v[164:167], v231 offset:6144
	v_mul_f32_e32 v238, s12, v52
	s_mov_b32 m0, s8
	v_mfma_f32_16x16x32_bf16 v[98:101], v[184:187], v[176:179], v[98:101]
	global_load_lds_dwordx4 v200, s[4:5]
	s_add_u32 m0, s8, 0x400
	v_mfma_f32_16x16x32_bf16 v[102:105], v[188:191], v[176:179], v[102:105]
	global_load_lds_dwordx4 v201, s[4:5]
	v_mul_f32_e32 v239, s12, v53
	s_add_u32 m0, s8, 0x800
	v_mfma_f32_16x16x32_bf16 v[106:109], v[192:195], v[176:179], v[106:109]
	global_load_lds_dwordx4 v202, s[4:5]
	s_add_u32 m0, s8, 0xc00
	v_mfma_f32_16x16x32_bf16 v[110:113], v[196:199], v[176:179], v[110:113]
	global_load_lds_dwordx4 v203, s[4:5]
	v_exp_f32_e32 v1, v1
	s_mov_b32 m0, s9
	v_mfma_f32_16x16x32_bf16 v[114:117], v[184:187], v[180:183], v[114:117]
	global_load_lds_dwordx4 v204, s[6:7]
	v_exp_f32_e32 v130, v130
	s_add_u32 m0, s9, 0x400
	v_mfma_f32_16x16x32_bf16 v[118:121], v[188:191], v[180:183], v[118:121]
	global_load_lds_dwordx4 v205, s[6:7]
	v_mfma_f32_16x16x32_bf16 v[122:125], v[192:195], v[180:183], v[122:125]
	s_add_u32 s4, s4, 0x80
	s_addc_u32 s5, s5, 0
	v_exp_f32_e32 v238, v238
	v_mfma_f32_16x16x32_bf16 v[126:129], v[196:199], v[180:183], v[126:129]
	s_add_u32 s6, s6, 0x80
	s_addc_u32 s7, s7, 0
	v_exp_f32_e32 v239, v239
	s_waitcnt lgkmcnt(0)
	v_mfma_f32_16x16x32_bf16 v[66:69], v[152:155], v[136:139], v[66:69]
	ds_read_b128 v[168:171], v228 offset:0
	v_mfma_f32_16x16x32_bf16 v[70:73], v[156:159], v[136:139], v[70:73]
	ds_read_b128 v[172:175], v228 offset:2048
	v_add_f32_e32 v1, 1.0, v1
	v_mfma_f32_16x16x32_bf16 v[74:77], v[160:163], v[136:139], v[74:77]
	ds_read_b128 v[176:179], v228 offset:4096
	v_add_f32_e32 v130, 1.0, v130
	v_mfma_f32_16x16x32_bf16 v[78:81], v[164:167], v[136:139], v[78:81]
	ds_read_b128 v[180:183], v228 offset:6144
	v_add_f32_e32 v238, 1.0, v238
	v_mfma_f32_16x16x32_bf16 v[82:85], v[152:155], v[140:143], v[82:85]
	ds_read_b128 v[184:187], v234 offset:0
	v_add_f32_e32 v239, 1.0, v239
	v_mfma_f32_16x16x32_bf16 v[86:89], v[156:159], v[140:143], v[86:89]
	ds_read_b128 v[188:191], v234 offset:2048
	v_rcp_f32_e32 v1, v1
	v_mfma_f32_16x16x32_bf16 v[90:93], v[160:163], v[140:143], v[90:93]
	ds_read_b128 v[192:195], v234 offset:4096
	v_rcp_f32_e32 v130, v130
	v_mfma_f32_16x16x32_bf16 v[94:97], v[164:167], v[140:143], v[94:97]
	ds_read_b128 v[196:199], v234 offset:6144
	v_rcp_f32_e32 v238, v238
	v_mfma_f32_16x16x32_bf16 v[98:101], v[152:155], v[144:147], v[98:101]
	v_mfma_f32_16x16x32_bf16 v[102:105], v[156:159], v[144:147], v[102:105]
	v_rcp_f32_e32 v239, v239
	v_mfma_f32_16x16x32_bf16 v[106:109], v[160:163], v[144:147], v[106:109]
	v_mul_f32_e32 v50, v50, v1
	v_mfma_f32_16x16x32_bf16 v[110:113], v[164:167], v[144:147], v[110:113]
	v_mul_f32_e32 v51, v51, v130
	v_mfma_f32_16x16x32_bf16 v[114:117], v[152:155], v[148:151], v[114:117]
	v_mul_f32_e32 v52, v52, v238
	v_mfma_f32_16x16x32_bf16 v[118:121], v[156:159], v[148:151], v[118:121]
	v_mul_f32_e32 v53, v53, v239
	v_mfma_f32_16x16x32_bf16 v[122:125], v[160:163], v[148:151], v[122:125]
	v_cvt_pk_bf16_f32 v50, v50, v51
	v_mfma_f32_16x16x32_bf16 v[126:129], v[164:167], v[148:151], v[126:129]
	v_cvt_pk_bf16_f32 v51, v52, v53
	s_waitcnt vmcnt(7) lgkmcnt(0)
	s_barrier
	v_mfma_f32_16x16x32_bf16 v[66:69], v[184:187], v[168:171], v[66:69]
	ds_read_b128 v[136:139], v224 offset:0
	v_mfma_f32_16x16x32_bf16 v[70:73], v[188:191], v[168:171], v[70:73]
	ds_read_b128 v[140:143], v224 offset:2048
	global_store_dwordx2 v236, v[50:51], s[10:11] offset:0 sc1
	v_mfma_f32_16x16x32_bf16 v[74:77], v[192:195], v[168:171], v[74:77]
	ds_read_b128 v[144:147], v224 offset:4096
	v_mfma_f32_16x16x32_bf16 v[78:81], v[196:199], v[168:171], v[78:81]
	ds_read_b128 v[148:151], v224 offset:6144
	v_mul_f32_e32 v1, s12, v54
	v_mfma_f32_16x16x32_bf16 v[82:85], v[184:187], v[172:175], v[82:85]
	ds_read_b128 v[152:155], v232 offset:0
	v_mul_f32_e32 v130, s12, v55
	v_mfma_f32_16x16x32_bf16 v[86:89], v[188:191], v[172:175], v[86:89]
	ds_read_b128 v[156:159], v232 offset:2048
	v_mfma_f32_16x16x32_bf16 v[90:93], v[192:195], v[172:175], v[90:93]
	ds_read_b128 v[160:163], v232 offset:4096
	v_mul_f32_e32 v238, s12, v56
	v_mfma_f32_16x16x32_bf16 v[94:97], v[196:199], v[172:175], v[94:97]
	ds_read_b128 v[164:167], v232 offset:6144
	v_mul_f32_e32 v239, s12, v57
	s_add_u32 m0, s8, 0xc000
	v_mfma_f32_16x16x32_bf16 v[98:101], v[184:187], v[176:179], v[98:101]
	global_load_lds_dwordx4 v200, s[4:5]
	s_add_u32 m0, s8, 0xc400
	v_mfma_f32_16x16x32_bf16 v[102:105], v[188:191], v[176:179], v[102:105]
	global_load_lds_dwordx4 v201, s[4:5]
	v_exp_f32_e32 v1, v1
	s_add_u32 m0, s8, 0xc800
	v_mfma_f32_16x16x32_bf16 v[106:109], v[192:195], v[176:179], v[106:109]
	global_load_lds_dwordx4 v202, s[4:5]
	s_add_u32 m0, s8, 0xcc00
	v_mfma_f32_16x16x32_bf16 v[110:113], v[196:199], v[176:179], v[110:113]
	global_load_lds_dwordx4 v203, s[4:5]
	v_exp_f32_e32 v130, v130
	s_add_u32 m0, s9, 0xc000
	v_mfma_f32_16x16x32_bf16 v[114:117], v[184:187], v[180:183], v[114:117]
	global_load_lds_dwordx4 v204, s[6:7]
	v_exp_f32_e32 v238, v238
	s_add_u32 m0, s9, 0xc400
	v_mfma_f32_16x16x32_bf16 v[118:121], v[188:191], v[180:183], v[118:121]
	global_load_lds_dwordx4 v205, s[6:7]
	v_mfma_f32_16x16x32_bf16 v[122:125], v[192:195], v[180:183], v[122:125]
	s_sub_u32 s4, s4, 0x780
	s_subb_u32 s5, s5, 0
	v_exp_f32_e32 v239, v239
	v_mfma_f32_16x16x32_bf16 v[126:129], v[196:199], v[180:183], v[126:129]
	s_add_u32 s6, s6, 0x3f880
	s_addc_u32 s7, s7, 0
	v_add_f32_e32 v1, 1.0, v1
	s_waitcnt lgkmcnt(0)
	v_mfma_f32_16x16x32_bf16 v[66:69], v[152:155], v[136:139], v[66:69]
	ds_read_b128 v[168:171], v229 offset:0
	v_mfma_f32_16x16x32_bf16 v[70:73], v[156:159], v[136:139], v[70:73]
	ds_read_b128 v[172:175], v229 offset:2048
	v_add_f32_e32 v130, 1.0, v130
	v_mfma_f32_16x16x32_bf16 v[74:77], v[160:163], v[136:139], v[74:77]
	ds_read_b128 v[176:179], v229 offset:4096
	v_add_f32_e32 v238, 1.0, v238
	v_mfma_f32_16x16x32_bf16 v[78:81], v[164:167], v[136:139], v[78:81]
	ds_read_b128 v[180:183], v229 offset:6144
	v_add_f32_e32 v239, 1.0, v239
	v_mfma_f32_16x16x32_bf16 v[82:85], v[152:155], v[140:143], v[82:85]
	ds_read_b128 v[184:187], v235 offset:0
	v_rcp_f32_e32 v1, v1
	v_mfma_f32_16x16x32_bf16 v[86:89], v[156:159], v[140:143], v[86:89]
	ds_read_b128 v[188:191], v235 offset:2048
	v_rcp_f32_e32 v130, v130
	v_mfma_f32_16x16x32_bf16 v[90:93], v[160:163], v[140:143], v[90:93]
	ds_read_b128 v[192:195], v235 offset:4096
	v_rcp_f32_e32 v238, v238
	v_mfma_f32_16x16x32_bf16 v[94:97], v[164:167], v[140:143], v[94:97]
	ds_read_b128 v[196:199], v235 offset:6144
	v_rcp_f32_e32 v239, v239
	v_mfma_f32_16x16x32_bf16 v[98:101], v[152:155], v[144:147], v[98:101]
	v_mfma_f32_16x16x32_bf16 v[102:105], v[156:159], v[144:147], v[102:105]
	v_mul_f32_e32 v54, v54, v1
	v_mfma_f32_16x16x32_bf16 v[106:109], v[160:163], v[144:147], v[106:109]
	v_mul_f32_e32 v55, v55, v130
	v_mfma_f32_16x16x32_bf16 v[110:113], v[164:167], v[144:147], v[110:113]
	v_mul_f32_e32 v56, v56, v238
	v_mfma_f32_16x16x32_bf16 v[114:117], v[152:155], v[148:151], v[114:117]
	v_mul_f32_e32 v57, v57, v239
	v_mfma_f32_16x16x32_bf16 v[118:121], v[156:159], v[148:151], v[118:121]
	v_cvt_pk_bf16_f32 v54, v54, v55
	v_mfma_f32_16x16x32_bf16 v[122:125], v[160:163], v[148:151], v[122:125]
	v_cvt_pk_bf16_f32 v55, v56, v57
	v_mfma_f32_16x16x32_bf16 v[126:129], v[164:167], v[148:151], v[126:129]
	global_store_dwordx2 v236, v[54:55], s[10:11] offset:32 sc1
	s_waitcnt vmcnt(8) lgkmcnt(0)
	s_barrier
	v_mfma_f32_16x16x32_bf16 v[66:69], v[184:187], v[168:171], v[66:69]
	ds_read_b128 v[136:139], v218 offset:0
	v_mfma_f32_16x16x32_bf16 v[70:73], v[188:191], v[168:171], v[70:73]
	ds_read_b128 v[140:143], v218 offset:2048
	v_mul_f32_e32 v1, s12, v58
	v_mfma_f32_16x16x32_bf16 v[74:77], v[192:195], v[168:171], v[74:77]
	ds_read_b128 v[144:147], v218 offset:4096
	v_mfma_f32_16x16x32_bf16 v[78:81], v[196:199], v[168:171], v[78:81]
	ds_read_b128 v[148:151], v218 offset:6144
	v_mul_f32_e32 v130, s12, v59
	v_mfma_f32_16x16x32_bf16 v[82:85], v[184:187], v[172:175], v[82:85]
	ds_read_b128 v[152:155], v230 offset:0
	v_mul_f32_e32 v238, s12, v60
	v_mfma_f32_16x16x32_bf16 v[86:89], v[188:191], v[172:175], v[86:89]
	ds_read_b128 v[156:159], v230 offset:2048
	v_mfma_f32_16x16x32_bf16 v[90:93], v[192:195], v[172:175], v[90:93]
	ds_read_b128 v[160:163], v230 offset:4096
	v_mul_f32_e32 v239, s12, v61
	v_mfma_f32_16x16x32_bf16 v[94:97], v[196:199], v[172:175], v[94:97]
	ds_read_b128 v[164:167], v230 offset:6144
	v_exp_f32_e32 v1, v1
	v_mfma_f32_16x16x32_bf16 v[98:101], v[184:187], v[176:179], v[98:101]
	v_mfma_f32_16x16x32_bf16 v[102:105], v[188:191], v[176:179], v[102:105]
	v_exp_f32_e32 v130, v130
	v_mfma_f32_16x16x32_bf16 v[106:109], v[192:195], v[176:179], v[106:109]
	v_mfma_f32_16x16x32_bf16 v[110:113], v[196:199], v[176:179], v[110:113]
	v_exp_f32_e32 v238, v238
	v_mfma_f32_16x16x32_bf16 v[114:117], v[184:187], v[180:183], v[114:117]
	v_exp_f32_e32 v239, v239
	v_mfma_f32_16x16x32_bf16 v[118:121], v[188:191], v[180:183], v[118:121]
	v_mfma_f32_16x16x32_bf16 v[122:125], v[192:195], v[180:183], v[122:125]
	v_add_f32_e32 v1, 1.0, v1
	v_mfma_f32_16x16x32_bf16 v[126:129], v[196:199], v[180:183], v[126:129]
	v_add_f32_e32 v130, 1.0, v130
	s_waitcnt lgkmcnt(0)
	v_mfma_f32_16x16x32_bf16 v[66:69], v[152:155], v[136:139], v[66:69]
	ds_read_b128 v[168:171], v225 offset:0
	v_mfma_f32_16x16x32_bf16 v[70:73], v[156:159], v[136:139], v[70:73]
	ds_read_b128 v[172:175], v225 offset:2048
	v_add_f32_e32 v238, 1.0, v238
	v_mfma_f32_16x16x32_bf16 v[74:77], v[160:163], v[136:139], v[74:77]
	ds_read_b128 v[176:179], v225 offset:4096
	v_add_f32_e32 v239, 1.0, v239
	v_mfma_f32_16x16x32_bf16 v[78:81], v[164:167], v[136:139], v[78:81]
	ds_read_b128 v[180:183], v225 offset:6144
	v_rcp_f32_e32 v1, v1
	v_mfma_f32_16x16x32_bf16 v[82:85], v[152:155], v[140:143], v[82:85]
	ds_read_b128 v[184:187], v233 offset:0
	v_rcp_f32_e32 v130, v130
	v_mfma_f32_16x16x32_bf16 v[86:89], v[156:159], v[140:143], v[86:89]
	ds_read_b128 v[188:191], v233 offset:2048
	v_rcp_f32_e32 v238, v238
	v_mfma_f32_16x16x32_bf16 v[90:93], v[160:163], v[140:143], v[90:93]
	ds_read_b128 v[192:195], v233 offset:4096
	v_rcp_f32_e32 v239, v239
	v_mfma_f32_16x16x32_bf16 v[94:97], v[164:167], v[140:143], v[94:97]
	ds_read_b128 v[196:199], v233 offset:6144
	v_mul_f32_e32 v58, v58, v1
	v_mfma_f32_16x16x32_bf16 v[98:101], v[152:155], v[144:147], v[98:101]
	v_mfma_f32_16x16x32_bf16 v[102:105], v[156:159], v[144:147], v[102:105]
	v_mul_f32_e32 v59, v59, v130
	v_mfma_f32_16x16x32_bf16 v[106:109], v[160:163], v[144:147], v[106:109]
	v_mul_f32_e32 v60, v60, v238
	v_mfma_f32_16x16x32_bf16 v[110:113], v[164:167], v[144:147], v[110:113]
	v_mul_f32_e32 v61, v61, v239
	v_mfma_f32_16x16x32_bf16 v[114:117], v[152:155], v[148:151], v[114:117]
	v_cvt_pk_bf16_f32 v58, v58, v59
	v_mfma_f32_16x16x32_bf16 v[118:121], v[156:159], v[148:151], v[118:121]
	v_cvt_pk_bf16_f32 v59, v60, v61
	v_mfma_f32_16x16x32_bf16 v[122:125], v[160:163], v[148:151], v[122:125]
	global_store_dwordx2 v236, v[58:59], s[10:11] offset:64 sc1
	v_mfma_f32_16x16x32_bf16 v[126:129], v[164:167], v[148:151], v[126:129]
	v_mul_f32_e32 v1, s12, v62
	s_waitcnt vmcnt(2) lgkmcnt(0)
	s_barrier
	v_mfma_f32_16x16x32_bf16 v[66:69], v[184:187], v[168:171], v[66:69]
	ds_read_b128 v[136:139], v219 offset:0
	v_mfma_f32_16x16x32_bf16 v[70:73], v[188:191], v[168:171], v[70:73]
	ds_read_b128 v[140:143], v219 offset:2048
	v_mul_f32_e32 v130, s12, v63
	v_mfma_f32_16x16x32_bf16 v[74:77], v[192:195], v[168:171], v[74:77]
	ds_read_b128 v[144:147], v219 offset:4096
	v_mfma_f32_16x16x32_bf16 v[78:81], v[196:199], v[168:171], v[78:81]
	ds_read_b128 v[148:151], v219 offset:6144
	v_mul_f32_e32 v238, s12, v64
	v_mfma_f32_16x16x32_bf16 v[82:85], v[184:187], v[172:175], v[82:85]
	ds_read_b128 v[152:155], v231 offset:0
	v_mul_f32_e32 v239, s12, v65
	v_mfma_f32_16x16x32_bf16 v[86:89], v[188:191], v[172:175], v[86:89]
	ds_read_b128 v[156:159], v231 offset:2048
	v_mfma_f32_16x16x32_bf16 v[90:93], v[192:195], v[172:175], v[90:93]
	ds_read_b128 v[160:163], v231 offset:4096
	v_exp_f32_e32 v1, v1
	v_mfma_f32_16x16x32_bf16 v[94:97], v[196:199], v[172:175], v[94:97]
	ds_read_b128 v[164:167], v231 offset:6144
	v_exp_f32_e32 v130, v130
	v_mfma_f32_16x16x32_bf16 v[98:101], v[184:187], v[176:179], v[98:101]
	v_mfma_f32_16x16x32_bf16 v[102:105], v[188:191], v[176:179], v[102:105]
	v_exp_f32_e32 v238, v238
	v_mfma_f32_16x16x32_bf16 v[106:109], v[192:195], v[176:179], v[106:109]
	v_mfma_f32_16x16x32_bf16 v[110:113], v[196:199], v[176:179], v[110:113]
	v_exp_f32_e32 v239, v239
	v_mfma_f32_16x16x32_bf16 v[114:117], v[184:187], v[180:183], v[114:117]
	v_add_f32_e32 v1, 1.0, v1
	v_mfma_f32_16x16x32_bf16 v[118:121], v[188:191], v[180:183], v[118:121]
	v_mfma_f32_16x16x32_bf16 v[122:125], v[192:195], v[180:183], v[122:125]
	v_add_f32_e32 v130, 1.0, v130
	v_mfma_f32_16x16x32_bf16 v[126:129], v[196:199], v[180:183], v[126:129]
	v_add_f32_e32 v238, 1.0, v238
	s_waitcnt lgkmcnt(0)
	v_mfma_f32_16x16x32_bf16 v[66:69], v[152:155], v[136:139], v[66:69]
	ds_read_b128 v[168:171], v228 offset:0
	v_mfma_f32_16x16x32_bf16 v[70:73], v[156:159], v[136:139], v[70:73]
	ds_read_b128 v[172:175], v228 offset:2048
	v_add_f32_e32 v239, 1.0, v239
	v_mfma_f32_16x16x32_bf16 v[74:77], v[160:163], v[136:139], v[74:77]
	ds_read_b128 v[176:179], v228 offset:4096
	v_rcp_f32_e32 v1, v1
	v_mfma_f32_16x16x32_bf16 v[78:81], v[164:167], v[136:139], v[78:81]
	ds_read_b128 v[180:183], v228 offset:6144
	v_rcp_f32_e32 v130, v130
	v_mfma_f32_16x16x32_bf16 v[82:85], v[152:155], v[140:143], v[82:85]
	ds_read_b128 v[184:187], v234 offset:0
	v_mfma_f32_16x16x32_bf16 v[86:89], v[156:159], v[140:143], v[86:89]
	ds_read_b128 v[188:191], v234 offset:2048
	v_rcp_f32_e32 v238, v238
	v_mfma_f32_16x16x32_bf16 v[90:93], v[160:163], v[140:143], v[90:93]
	ds_read_b128 v[192:195], v234 offset:4096
	v_rcp_f32_e32 v239, v239
	v_mfma_f32_16x16x32_bf16 v[94:97], v[164:167], v[140:143], v[94:97]
	ds_read_b128 v[196:199], v234 offset:6144
	v_mul_f32_e32 v62, v62, v1
	v_mfma_f32_16x16x32_bf16 v[98:101], v[152:155], v[144:147], v[98:101]
	v_mfma_f32_16x16x32_bf16 v[102:105], v[156:159], v[144:147], v[102:105]
	v_mul_f32_e32 v63, v63, v130
	v_mfma_f32_16x16x32_bf16 v[106:109], v[160:163], v[144:147], v[106:109]
	v_mul_f32_e32 v64, v64, v238
	v_mfma_f32_16x16x32_bf16 v[110:113], v[164:167], v[144:147], v[110:113]
	v_mul_f32_e32 v65, v65, v239
	v_mfma_f32_16x16x32_bf16 v[114:117], v[152:155], v[148:151], v[114:117]
	v_mfma_f32_16x16x32_bf16 v[118:121], v[156:159], v[148:151], v[118:121]
	v_cvt_pk_bf16_f32 v62, v62, v63
	v_mfma_f32_16x16x32_bf16 v[122:125], v[160:163], v[148:151], v[122:125]
	v_cvt_pk_bf16_f32 v63, v64, v65
	v_mfma_f32_16x16x32_bf16 v[126:129], v[164:167], v[148:151], v[126:129]
	global_store_dwordx2 v236, v[62:63], s[10:11] offset:96 sc1
	s_waitcnt lgkmcnt(0)
	v_mfma_f32_16x16x32_bf16 v[66:69], v[184:187], v[168:171], v[66:69]
	v_mfma_f32_16x16x32_bf16 v[70:73], v[188:191], v[168:171], v[70:73]
	v_mfma_f32_16x16x32_bf16 v[74:77], v[192:195], v[168:171], v[74:77]
	v_mfma_f32_16x16x32_bf16 v[78:81], v[196:199], v[168:171], v[78:81]
	v_mfma_f32_16x16x32_bf16 v[82:85], v[184:187], v[172:175], v[82:85]
	v_mfma_f32_16x16x32_bf16 v[86:89], v[188:191], v[172:175], v[86:89]
	v_mfma_f32_16x16x32_bf16 v[90:93], v[192:195], v[172:175], v[90:93]
	v_mfma_f32_16x16x32_bf16 v[94:97], v[196:199], v[172:175], v[94:97]
	v_mfma_f32_16x16x32_bf16 v[98:101], v[184:187], v[176:179], v[98:101]
	v_mfma_f32_16x16x32_bf16 v[102:105], v[188:191], v[176:179], v[102:105]
	v_mfma_f32_16x16x32_bf16 v[106:109], v[192:195], v[176:179], v[106:109]
	v_mfma_f32_16x16x32_bf16 v[110:113], v[196:199], v[176:179], v[110:113]
	v_mfma_f32_16x16x32_bf16 v[114:117], v[184:187], v[180:183], v[114:117]
	v_mfma_f32_16x16x32_bf16 v[118:121], v[188:191], v[180:183], v[118:121]
	v_mfma_f32_16x16x32_bf16 v[122:125], v[192:195], v[180:183], v[122:125]
	v_mfma_f32_16x16x32_bf16 v[126:129], v[196:199], v[180:183], v[126:129]
	s_nop 7
	s_add_u32 s10, s52, 0x100
	s_addc_u32 s11, s53, 0
	v_mul_f32_e32 v1, s12, v66
	v_mul_f32_e32 v130, s12, v67
	v_mul_f32_e32 v238, s12, v68
	v_mul_f32_e32 v239, s12, v69
	v_exp_f32_e32 v1, v1
	v_exp_f32_e32 v130, v130
	v_exp_f32_e32 v238, v238
	v_exp_f32_e32 v239, v239
	v_add_f32_e32 v1, 1.0, v1
	v_add_f32_e32 v130, 1.0, v130
	v_add_f32_e32 v238, 1.0, v238
	v_add_f32_e32 v239, 1.0, v239
	v_rcp_f32_e32 v1, v1
	v_rcp_f32_e32 v130, v130
	v_rcp_f32_e32 v238, v238
	v_rcp_f32_e32 v239, v239
	v_mul_f32_e32 v66, v66, v1
	v_mul_f32_e32 v67, v67, v130
	v_mul_f32_e32 v68, v68, v238
	v_mul_f32_e32 v69, v69, v239
	v_cvt_pk_bf16_f32 v66, v66, v67
	v_cvt_pk_bf16_f32 v67, v68, v69
	global_store_dwordx2 v236, v[66:67], s[10:11] offset:0 sc1
	v_mul_f32_e32 v1, s12, v70
	v_mul_f32_e32 v130, s12, v71
	v_mul_f32_e32 v238, s12, v72
	v_mul_f32_e32 v239, s12, v73
	v_exp_f32_e32 v1, v1
	v_exp_f32_e32 v130, v130
	v_exp_f32_e32 v238, v238
	v_exp_f32_e32 v239, v239
	v_add_f32_e32 v1, 1.0, v1
	v_add_f32_e32 v130, 1.0, v130
	v_add_f32_e32 v238, 1.0, v238
	v_add_f32_e32 v239, 1.0, v239
	v_rcp_f32_e32 v1, v1
	v_rcp_f32_e32 v130, v130
	v_rcp_f32_e32 v238, v238
	v_rcp_f32_e32 v239, v239
	v_mul_f32_e32 v70, v70, v1
	v_mul_f32_e32 v71, v71, v130
	v_mul_f32_e32 v72, v72, v238
	v_mul_f32_e32 v73, v73, v239
	v_cvt_pk_bf16_f32 v70, v70, v71
	v_cvt_pk_bf16_f32 v71, v72, v73
	global_store_dwordx2 v236, v[70:71], s[10:11] offset:32 sc1
	v_mul_f32_e32 v1, s12, v74
	v_mul_f32_e32 v130, s12, v75
	v_mul_f32_e32 v238, s12, v76
	v_mul_f32_e32 v239, s12, v77
	v_exp_f32_e32 v1, v1
	v_exp_f32_e32 v130, v130
	v_exp_f32_e32 v238, v238
	v_exp_f32_e32 v239, v239
	v_add_f32_e32 v1, 1.0, v1
	v_add_f32_e32 v130, 1.0, v130
	v_add_f32_e32 v238, 1.0, v238
	v_add_f32_e32 v239, 1.0, v239
	v_rcp_f32_e32 v1, v1
	v_rcp_f32_e32 v130, v130
	v_rcp_f32_e32 v238, v238
	v_rcp_f32_e32 v239, v239
	v_mul_f32_e32 v74, v74, v1
	v_mul_f32_e32 v75, v75, v130
	v_mul_f32_e32 v76, v76, v238
	v_mul_f32_e32 v77, v77, v239
	v_cvt_pk_bf16_f32 v74, v74, v75
	v_cvt_pk_bf16_f32 v75, v76, v77
	global_store_dwordx2 v236, v[74:75], s[10:11] offset:64 sc1
	v_mul_f32_e32 v1, s12, v78
	v_mul_f32_e32 v130, s12, v79
	v_mul_f32_e32 v238, s12, v80
	v_mul_f32_e32 v239, s12, v81
	v_exp_f32_e32 v1, v1
	v_exp_f32_e32 v130, v130
	v_exp_f32_e32 v238, v238
	v_exp_f32_e32 v239, v239
	v_add_f32_e32 v1, 1.0, v1
	v_add_f32_e32 v130, 1.0, v130
	v_add_f32_e32 v238, 1.0, v238
	v_add_f32_e32 v239, 1.0, v239
	v_rcp_f32_e32 v1, v1
	v_rcp_f32_e32 v130, v130
	v_rcp_f32_e32 v238, v238
	v_rcp_f32_e32 v239, v239
	v_mul_f32_e32 v78, v78, v1
	v_mul_f32_e32 v79, v79, v130
	v_mul_f32_e32 v80, v80, v238
	v_mul_f32_e32 v81, v81, v239
	v_cvt_pk_bf16_f32 v78, v78, v79
	v_cvt_pk_bf16_f32 v79, v80, v81
	global_store_dwordx2 v236, v[78:79], s[10:11] offset:96 sc1
	s_add_u32 s10, s10, 0x8000
	s_addc_u32 s11, s11, 0
	v_mul_f32_e32 v1, s12, v82
	v_mul_f32_e32 v130, s12, v83
	v_mul_f32_e32 v238, s12, v84
	v_mul_f32_e32 v239, s12, v85
	v_exp_f32_e32 v1, v1
	v_exp_f32_e32 v130, v130
	v_exp_f32_e32 v238, v238
	v_exp_f32_e32 v239, v239
	v_add_f32_e32 v1, 1.0, v1
	v_add_f32_e32 v130, 1.0, v130
	v_add_f32_e32 v238, 1.0, v238
	v_add_f32_e32 v239, 1.0, v239
	v_rcp_f32_e32 v1, v1
	v_rcp_f32_e32 v130, v130
	v_rcp_f32_e32 v238, v238
	v_rcp_f32_e32 v239, v239
	v_mul_f32_e32 v82, v82, v1
	v_mul_f32_e32 v83, v83, v130
	v_mul_f32_e32 v84, v84, v238
	v_mul_f32_e32 v85, v85, v239
	v_cvt_pk_bf16_f32 v82, v82, v83
	v_cvt_pk_bf16_f32 v83, v84, v85
	global_store_dwordx2 v236, v[82:83], s[10:11] offset:0 sc1
	v_mul_f32_e32 v1, s12, v86
	v_mul_f32_e32 v130, s12, v87
	v_mul_f32_e32 v238, s12, v88
	v_mul_f32_e32 v239, s12, v89
	v_exp_f32_e32 v1, v1
	v_exp_f32_e32 v130, v130
	v_exp_f32_e32 v238, v238
	v_exp_f32_e32 v239, v239
	v_add_f32_e32 v1, 1.0, v1
	v_add_f32_e32 v130, 1.0, v130
	v_add_f32_e32 v238, 1.0, v238
	v_add_f32_e32 v239, 1.0, v239
	v_rcp_f32_e32 v1, v1
	v_rcp_f32_e32 v130, v130
	v_rcp_f32_e32 v238, v238
	v_rcp_f32_e32 v239, v239
	v_mul_f32_e32 v86, v86, v1
	v_mul_f32_e32 v87, v87, v130
	v_mul_f32_e32 v88, v88, v238
	v_mul_f32_e32 v89, v89, v239
	v_cvt_pk_bf16_f32 v86, v86, v87
	v_cvt_pk_bf16_f32 v87, v88, v89
	global_store_dwordx2 v236, v[86:87], s[10:11] offset:32 sc1
	v_mul_f32_e32 v1, s12, v90
	v_mul_f32_e32 v130, s12, v91
	v_mul_f32_e32 v238, s12, v92
	v_mul_f32_e32 v239, s12, v93
	v_exp_f32_e32 v1, v1
	v_exp_f32_e32 v130, v130
	v_exp_f32_e32 v238, v238
	v_exp_f32_e32 v239, v239
	v_add_f32_e32 v1, 1.0, v1
	v_add_f32_e32 v130, 1.0, v130
	v_add_f32_e32 v238, 1.0, v238
	v_add_f32_e32 v239, 1.0, v239
	v_rcp_f32_e32 v1, v1
	v_rcp_f32_e32 v130, v130
	v_rcp_f32_e32 v238, v238
	v_rcp_f32_e32 v239, v239
	v_mul_f32_e32 v90, v90, v1
	v_mul_f32_e32 v91, v91, v130
	v_mul_f32_e32 v92, v92, v238
	v_mul_f32_e32 v93, v93, v239
	v_cvt_pk_bf16_f32 v90, v90, v91
	v_cvt_pk_bf16_f32 v91, v92, v93
	global_store_dwordx2 v236, v[90:91], s[10:11] offset:64 sc1
	v_mul_f32_e32 v1, s12, v94
	v_mul_f32_e32 v130, s12, v95
	v_mul_f32_e32 v238, s12, v96
	v_mul_f32_e32 v239, s12, v97
	v_exp_f32_e32 v1, v1
	v_exp_f32_e32 v130, v130
	v_exp_f32_e32 v238, v238
	v_exp_f32_e32 v239, v239
	v_add_f32_e32 v1, 1.0, v1
	v_add_f32_e32 v130, 1.0, v130
	v_add_f32_e32 v238, 1.0, v238
	v_add_f32_e32 v239, 1.0, v239
	v_rcp_f32_e32 v1, v1
	v_rcp_f32_e32 v130, v130
	v_rcp_f32_e32 v238, v238
	v_rcp_f32_e32 v239, v239
	v_mul_f32_e32 v94, v94, v1
	v_mul_f32_e32 v95, v95, v130
	v_mul_f32_e32 v96, v96, v238
	v_mul_f32_e32 v97, v97, v239
	v_cvt_pk_bf16_f32 v94, v94, v95
	v_cvt_pk_bf16_f32 v95, v96, v97
	global_store_dwordx2 v236, v[94:95], s[10:11] offset:96 sc1
	s_add_u32 s10, s10, 0x8000
	s_addc_u32 s11, s11, 0
	v_mul_f32_e32 v1, s12, v98
	v_mul_f32_e32 v130, s12, v99
	v_mul_f32_e32 v238, s12, v100
	v_mul_f32_e32 v239, s12, v101
	v_exp_f32_e32 v1, v1
	v_exp_f32_e32 v130, v130
	v_exp_f32_e32 v238, v238
	v_exp_f32_e32 v239, v239
	v_add_f32_e32 v1, 1.0, v1
	v_add_f32_e32 v130, 1.0, v130
	v_add_f32_e32 v238, 1.0, v238
	v_add_f32_e32 v239, 1.0, v239
	v_rcp_f32_e32 v1, v1
	v_rcp_f32_e32 v130, v130
	v_rcp_f32_e32 v238, v238
	v_rcp_f32_e32 v239, v239
	v_mul_f32_e32 v98, v98, v1
	v_mul_f32_e32 v99, v99, v130
	v_mul_f32_e32 v100, v100, v238
	v_mul_f32_e32 v101, v101, v239
	v_cvt_pk_bf16_f32 v98, v98, v99
	v_cvt_pk_bf16_f32 v99, v100, v101
	global_store_dwordx2 v236, v[98:99], s[10:11] offset:0 sc1
	v_mul_f32_e32 v1, s12, v102
	v_mul_f32_e32 v130, s12, v103
	v_mul_f32_e32 v238, s12, v104
	v_mul_f32_e32 v239, s12, v105
	v_exp_f32_e32 v1, v1
	v_exp_f32_e32 v130, v130
	v_exp_f32_e32 v238, v238
	v_exp_f32_e32 v239, v239
	v_add_f32_e32 v1, 1.0, v1
	v_add_f32_e32 v130, 1.0, v130
	v_add_f32_e32 v238, 1.0, v238
	v_add_f32_e32 v239, 1.0, v239
	v_rcp_f32_e32 v1, v1
	v_rcp_f32_e32 v130, v130
	v_rcp_f32_e32 v238, v238
	v_rcp_f32_e32 v239, v239
	v_mul_f32_e32 v102, v102, v1
	v_mul_f32_e32 v103, v103, v130
	v_mul_f32_e32 v104, v104, v238
	v_mul_f32_e32 v105, v105, v239
	v_cvt_pk_bf16_f32 v102, v102, v103
	v_cvt_pk_bf16_f32 v103, v104, v105
	global_store_dwordx2 v236, v[102:103], s[10:11] offset:32 sc1
	v_mul_f32_e32 v1, s12, v106
	v_mul_f32_e32 v130, s12, v107
	v_mul_f32_e32 v238, s12, v108
	v_mul_f32_e32 v239, s12, v109
	v_exp_f32_e32 v1, v1
	v_exp_f32_e32 v130, v130
	v_exp_f32_e32 v238, v238
	v_exp_f32_e32 v239, v239
	v_add_f32_e32 v1, 1.0, v1
	v_add_f32_e32 v130, 1.0, v130
	v_add_f32_e32 v238, 1.0, v238
	v_add_f32_e32 v239, 1.0, v239
	v_rcp_f32_e32 v1, v1
	v_rcp_f32_e32 v130, v130
	v_rcp_f32_e32 v238, v238
	v_rcp_f32_e32 v239, v239
	v_mul_f32_e32 v106, v106, v1
	v_mul_f32_e32 v107, v107, v130
	v_mul_f32_e32 v108, v108, v238
	v_mul_f32_e32 v109, v109, v239
	v_cvt_pk_bf16_f32 v106, v106, v107
	v_cvt_pk_bf16_f32 v107, v108, v109
	global_store_dwordx2 v236, v[106:107], s[10:11] offset:64 sc1
	v_mul_f32_e32 v1, s12, v110
	v_mul_f32_e32 v130, s12, v111
	v_mul_f32_e32 v238, s12, v112
	v_mul_f32_e32 v239, s12, v113
	v_exp_f32_e32 v1, v1
	v_exp_f32_e32 v130, v130
	v_exp_f32_e32 v238, v238
	v_exp_f32_e32 v239, v239
	v_add_f32_e32 v1, 1.0, v1
	v_add_f32_e32 v130, 1.0, v130
	v_add_f32_e32 v238, 1.0, v238
	v_add_f32_e32 v239, 1.0, v239
	v_rcp_f32_e32 v1, v1
	v_rcp_f32_e32 v130, v130
	v_rcp_f32_e32 v238, v238
	v_rcp_f32_e32 v239, v239
	v_mul_f32_e32 v110, v110, v1
	v_mul_f32_e32 v111, v111, v130
	v_mul_f32_e32 v112, v112, v238
	v_mul_f32_e32 v113, v113, v239
	v_cvt_pk_bf16_f32 v110, v110, v111
	v_cvt_pk_bf16_f32 v111, v112, v113
	global_store_dwordx2 v236, v[110:111], s[10:11] offset:96 sc1
	s_add_u32 s10, s10, 0x8000
	s_addc_u32 s11, s11, 0
	v_mul_f32_e32 v1, s12, v114
	v_mul_f32_e32 v130, s12, v115
	v_mul_f32_e32 v238, s12, v116
	v_mul_f32_e32 v239, s12, v117
	v_exp_f32_e32 v1, v1
	v_exp_f32_e32 v130, v130
	v_exp_f32_e32 v238, v238
	v_exp_f32_e32 v239, v239
	v_add_f32_e32 v1, 1.0, v1
	v_add_f32_e32 v130, 1.0, v130
	v_add_f32_e32 v238, 1.0, v238
	v_add_f32_e32 v239, 1.0, v239
	v_rcp_f32_e32 v1, v1
	v_rcp_f32_e32 v130, v130
	v_rcp_f32_e32 v238, v238
	v_rcp_f32_e32 v239, v239
	v_mul_f32_e32 v114, v114, v1
	v_mul_f32_e32 v115, v115, v130
	v_mul_f32_e32 v116, v116, v238
	v_mul_f32_e32 v117, v117, v239
	v_cvt_pk_bf16_f32 v114, v114, v115
	v_cvt_pk_bf16_f32 v115, v116, v117
	global_store_dwordx2 v236, v[114:115], s[10:11] offset:0 sc1
	v_mul_f32_e32 v1, s12, v118
	v_mul_f32_e32 v130, s12, v119
	v_mul_f32_e32 v238, s12, v120
	v_mul_f32_e32 v239, s12, v121
	v_exp_f32_e32 v1, v1
	v_exp_f32_e32 v130, v130
	v_exp_f32_e32 v238, v238
	v_exp_f32_e32 v239, v239
	v_add_f32_e32 v1, 1.0, v1
	v_add_f32_e32 v130, 1.0, v130
	v_add_f32_e32 v238, 1.0, v238
	v_add_f32_e32 v239, 1.0, v239
	v_rcp_f32_e32 v1, v1
	v_rcp_f32_e32 v130, v130
	v_rcp_f32_e32 v238, v238
	v_rcp_f32_e32 v239, v239
	v_mul_f32_e32 v118, v118, v1
	v_mul_f32_e32 v119, v119, v130
	v_mul_f32_e32 v120, v120, v238
	v_mul_f32_e32 v121, v121, v239
	v_cvt_pk_bf16_f32 v118, v118, v119
	v_cvt_pk_bf16_f32 v119, v120, v121
	global_store_dwordx2 v236, v[118:119], s[10:11] offset:32 sc1
	v_mul_f32_e32 v1, s12, v122
	v_mul_f32_e32 v130, s12, v123
	v_mul_f32_e32 v238, s12, v124
	v_mul_f32_e32 v239, s12, v125
	v_exp_f32_e32 v1, v1
	v_exp_f32_e32 v130, v130
	v_exp_f32_e32 v238, v238
	v_exp_f32_e32 v239, v239
	v_add_f32_e32 v1, 1.0, v1
	v_add_f32_e32 v130, 1.0, v130
	v_add_f32_e32 v238, 1.0, v238
	v_add_f32_e32 v239, 1.0, v239
	v_rcp_f32_e32 v1, v1
	v_rcp_f32_e32 v130, v130
	v_rcp_f32_e32 v238, v238
	v_rcp_f32_e32 v239, v239
	v_mul_f32_e32 v122, v122, v1
	v_mul_f32_e32 v123, v123, v130
	v_mul_f32_e32 v124, v124, v238
	v_mul_f32_e32 v125, v125, v239
	v_cvt_pk_bf16_f32 v122, v122, v123
	v_cvt_pk_bf16_f32 v123, v124, v125
	global_store_dwordx2 v236, v[122:123], s[10:11] offset:64 sc1
	v_mul_f32_e32 v1, s12, v126
	v_mul_f32_e32 v130, s12, v127
	v_mul_f32_e32 v238, s12, v128
	v_mul_f32_e32 v239, s12, v129
	v_exp_f32_e32 v1, v1
	v_exp_f32_e32 v130, v130
	v_exp_f32_e32 v238, v238
	v_exp_f32_e32 v239, v239
	v_add_f32_e32 v1, 1.0, v1
	v_add_f32_e32 v130, 1.0, v130
	v_add_f32_e32 v238, 1.0, v238
	v_add_f32_e32 v239, 1.0, v239
	v_rcp_f32_e32 v1, v1
	v_rcp_f32_e32 v130, v130
	v_rcp_f32_e32 v238, v238
	v_rcp_f32_e32 v239, v239
	v_mul_f32_e32 v126, v126, v1
	v_mul_f32_e32 v127, v127, v130
	v_mul_f32_e32 v128, v128, v238
	v_mul_f32_e32 v129, v129, v239
	v_cvt_pk_bf16_f32 v126, v126, v127
	v_cvt_pk_bf16_f32 v127, v128, v129
	global_store_dwordx2 v236, v[126:127], s[10:11] offset:96 sc1
	s_branch .La1_done
.La1_p:
	s_mul_i32 s51, s1, 0x220000
	s_add_u32 s52, s28, s51
	s_addc_u32 s53, s29, 0
	s_add_u32 s52, s52, 0x2000
	s_addc_u32 s53, s53, 0
	s_mov_b32 m0, s8
	s_nop 0
	global_load_lds_dwordx4 v200, s[4:5]
	s_add_u32 m0, s8, 0x400
	s_nop 0
	global_load_lds_dwordx4 v201, s[4:5]
	s_add_u32 m0, s8, 0x800
	s_nop 0
	global_load_lds_dwordx4 v202, s[4:5]
	s_add_u32 m0, s8, 0xc00
	s_nop 0
	global_load_lds_dwordx4 v203, s[4:5]
	s_mov_b32 m0, s9
	s_nop 0
	global_load_lds_dwordx4 v204, s[6:7]
	s_add_u32 m0, s9, 0x400
	s_nop 0
	global_load_lds_dwordx4 v205, s[6:7]
	s_add_u32 s4, s4, 0x80
	s_addc_u32 s5, s5, 0
	s_add_u32 s6, s6, 0x80
	s_addc_u32 s7, s7, 0
	s_add_u32 m0, s8, 0xc000
	s_nop 0
	global_load_lds_dwordx4 v200, s[4:5]
	s_add_u32 m0, s8, 0xc400
	s_nop 0
	global_load_lds_dwordx4 v201, s[4:5]
	s_add_u32 m0, s8, 0xc800
	s_nop 0
	global_load_lds_dwordx4 v202, s[4:5]
	s_add_u32 m0, s8, 0xcc00
	s_nop 0
	global_load_lds_dwordx4 v203, s[4:5]
	s_add_u32 m0, s9, 0xc000
	s_nop 0
	global_load_lds_dwordx4 v204, s[6:7]
	s_add_u32 m0, s9, 0xc400
	s_nop 0
	global_load_lds_dwordx4 v205, s[6:7]
	s_add_u32 s4, s4, 0x80
	s_addc_u32 s5, s5, 0
	s_add_u32 s6, s6, 0x80
	s_addc_u32 s7, s7, 0
	s_add_u32 m0, s8, 0x18000
	s_nop 0
	global_load_lds_dwordx4 v200, s[4:5]
	s_add_u32 m0, s8, 0x18400
	s_nop 0
	global_load_lds_dwordx4 v201, s[4:5]
	s_add_u32 m0, s8, 0x18800
	s_nop 0
	global_load_lds_dwordx4 v202, s[4:5]
	s_add_u32 m0, s8, 0x18c00
	s_nop 0
	global_load_lds_dwordx4 v203, s[4:5]
	s_add_u32 m0, s9, 0x18000
	s_nop 0
	global_load_lds_dwordx4 v204, s[6:7]
	s_add_u32 m0, s9, 0x18400
	s_nop 0
	global_load_lds_dwordx4 v205, s[6:7]
	s_add_u32 s4, s4, 0x80
	s_addc_u32 s5, s5, 0
	s_add_u32 s6, s6, 0x80
	s_addc_u32 s7, s7, 0
	s_waitcnt vmcnt(12)
	s_barrier
	ds_read_b128 v[136:139], v218 offset:0
	ds_read_b128 v[140:143], v218 offset:2048
	ds_read_b128 v[144:147], v218 offset:4096
	ds_read_b128 v[148:151], v218 offset:6144
	ds_read_b128 v[152:155], v230 offset:0
	ds_read_b128 v[156:159], v230 offset:2048
	ds_read_b128 v[160:163], v230 offset:4096
	ds_read_b128 v[164:167], v230 offset:6144
	s_waitcnt lgkmcnt(0)
	v_mfma_f32_16x16x32_bf16 v[2:5], v[152:155], v[136:139], 0
	ds_read_b128 v[168:171], v225 offset:0
	v_mfma_f32_16x16x32_bf16 v[6:9], v[156:159], v[136:139], 0
	ds_read_b128 v[172:175], v225 offset:2048
	v_mfma_f32_16x16x32_bf16 v[10:13], v[160:163], v[136:139], 0
	ds_read_b128 v[176:179], v225 offset:4096
	v_mfma_f32_16x16x32_bf16 v[14:17], v[164:167], v[136:139], 0
	ds_read_b128 v[180:183], v225 offset:6144
	v_mfma_f32_16x16x32_bf16 v[18:21], v[152:155], v[140:143], 0
	ds_read_b128 v[184:187], v233 offset:0
	v_mfma_f32_16x16x32_bf16 v[22:25], v[156:159], v[140:143], 0
	ds_read_b128 v[188:191], v233 offset:2048
	v_mfma_f32_16x16x32_bf16 v[26:29], v[160:163], v[140:143], 0
	ds_read_b128 v[192:195], v233 offset:4096
	v_mfma_f32_16x16x32_bf16 v[30:33], v[164:167], v[140:143], 0
	ds_read_b128 v[196:199], v233 offset:6144
	v_mfma_f32_16x16x32_bf16 v[34:37], v[152:155], v[144:147], 0
	v_mfma_f32_16x16x32_bf16 v[38:41], v[156:159], v[144:147], 0
	v_mfma_f32_16x16x32_bf16 v[42:45], v[160:163], v[144:147], 0
	v_mfma_f32_16x16x32_bf16 v[46:49], v[164:167], v[144:147], 0
	v_mfma_f32_16x16x32_bf16 v[50:53], v[152:155], v[148:151], 0
	v_mfma_f32_16x16x32_bf16 v[54:57], v[156:159], v[148:151], 0
	v_mfma_f32_16x16x32_bf16 v[58:61], v[160:163], v[148:151], 0
	v_mfma_f32_16x16x32_bf16 v[62:65], v[164:167], v[148:151], 0
	s_waitcnt vmcnt(6) lgkmcnt(0)
	s_barrier
	v_mfma_f32_16x16x32_bf16 v[2:5], v[184:187], v[168:171], v[2:5]
	ds_read_b128 v[136:139], v219 offset:0
	v_mfma_f32_16x16x32_bf16 v[6:9], v[188:191], v[168:171], v[6:9]
	ds_read_b128 v[140:143], v219 offset:2048
	v_mfma_f32_16x16x32_bf16 v[10:13], v[192:195], v[168:171], v[10:13]
	ds_read_b128 v[144:147], v219 offset:4096
	v_mfma_f32_16x16x32_bf16 v[14:17], v[196:199], v[168:171], v[14:17]
	ds_read_b128 v[148:151], v219 offset:6144
	v_mfma_f32_16x16x32_bf16 v[18:21], v[184:187], v[172:175], v[18:21]
	ds_read_b128 v[152:155], v231 offset:0
	v_mfma_f32_16x16x32_bf16 v[22:25], v[188:191], v[172:175], v[22:25]
	ds_read_b128 v[156:159], v231 offset:2048
	v_mfma_f32_16x16x32_bf16 v[26:29], v[192:195], v[172:175], v[26:29]
	ds_read_b128 v[160:163], v231 offset:4096
	v_mfma_f32_16x16x32_bf16 v[30:33], v[196:199], v[172:175], v[30:33]
	ds_read_b128 v[164:167], v231 offset:6144
	s_mov_b32 m0, s8
	v_mfma_f32_16x16x32_bf16 v[34:37], v[184:187], v[176:179], v[34:37]
	global_load_lds_dwordx4 v200, s[4:5]
	s_add_u32 m0, s8, 0x400
	v_mfma_f32_16x16x32_bf16 v[38:41], v[188:191], v[176:179], v[38:41]
	global_load_lds_dwordx4 v201, s[4:5]
	s_add_u32 m0, s8, 0x800
	v_mfma_f32_16x16x32_bf16 v[42:45], v[192:195], v[176:179], v[42:45]
	global_load_lds_dwordx4 v202, s[4:5]
	s_add_u32 m0, s8, 0xc00
	v_mfma_f32_16x16x32_bf16 v[46:49], v[196:199], v[176:179], v[46:49]
	global_load_lds_dwordx4 v203, s[4:5]
	s_mov_b32 m0, s9
	v_mfma_f32_16x16x32_bf16 v[50:53], v[184:187], v[180:183], v[50:53]
	global_load_lds_dwordx4 v204, s[6:7]
	s_add_u32 m0, s9, 0x400
	v_mfma_f32_16x16x32_bf16 v[54:57], v[188:191], v[180:183], v[54:57]
	global_load_lds_dwordx4 v205, s[6:7]
	v_mfma_f32_16x16x32_bf16 v[58:61], v[192:195], v[180:183], v[58:61]
	s_add_u32 s4, s4, 0x80
	s_addc_u32 s5, s5, 0
	v_mfma_f32_16x16x32_bf16 v[62:65], v[196:199], v[180:183], v[62:65]
	s_add_u32 s6, s6, 0x80
	s_addc_u32 s7, s7, 0
	s_waitcnt lgkmcnt(0)
	v_mfma_f32_16x16x32_bf16 v[2:5], v[152:155], v[136:139], v[2:5]
	ds_read_b128 v[168:171], v228 offset:0
	v_mfma_f32_16x16x32_bf16 v[6:9], v[156:159], v[136:139], v[6:9]
	ds_read_b128 v[172:175], v228 offset:2048
	v_mfma_f32_16x16x32_bf16 v[10:13], v[160:163], v[136:139], v[10:13]
	ds_read_b128 v[176:179], v228 offset:4096
	v_mfma_f32_16x16x32_bf16 v[14:17], v[164:167], v[136:139], v[14:17]
	ds_read_b128 v[180:183], v228 offset:6144
	v_mfma_f32_16x16x32_bf16 v[18:21], v[152:155], v[140:143], v[18:21]
	ds_read_b128 v[184:187], v234 offset:0
	v_mfma_f32_16x16x32_bf16 v[22:25], v[156:159], v[140:143], v[22:25]
	ds_read_b128 v[188:191], v234 offset:2048
	v_mfma_f32_16x16x32_bf16 v[26:29], v[160:163], v[140:143], v[26:29]
	ds_read_b128 v[192:195], v234 offset:4096
	v_mfma_f32_16x16x32_bf16 v[30:33], v[164:167], v[140:143], v[30:33]
	ds_read_b128 v[196:199], v234 offset:6144
	v_mfma_f32_16x16x32_bf16 v[34:37], v[152:155], v[144:147], v[34:37]
	v_mfma_f32_16x16x32_bf16 v[38:41], v[156:159], v[144:147], v[38:41]
	v_mfma_f32_16x16x32_bf16 v[42:45], v[160:163], v[144:147], v[42:45]
	v_mfma_f32_16x16x32_bf16 v[46:49], v[164:167], v[144:147], v[46:49]
	v_mfma_f32_16x16x32_bf16 v[50:53], v[152:155], v[148:151], v[50:53]
	v_mfma_f32_16x16x32_bf16 v[54:57], v[156:159], v[148:151], v[54:57]
	v_mfma_f32_16x16x32_bf16 v[58:61], v[160:163], v[148:151], v[58:61]
	v_mfma_f32_16x16x32_bf16 v[62:65], v[164:167], v[148:151], v[62:65]
	s_waitcnt vmcnt(6) lgkmcnt(0)
	s_barrier
	v_mfma_f32_16x16x32_bf16 v[2:5], v[184:187], v[168:171], v[2:5]
	ds_read_b128 v[136:139], v224 offset:0
	v_mfma_f32_16x16x32_bf16 v[6:9], v[188:191], v[168:171], v[6:9]
	ds_read_b128 v[140:143], v224 offset:2048
	v_mfma_f32_16x16x32_bf16 v[10:13], v[192:195], v[168:171], v[10:13]
	ds_read_b128 v[144:147], v224 offset:4096
	v_mfma_f32_16x16x32_bf16 v[14:17], v[196:199], v[168:171], v[14:17]
	ds_read_b128 v[148:151], v224 offset:6144
	v_mfma_f32_16x16x32_bf16 v[18:21], v[184:187], v[172:175], v[18:21]
	ds_read_b128 v[152:155], v232 offset:0
	v_mfma_f32_16x16x32_bf16 v[22:25], v[188:191], v[172:175], v[22:25]
	ds_read_b128 v[156:159], v232 offset:2048
	v_mfma_f32_16x16x32_bf16 v[26:29], v[192:195], v[172:175], v[26:29]
	ds_read_b128 v[160:163], v232 offset:4096
	v_mfma_f32_16x16x32_bf16 v[30:33], v[196:199], v[172:175], v[30:33]
	ds_read_b128 v[164:167], v232 offset:6144
	s_add_u32 m0, s8, 0xc000
	v_mfma_f32_16x16x32_bf16 v[34:37], v[184:187], v[176:179], v[34:37]
	global_load_lds_dwordx4 v200, s[4:5]
	s_add_u32 m0, s8, 0xc400
	v_mfma_f32_16x16x32_bf16 v[38:41], v[188:191], v[176:179], v[38:41]
	global_load_lds_dwordx4 v201, s[4:5]
	s_add_u32 m0, s8, 0xc800
	v_mfma_f32_16x16x32_bf16 v[42:45], v[192:195], v[176:179], v[42:45]
	global_load_lds_dwordx4 v202, s[4:5]
	s_add_u32 m0, s8, 0xcc00
	v_mfma_f32_16x16x32_bf16 v[46:49], v[196:199], v[176:179], v[46:49]
	global_load_lds_dwordx4 v203, s[4:5]
	s_add_u32 m0, s9, 0xc000
	v_mfma_f32_16x16x32_bf16 v[50:53], v[184:187], v[180:183], v[50:53]
	global_load_lds_dwordx4 v204, s[6:7]
	s_add_u32 m0, s9, 0xc400
	v_mfma_f32_16x16x32_bf16 v[54:57], v[188:191], v[180:183], v[54:57]
	global_load_lds_dwordx4 v205, s[6:7]
	v_mfma_f32_16x16x32_bf16 v[58:61], v[192:195], v[180:183], v[58:61]
	s_add_u32 s4, s4, 0x80
	s_addc_u32 s5, s5, 0
	v_mfma_f32_16x16x32_bf16 v[62:65], v[196:199], v[180:183], v[62:65]
	s_add_u32 s6, s6, 0x80
	s_addc_u32 s7, s7, 0
	s_waitcnt lgkmcnt(0)
	v_mfma_f32_16x16x32_bf16 v[2:5], v[152:155], v[136:139], v[2:5]
	ds_read_b128 v[168:171], v229 offset:0
	v_mfma_f32_16x16x32_bf16 v[6:9], v[156:159], v[136:139], v[6:9]
	ds_read_b128 v[172:175], v229 offset:2048
	v_mfma_f32_16x16x32_bf16 v[10:13], v[160:163], v[136:139], v[10:13]
	ds_read_b128 v[176:179], v229 offset:4096
	v_mfma_f32_16x16x32_bf16 v[14:17], v[164:167], v[136:139], v[14:17]
	ds_read_b128 v[180:183], v229 offset:6144
	v_mfma_f32_16x16x32_bf16 v[18:21], v[152:155], v[140:143], v[18:21]
	ds_read_b128 v[184:187], v235 offset:0
	v_mfma_f32_16x16x32_bf16 v[22:25], v[156:159], v[140:143], v[22:25]
	ds_read_b128 v[188:191], v235 offset:2048
	v_mfma_f32_16x16x32_bf16 v[26:29], v[160:163], v[140:143], v[26:29]
	ds_read_b128 v[192:195], v235 offset:4096
	v_mfma_f32_16x16x32_bf16 v[30:33], v[164:167], v[140:143], v[30:33]
	ds_read_b128 v[196:199], v235 offset:6144
	v_mfma_f32_16x16x32_bf16 v[34:37], v[152:155], v[144:147], v[34:37]
	v_mfma_f32_16x16x32_bf16 v[38:41], v[156:159], v[144:147], v[38:41]
	v_mfma_f32_16x16x32_bf16 v[42:45], v[160:163], v[144:147], v[42:45]
	v_mfma_f32_16x16x32_bf16 v[46:49], v[164:167], v[144:147], v[46:49]
	v_mfma_f32_16x16x32_bf16 v[50:53], v[152:155], v[148:151], v[50:53]
	v_mfma_f32_16x16x32_bf16 v[54:57], v[156:159], v[148:151], v[54:57]
	v_mfma_f32_16x16x32_bf16 v[58:61], v[160:163], v[148:151], v[58:61]
	v_mfma_f32_16x16x32_bf16 v[62:65], v[164:167], v[148:151], v[62:65]
	s_waitcnt vmcnt(6) lgkmcnt(0)
	s_barrier
	v_mfma_f32_16x16x32_bf16 v[2:5], v[184:187], v[168:171], v[2:5]
	ds_read_b128 v[136:139], v218 offset:0
	v_mfma_f32_16x16x32_bf16 v[6:9], v[188:191], v[168:171], v[6:9]
	ds_read_b128 v[140:143], v218 offset:2048
	v_mfma_f32_16x16x32_bf16 v[10:13], v[192:195], v[168:171], v[10:13]
	ds_read_b128 v[144:147], v218 offset:4096
	v_mfma_f32_16x16x32_bf16 v[14:17], v[196:199], v[168:171], v[14:17]
	ds_read_b128 v[148:151], v218 offset:6144
	v_mfma_f32_16x16x32_bf16 v[18:21], v[184:187], v[172:175], v[18:21]
	ds_read_b128 v[152:155], v230 offset:0
	v_mfma_f32_16x16x32_bf16 v[22:25], v[188:191], v[172:175], v[22:25]
	ds_read_b128 v[156:159], v230 offset:2048
	v_mfma_f32_16x16x32_bf16 v[26:29], v[192:195], v[172:175], v[26:29]
	ds_read_b128 v[160:163], v230 offset:4096
	v_mfma_f32_16x16x32_bf16 v[30:33], v[196:199], v[172:175], v[30:33]
	ds_read_b128 v[164:167], v230 offset:6144
	s_add_u32 m0, s8, 0x18000
	v_mfma_f32_16x16x32_bf16 v[34:37], v[184:187], v[176:179], v[34:37]
	global_load_lds_dwordx4 v200, s[4:5]
	s_add_u32 m0, s8, 0x18400
	v_mfma_f32_16x16x32_bf16 v[38:41], v[188:191], v[176:179], v[38:41]
	global_load_lds_dwordx4 v201, s[4:5]
	s_add_u32 m0, s8, 0x18800
	v_mfma_f32_16x16x32_bf16 v[42:45], v[192:195], v[176:179], v[42:45]
	global_load_lds_dwordx4 v202, s[4:5]
	s_add_u32 m0, s8, 0x18c00
	v_mfma_f32_16x16x32_bf16 v[46:49], v[196:199], v[176:179], v[46:49]
	global_load_lds_dwordx4 v203, s[4:5]
	s_add_u32 m0, s9, 0x18000
	v_mfma_f32_16x16x32_bf16 v[50:53], v[184:187], v[180:183], v[50:53]
	global_load_lds_dwordx4 v204, s[6:7]
	s_add_u32 m0, s9, 0x18400
	v_mfma_f32_16x16x32_bf16 v[54:57], v[188:191], v[180:183], v[54:57]
	global_load_lds_dwordx4 v205, s[6:7]
	v_mfma_f32_16x16x32_bf16 v[58:61], v[192:195], v[180:183], v[58:61]
	s_add_u32 s4, s4, 0x80
	s_addc_u32 s5, s5, 0
	v_mfma_f32_16x16x32_bf16 v[62:65], v[196:199], v[180:183], v[62:65]
	s_add_u32 s6, s6, 0x80
	s_addc_u32 s7, s7, 0
	s_waitcnt lgkmcnt(0)
	v_mfma_f32_16x16x32_bf16 v[2:5], v[152:155], v[136:139], v[2:5]
	ds_read_b128 v[168:171], v225 offset:0
	v_mfma_f32_16x16x32_bf16 v[6:9], v[156:159], v[136:139], v[6:9]
	ds_read_b128 v[172:175], v225 offset:2048
	v_mfma_f32_16x16x32_bf16 v[10:13], v[160:163], v[136:139], v[10:13]
	ds_read_b128 v[176:179], v225 offset:4096
	v_mfma_f32_16x16x32_bf16 v[14:17], v[164:167], v[136:139], v[14:17]
	ds_read_b128 v[180:183], v225 offset:6144
	v_mfma_f32_16x16x32_bf16 v[18:21], v[152:155], v[140:143], v[18:21]
	ds_read_b128 v[184:187], v233 offset:0
	v_mfma_f32_16x16x32_bf16 v[22:25], v[156:159], v[140:143], v[22:25]
	ds_read_b128 v[188:191], v233 offset:2048
	v_mfma_f32_16x16x32_bf16 v[26:29], v[160:163], v[140:143], v[26:29]
	ds_read_b128 v[192:195], v233 offset:4096
	v_mfma_f32_16x16x32_bf16 v[30:33], v[164:167], v[140:143], v[30:33]
	ds_read_b128 v[196:199], v233 offset:6144
	v_mfma_f32_16x16x32_bf16 v[34:37], v[152:155], v[144:147], v[34:37]
	v_mfma_f32_16x16x32_bf16 v[38:41], v[156:159], v[144:147], v[38:41]
	v_mfma_f32_16x16x32_bf16 v[42:45], v[160:163], v[144:147], v[42:45]
	v_mfma_f32_16x16x32_bf16 v[46:49], v[164:167], v[144:147], v[46:49]
	v_mfma_f32_16x16x32_bf16 v[50:53], v[152:155], v[148:151], v[50:53]
	v_mfma_f32_16x16x32_bf16 v[54:57], v[156:159], v[148:151], v[54:57]
	v_mfma_f32_16x16x32_bf16 v[58:61], v[160:163], v[148:151], v[58:61]
	v_mfma_f32_16x16x32_bf16 v[62:65], v[164:167], v[148:151], v[62:65]
	s_waitcnt vmcnt(6) lgkmcnt(0)
	s_barrier
	v_mfma_f32_16x16x32_bf16 v[2:5], v[184:187], v[168:171], v[2:5]
	ds_read_b128 v[136:139], v219 offset:0
	v_mfma_f32_16x16x32_bf16 v[6:9], v[188:191], v[168:171], v[6:9]
	ds_read_b128 v[140:143], v219 offset:2048
	v_mfma_f32_16x16x32_bf16 v[10:13], v[192:195], v[168:171], v[10:13]
	ds_read_b128 v[144:147], v219 offset:4096
	v_mfma_f32_16x16x32_bf16 v[14:17], v[196:199], v[168:171], v[14:17]
	ds_read_b128 v[148:151], v219 offset:6144
	v_mfma_f32_16x16x32_bf16 v[18:21], v[184:187], v[172:175], v[18:21]
	ds_read_b128 v[152:155], v231 offset:0
	v_mfma_f32_16x16x32_bf16 v[22:25], v[188:191], v[172:175], v[22:25]
	ds_read_b128 v[156:159], v231 offset:2048
	v_mfma_f32_16x16x32_bf16 v[26:29], v[192:195], v[172:175], v[26:29]
	ds_read_b128 v[160:163], v231 offset:4096
	v_mfma_f32_16x16x32_bf16 v[30:33], v[196:199], v[172:175], v[30:33]
	ds_read_b128 v[164:167], v231 offset:6144
	s_mov_b32 m0, s8
	v_mfma_f32_16x16x32_bf16 v[34:37], v[184:187], v[176:179], v[34:37]
	global_load_lds_dwordx4 v200, s[4:5]
	s_add_u32 m0, s8, 0x400
	v_mfma_f32_16x16x32_bf16 v[38:41], v[188:191], v[176:179], v[38:41]
	global_load_lds_dwordx4 v201, s[4:5]
	s_add_u32 m0, s8, 0x800
	v_mfma_f32_16x16x32_bf16 v[42:45], v[192:195], v[176:179], v[42:45]
	global_load_lds_dwordx4 v202, s[4:5]
	s_add_u32 m0, s8, 0xc00
	v_mfma_f32_16x16x32_bf16 v[46:49], v[196:199], v[176:179], v[46:49]
	global_load_lds_dwordx4 v203, s[4:5]
	s_mov_b32 m0, s9
	v_mfma_f32_16x16x32_bf16 v[50:53], v[184:187], v[180:183], v[50:53]
	global_load_lds_dwordx4 v204, s[6:7]
	s_add_u32 m0, s9, 0x400
	v_mfma_f32_16x16x32_bf16 v[54:57], v[188:191], v[180:183], v[54:57]
	global_load_lds_dwordx4 v205, s[6:7]
	v_mfma_f32_16x16x32_bf16 v[58:61], v[192:195], v[180:183], v[58:61]
	s_add_u32 s4, s4, 0x80
	s_addc_u32 s5, s5, 0
	v_mfma_f32_16x16x32_bf16 v[62:65], v[196:199], v[180:183], v[62:65]
	s_add_u32 s6, s6, 0x80
	s_addc_u32 s7, s7, 0
	s_waitcnt lgkmcnt(0)
	v_mfma_f32_16x16x32_bf16 v[2:5], v[152:155], v[136:139], v[2:5]
	ds_read_b128 v[168:171], v228 offset:0
	v_mfma_f32_16x16x32_bf16 v[6:9], v[156:159], v[136:139], v[6:9]
	ds_read_b128 v[172:175], v228 offset:2048
	v_mfma_f32_16x16x32_bf16 v[10:13], v[160:163], v[136:139], v[10:13]
	ds_read_b128 v[176:179], v228 offset:4096
	v_mfma_f32_16x16x32_bf16 v[14:17], v[164:167], v[136:139], v[14:17]
	ds_read_b128 v[180:183], v228 offset:6144
	v_mfma_f32_16x16x32_bf16 v[18:21], v[152:155], v[140:143], v[18:21]
	ds_read_b128 v[184:187], v234 offset:0
	v_mfma_f32_16x16x32_bf16 v[22:25], v[156:159], v[140:143], v[22:25]
	ds_read_b128 v[188:191], v234 offset:2048
	v_mfma_f32_16x16x32_bf16 v[26:29], v[160:163], v[140:143], v[26:29]
	ds_read_b128 v[192:195], v234 offset:4096
	v_mfma_f32_16x16x32_bf16 v[30:33], v[164:167], v[140:143], v[30:33]
	ds_read_b128 v[196:199], v234 offset:6144
	v_mfma_f32_16x16x32_bf16 v[34:37], v[152:155], v[144:147], v[34:37]
	v_mfma_f32_16x16x32_bf16 v[38:41], v[156:159], v[144:147], v[38:41]
	v_mfma_f32_16x16x32_bf16 v[42:45], v[160:163], v[144:147], v[42:45]
	v_mfma_f32_16x16x32_bf16 v[46:49], v[164:167], v[144:147], v[46:49]
	v_mfma_f32_16x16x32_bf16 v[50:53], v[152:155], v[148:151], v[50:53]
	v_mfma_f32_16x16x32_bf16 v[54:57], v[156:159], v[148:151], v[54:57]
	v_mfma_f32_16x16x32_bf16 v[58:61], v[160:163], v[148:151], v[58:61]
	v_mfma_f32_16x16x32_bf16 v[62:65], v[164:167], v[148:151], v[62:65]
	s_waitcnt vmcnt(6) lgkmcnt(0)
	s_barrier
	v_mfma_f32_16x16x32_bf16 v[2:5], v[184:187], v[168:171], v[2:5]
	ds_read_b128 v[136:139], v224 offset:0
	v_mfma_f32_16x16x32_bf16 v[6:9], v[188:191], v[168:171], v[6:9]
	ds_read_b128 v[140:143], v224 offset:2048
	v_mfma_f32_16x16x32_bf16 v[10:13], v[192:195], v[168:171], v[10:13]
	ds_read_b128 v[144:147], v224 offset:4096
	v_mfma_f32_16x16x32_bf16 v[14:17], v[196:199], v[168:171], v[14:17]
	ds_read_b128 v[148:151], v224 offset:6144
	v_mfma_f32_16x16x32_bf16 v[18:21], v[184:187], v[172:175], v[18:21]
	ds_read_b128 v[152:155], v232 offset:0
	v_mfma_f32_16x16x32_bf16 v[22:25], v[188:191], v[172:175], v[22:25]
	ds_read_b128 v[156:159], v232 offset:2048
	v_mfma_f32_16x16x32_bf16 v[26:29], v[192:195], v[172:175], v[26:29]
	ds_read_b128 v[160:163], v232 offset:4096
	v_mfma_f32_16x16x32_bf16 v[30:33], v[196:199], v[172:175], v[30:33]
	ds_read_b128 v[164:167], v232 offset:6144
	s_add_u32 m0, s8, 0xc000
	v_mfma_f32_16x16x32_bf16 v[34:37], v[184:187], v[176:179], v[34:37]
	global_load_lds_dwordx4 v200, s[4:5]
	s_add_u32 m0, s8, 0xc400
	v_mfma_f32_16x16x32_bf16 v[38:41], v[188:191], v[176:179], v[38:41]
	global_load_lds_dwordx4 v201, s[4:5]
	s_add_u32 m0, s8, 0xc800
	v_mfma_f32_16x16x32_bf16 v[42:45], v[192:195], v[176:179], v[42:45]
	global_load_lds_dwordx4 v202, s[4:5]
	s_add_u32 m0, s8, 0xcc00
	v_mfma_f32_16x16x32_bf16 v[46:49], v[196:199], v[176:179], v[46:49]
	global_load_lds_dwordx4 v203, s[4:5]
	s_add_u32 m0, s9, 0xc000
	v_mfma_f32_16x16x32_bf16 v[50:53], v[184:187], v[180:183], v[50:53]
	global_load_lds_dwordx4 v204, s[6:7]
	s_add_u32 m0, s9, 0xc400
	v_mfma_f32_16x16x32_bf16 v[54:57], v[188:191], v[180:183], v[54:57]
	global_load_lds_dwordx4 v205, s[6:7]
	v_mfma_f32_16x16x32_bf16 v[58:61], v[192:195], v[180:183], v[58:61]
	s_add_u32 s4, s4, 0x80
	s_addc_u32 s5, s5, 0
	v_mfma_f32_16x16x32_bf16 v[62:65], v[196:199], v[180:183], v[62:65]
	s_add_u32 s6, s6, 0x80
	s_addc_u32 s7, s7, 0
	s_waitcnt lgkmcnt(0)
	v_mfma_f32_16x16x32_bf16 v[2:5], v[152:155], v[136:139], v[2:5]
	ds_read_b128 v[168:171], v229 offset:0
	v_mfma_f32_16x16x32_bf16 v[6:9], v[156:159], v[136:139], v[6:9]
	ds_read_b128 v[172:175], v229 offset:2048
	v_mfma_f32_16x16x32_bf16 v[10:13], v[160:163], v[136:139], v[10:13]
	ds_read_b128 v[176:179], v229 offset:4096
	v_mfma_f32_16x16x32_bf16 v[14:17], v[164:167], v[136:139], v[14:17]
	ds_read_b128 v[180:183], v229 offset:6144
	v_mfma_f32_16x16x32_bf16 v[18:21], v[152:155], v[140:143], v[18:21]
	ds_read_b128 v[184:187], v235 offset:0
	v_mfma_f32_16x16x32_bf16 v[22:25], v[156:159], v[140:143], v[22:25]
	ds_read_b128 v[188:191], v235 offset:2048
	v_mfma_f32_16x16x32_bf16 v[26:29], v[160:163], v[140:143], v[26:29]
	ds_read_b128 v[192:195], v235 offset:4096
	v_mfma_f32_16x16x32_bf16 v[30:33], v[164:167], v[140:143], v[30:33]
	ds_read_b128 v[196:199], v235 offset:6144
	v_mfma_f32_16x16x32_bf16 v[34:37], v[152:155], v[144:147], v[34:37]
	v_mfma_f32_16x16x32_bf16 v[38:41], v[156:159], v[144:147], v[38:41]
	v_mfma_f32_16x16x32_bf16 v[42:45], v[160:163], v[144:147], v[42:45]
	v_mfma_f32_16x16x32_bf16 v[46:49], v[164:167], v[144:147], v[46:49]
	v_mfma_f32_16x16x32_bf16 v[50:53], v[152:155], v[148:151], v[50:53]
	v_mfma_f32_16x16x32_bf16 v[54:57], v[156:159], v[148:151], v[54:57]
	v_mfma_f32_16x16x32_bf16 v[58:61], v[160:163], v[148:151], v[58:61]
	v_mfma_f32_16x16x32_bf16 v[62:65], v[164:167], v[148:151], v[62:65]
	s_waitcnt vmcnt(6) lgkmcnt(0)
	s_barrier
	v_mfma_f32_16x16x32_bf16 v[2:5], v[184:187], v[168:171], v[2:5]
	ds_read_b128 v[136:139], v218 offset:0
	v_mfma_f32_16x16x32_bf16 v[6:9], v[188:191], v[168:171], v[6:9]
	ds_read_b128 v[140:143], v218 offset:2048
	v_mfma_f32_16x16x32_bf16 v[10:13], v[192:195], v[168:171], v[10:13]
	ds_read_b128 v[144:147], v218 offset:4096
	v_mfma_f32_16x16x32_bf16 v[14:17], v[196:199], v[168:171], v[14:17]
	ds_read_b128 v[148:151], v218 offset:6144
	v_mfma_f32_16x16x32_bf16 v[18:21], v[184:187], v[172:175], v[18:21]
	ds_read_b128 v[152:155], v230 offset:0
	v_mfma_f32_16x16x32_bf16 v[22:25], v[188:191], v[172:175], v[22:25]
	ds_read_b128 v[156:159], v230 offset:2048
	v_mfma_f32_16x16x32_bf16 v[26:29], v[192:195], v[172:175], v[26:29]
	ds_read_b128 v[160:163], v230 offset:4096
	v_mfma_f32_16x16x32_bf16 v[30:33], v[196:199], v[172:175], v[30:33]
	ds_read_b128 v[164:167], v230 offset:6144
	s_add_u32 m0, s8, 0x18000
	v_mfma_f32_16x16x32_bf16 v[34:37], v[184:187], v[176:179], v[34:37]
	global_load_lds_dwordx4 v200, s[4:5]
	s_add_u32 m0, s8, 0x18400
	v_mfma_f32_16x16x32_bf16 v[38:41], v[188:191], v[176:179], v[38:41]
	global_load_lds_dwordx4 v201, s[4:5]
	s_add_u32 m0, s8, 0x18800
	v_mfma_f32_16x16x32_bf16 v[42:45], v[192:195], v[176:179], v[42:45]
	global_load_lds_dwordx4 v202, s[4:5]
	s_add_u32 m0, s8, 0x18c00
	v_mfma_f32_16x16x32_bf16 v[46:49], v[196:199], v[176:179], v[46:49]
	global_load_lds_dwordx4 v203, s[4:5]
	s_add_u32 m0, s9, 0x18000
	v_mfma_f32_16x16x32_bf16 v[50:53], v[184:187], v[180:183], v[50:53]
	global_load_lds_dwordx4 v204, s[6:7]
	s_add_u32 m0, s9, 0x18400
	v_mfma_f32_16x16x32_bf16 v[54:57], v[188:191], v[180:183], v[54:57]
	global_load_lds_dwordx4 v205, s[6:7]
	v_mfma_f32_16x16x32_bf16 v[58:61], v[192:195], v[180:183], v[58:61]
	s_add_u32 s4, s4, 0x80
	s_addc_u32 s5, s5, 0
	v_mfma_f32_16x16x32_bf16 v[62:65], v[196:199], v[180:183], v[62:65]
	s_add_u32 s6, s6, 0x80
	s_addc_u32 s7, s7, 0
	s_waitcnt lgkmcnt(0)
	v_mfma_f32_16x16x32_bf16 v[2:5], v[152:155], v[136:139], v[2:5]
	ds_read_b128 v[168:171], v225 offset:0
	v_mfma_f32_16x16x32_bf16 v[6:9], v[156:159], v[136:139], v[6:9]
	ds_read_b128 v[172:175], v225 offset:2048
	v_mfma_f32_16x16x32_bf16 v[10:13], v[160:163], v[136:139], v[10:13]
	ds_read_b128 v[176:179], v225 offset:4096
	v_mfma_f32_16x16x32_bf16 v[14:17], v[164:167], v[136:139], v[14:17]
	ds_read_b128 v[180:183], v225 offset:6144
	v_mfma_f32_16x16x32_bf16 v[18:21], v[152:155], v[140:143], v[18:21]
	ds_read_b128 v[184:187], v233 offset:0
	v_mfma_f32_16x16x32_bf16 v[22:25], v[156:159], v[140:143], v[22:25]
	ds_read_b128 v[188:191], v233 offset:2048
	v_mfma_f32_16x16x32_bf16 v[26:29], v[160:163], v[140:143], v[26:29]
	ds_read_b128 v[192:195], v233 offset:4096
	v_mfma_f32_16x16x32_bf16 v[30:33], v[164:167], v[140:143], v[30:33]
	ds_read_b128 v[196:199], v233 offset:6144
	v_mfma_f32_16x16x32_bf16 v[34:37], v[152:155], v[144:147], v[34:37]
	v_mfma_f32_16x16x32_bf16 v[38:41], v[156:159], v[144:147], v[38:41]
	v_mfma_f32_16x16x32_bf16 v[42:45], v[160:163], v[144:147], v[42:45]
	v_mfma_f32_16x16x32_bf16 v[46:49], v[164:167], v[144:147], v[46:49]
	v_mfma_f32_16x16x32_bf16 v[50:53], v[152:155], v[148:151], v[50:53]
	v_mfma_f32_16x16x32_bf16 v[54:57], v[156:159], v[148:151], v[54:57]
	v_mfma_f32_16x16x32_bf16 v[58:61], v[160:163], v[148:151], v[58:61]
	v_mfma_f32_16x16x32_bf16 v[62:65], v[164:167], v[148:151], v[62:65]
	s_waitcnt vmcnt(6) lgkmcnt(0)
	s_barrier
	v_mfma_f32_16x16x32_bf16 v[2:5], v[184:187], v[168:171], v[2:5]
	ds_read_b128 v[136:139], v219 offset:0
	v_mfma_f32_16x16x32_bf16 v[6:9], v[188:191], v[168:171], v[6:9]
	ds_read_b128 v[140:143], v219 offset:2048
	v_mfma_f32_16x16x32_bf16 v[10:13], v[192:195], v[168:171], v[10:13]
	ds_read_b128 v[144:147], v219 offset:4096
	v_mfma_f32_16x16x32_bf16 v[14:17], v[196:199], v[168:171], v[14:17]
	ds_read_b128 v[148:151], v219 offset:6144
	v_mfma_f32_16x16x32_bf16 v[18:21], v[184:187], v[172:175], v[18:21]
	ds_read_b128 v[152:155], v231 offset:0
	v_mfma_f32_16x16x32_bf16 v[22:25], v[188:191], v[172:175], v[22:25]
	ds_read_b128 v[156:159], v231 offset:2048
	v_mfma_f32_16x16x32_bf16 v[26:29], v[192:195], v[172:175], v[26:29]
	ds_read_b128 v[160:163], v231 offset:4096
	v_mfma_f32_16x16x32_bf16 v[30:33], v[196:199], v[172:175], v[30:33]
	ds_read_b128 v[164:167], v231 offset:6144
	s_mov_b32 m0, s8
	v_mfma_f32_16x16x32_bf16 v[34:37], v[184:187], v[176:179], v[34:37]
	global_load_lds_dwordx4 v200, s[4:5]
	s_add_u32 m0, s8, 0x400
	v_mfma_f32_16x16x32_bf16 v[38:41], v[188:191], v[176:179], v[38:41]
	global_load_lds_dwordx4 v201, s[4:5]
	s_add_u32 m0, s8, 0x800
	v_mfma_f32_16x16x32_bf16 v[42:45], v[192:195], v[176:179], v[42:45]
	global_load_lds_dwordx4 v202, s[4:5]
	s_add_u32 m0, s8, 0xc00
	v_mfma_f32_16x16x32_bf16 v[46:49], v[196:199], v[176:179], v[46:49]
	global_load_lds_dwordx4 v203, s[4:5]
	s_mov_b32 m0, s9
	v_mfma_f32_16x16x32_bf16 v[50:53], v[184:187], v[180:183], v[50:53]
	global_load_lds_dwordx4 v204, s[6:7]
	s_add_u32 m0, s9, 0x400
	v_mfma_f32_16x16x32_bf16 v[54:57], v[188:191], v[180:183], v[54:57]
	global_load_lds_dwordx4 v205, s[6:7]
	v_mfma_f32_16x16x32_bf16 v[58:61], v[192:195], v[180:183], v[58:61]
	s_add_u32 s4, s4, 0x80
	s_addc_u32 s5, s5, 0
	v_mfma_f32_16x16x32_bf16 v[62:65], v[196:199], v[180:183], v[62:65]
	s_add_u32 s6, s6, 0x80
	s_addc_u32 s7, s7, 0
	s_waitcnt lgkmcnt(0)
	v_mfma_f32_16x16x32_bf16 v[2:5], v[152:155], v[136:139], v[2:5]
	ds_read_b128 v[168:171], v228 offset:0
	v_mfma_f32_16x16x32_bf16 v[6:9], v[156:159], v[136:139], v[6:9]
	ds_read_b128 v[172:175], v228 offset:2048
	v_mfma_f32_16x16x32_bf16 v[10:13], v[160:163], v[136:139], v[10:13]
	ds_read_b128 v[176:179], v228 offset:4096
	v_mfma_f32_16x16x32_bf16 v[14:17], v[164:167], v[136:139], v[14:17]
	ds_read_b128 v[180:183], v228 offset:6144
	v_mfma_f32_16x16x32_bf16 v[18:21], v[152:155], v[140:143], v[18:21]
	ds_read_b128 v[184:187], v234 offset:0
	v_mfma_f32_16x16x32_bf16 v[22:25], v[156:159], v[140:143], v[22:25]
	ds_read_b128 v[188:191], v234 offset:2048
	v_mfma_f32_16x16x32_bf16 v[26:29], v[160:163], v[140:143], v[26:29]
	ds_read_b128 v[192:195], v234 offset:4096
	v_mfma_f32_16x16x32_bf16 v[30:33], v[164:167], v[140:143], v[30:33]
	ds_read_b128 v[196:199], v234 offset:6144
	v_mfma_f32_16x16x32_bf16 v[34:37], v[152:155], v[144:147], v[34:37]
	v_mfma_f32_16x16x32_bf16 v[38:41], v[156:159], v[144:147], v[38:41]
	v_mfma_f32_16x16x32_bf16 v[42:45], v[160:163], v[144:147], v[42:45]
	v_mfma_f32_16x16x32_bf16 v[46:49], v[164:167], v[144:147], v[46:49]
	v_mfma_f32_16x16x32_bf16 v[50:53], v[152:155], v[148:151], v[50:53]
	v_mfma_f32_16x16x32_bf16 v[54:57], v[156:159], v[148:151], v[54:57]
	v_mfma_f32_16x16x32_bf16 v[58:61], v[160:163], v[148:151], v[58:61]
	v_mfma_f32_16x16x32_bf16 v[62:65], v[164:167], v[148:151], v[62:65]
	s_waitcnt vmcnt(6) lgkmcnt(0)
	s_barrier
	v_mfma_f32_16x16x32_bf16 v[2:5], v[184:187], v[168:171], v[2:5]
	ds_read_b128 v[136:139], v224 offset:0
	v_mfma_f32_16x16x32_bf16 v[6:9], v[188:191], v[168:171], v[6:9]
	ds_read_b128 v[140:143], v224 offset:2048
	v_mfma_f32_16x16x32_bf16 v[10:13], v[192:195], v[168:171], v[10:13]
	ds_read_b128 v[144:147], v224 offset:4096
	v_mfma_f32_16x16x32_bf16 v[14:17], v[196:199], v[168:171], v[14:17]
	ds_read_b128 v[148:151], v224 offset:6144
	v_mfma_f32_16x16x32_bf16 v[18:21], v[184:187], v[172:175], v[18:21]
	ds_read_b128 v[152:155], v232 offset:0
	v_mfma_f32_16x16x32_bf16 v[22:25], v[188:191], v[172:175], v[22:25]
	ds_read_b128 v[156:159], v232 offset:2048
	v_mfma_f32_16x16x32_bf16 v[26:29], v[192:195], v[172:175], v[26:29]
	ds_read_b128 v[160:163], v232 offset:4096
	v_mfma_f32_16x16x32_bf16 v[30:33], v[196:199], v[172:175], v[30:33]
	ds_read_b128 v[164:167], v232 offset:6144
	s_add_u32 m0, s8, 0xc000
	v_mfma_f32_16x16x32_bf16 v[34:37], v[184:187], v[176:179], v[34:37]
	global_load_lds_dwordx4 v200, s[4:5]
	s_add_u32 m0, s8, 0xc400
	v_mfma_f32_16x16x32_bf16 v[38:41], v[188:191], v[176:179], v[38:41]
	global_load_lds_dwordx4 v201, s[4:5]
	s_add_u32 m0, s8, 0xc800
	v_mfma_f32_16x16x32_bf16 v[42:45], v[192:195], v[176:179], v[42:45]
	global_load_lds_dwordx4 v202, s[4:5]
	s_add_u32 m0, s8, 0xcc00
	v_mfma_f32_16x16x32_bf16 v[46:49], v[196:199], v[176:179], v[46:49]
	global_load_lds_dwordx4 v203, s[4:5]
	s_add_u32 m0, s9, 0xc000
	v_mfma_f32_16x16x32_bf16 v[50:53], v[184:187], v[180:183], v[50:53]
	global_load_lds_dwordx4 v204, s[6:7]
	s_add_u32 m0, s9, 0xc400
	v_mfma_f32_16x16x32_bf16 v[54:57], v[188:191], v[180:183], v[54:57]
	global_load_lds_dwordx4 v205, s[6:7]
	v_mfma_f32_16x16x32_bf16 v[58:61], v[192:195], v[180:183], v[58:61]
	s_add_u32 s4, s4, 0x80
	s_addc_u32 s5, s5, 0
	v_mfma_f32_16x16x32_bf16 v[62:65], v[196:199], v[180:183], v[62:65]
	s_add_u32 s6, s6, 0x80
	s_addc_u32 s7, s7, 0
	s_waitcnt lgkmcnt(0)
	v_mfma_f32_16x16x32_bf16 v[2:5], v[152:155], v[136:139], v[2:5]
	ds_read_b128 v[168:171], v229 offset:0
	v_mfma_f32_16x16x32_bf16 v[6:9], v[156:159], v[136:139], v[6:9]
	ds_read_b128 v[172:175], v229 offset:2048
	v_mfma_f32_16x16x32_bf16 v[10:13], v[160:163], v[136:139], v[10:13]
	ds_read_b128 v[176:179], v229 offset:4096
	v_mfma_f32_16x16x32_bf16 v[14:17], v[164:167], v[136:139], v[14:17]
	ds_read_b128 v[180:183], v229 offset:6144
	v_mfma_f32_16x16x32_bf16 v[18:21], v[152:155], v[140:143], v[18:21]
	ds_read_b128 v[184:187], v235 offset:0
	v_mfma_f32_16x16x32_bf16 v[22:25], v[156:159], v[140:143], v[22:25]
	ds_read_b128 v[188:191], v235 offset:2048
	v_mfma_f32_16x16x32_bf16 v[26:29], v[160:163], v[140:143], v[26:29]
	ds_read_b128 v[192:195], v235 offset:4096
	v_mfma_f32_16x16x32_bf16 v[30:33], v[164:167], v[140:143], v[30:33]
	ds_read_b128 v[196:199], v235 offset:6144
	v_mfma_f32_16x16x32_bf16 v[34:37], v[152:155], v[144:147], v[34:37]
	v_mfma_f32_16x16x32_bf16 v[38:41], v[156:159], v[144:147], v[38:41]
	v_mfma_f32_16x16x32_bf16 v[42:45], v[160:163], v[144:147], v[42:45]
	v_mfma_f32_16x16x32_bf16 v[46:49], v[164:167], v[144:147], v[46:49]
	v_mfma_f32_16x16x32_bf16 v[50:53], v[152:155], v[148:151], v[50:53]
	v_mfma_f32_16x16x32_bf16 v[54:57], v[156:159], v[148:151], v[54:57]
	v_mfma_f32_16x16x32_bf16 v[58:61], v[160:163], v[148:151], v[58:61]
	v_mfma_f32_16x16x32_bf16 v[62:65], v[164:167], v[148:151], v[62:65]
	s_waitcnt vmcnt(6) lgkmcnt(0)
	s_barrier
	v_mfma_f32_16x16x32_bf16 v[2:5], v[184:187], v[168:171], v[2:5]
	ds_read_b128 v[136:139], v218 offset:0
	v_mfma_f32_16x16x32_bf16 v[6:9], v[188:191], v[168:171], v[6:9]
	ds_read_b128 v[140:143], v218 offset:2048
	v_mfma_f32_16x16x32_bf16 v[10:13], v[192:195], v[168:171], v[10:13]
	ds_read_b128 v[144:147], v218 offset:4096
	v_mfma_f32_16x16x32_bf16 v[14:17], v[196:199], v[168:171], v[14:17]
	ds_read_b128 v[148:151], v218 offset:6144
	v_mfma_f32_16x16x32_bf16 v[18:21], v[184:187], v[172:175], v[18:21]
	ds_read_b128 v[152:155], v230 offset:0
	v_mfma_f32_16x16x32_bf16 v[22:25], v[188:191], v[172:175], v[22:25]
	ds_read_b128 v[156:159], v230 offset:2048
	v_mfma_f32_16x16x32_bf16 v[26:29], v[192:195], v[172:175], v[26:29]
	ds_read_b128 v[160:163], v230 offset:4096
	v_mfma_f32_16x16x32_bf16 v[30:33], v[196:199], v[172:175], v[30:33]
	ds_read_b128 v[164:167], v230 offset:6144
	s_add_u32 m0, s8, 0x18000
	v_mfma_f32_16x16x32_bf16 v[34:37], v[184:187], v[176:179], v[34:37]
	global_load_lds_dwordx4 v200, s[4:5]
	s_add_u32 m0, s8, 0x18400
	v_mfma_f32_16x16x32_bf16 v[38:41], v[188:191], v[176:179], v[38:41]
	global_load_lds_dwordx4 v201, s[4:5]
	s_add_u32 m0, s8, 0x18800
	v_mfma_f32_16x16x32_bf16 v[42:45], v[192:195], v[176:179], v[42:45]
	global_load_lds_dwordx4 v202, s[4:5]
	s_add_u32 m0, s8, 0x18c00
	v_mfma_f32_16x16x32_bf16 v[46:49], v[196:199], v[176:179], v[46:49]
	global_load_lds_dwordx4 v203, s[4:5]
	s_add_u32 m0, s9, 0x18000
	v_mfma_f32_16x16x32_bf16 v[50:53], v[184:187], v[180:183], v[50:53]
	global_load_lds_dwordx4 v204, s[6:7]
	s_add_u32 m0, s9, 0x18400
	v_mfma_f32_16x16x32_bf16 v[54:57], v[188:191], v[180:183], v[54:57]
	global_load_lds_dwordx4 v205, s[6:7]
	v_mfma_f32_16x16x32_bf16 v[58:61], v[192:195], v[180:183], v[58:61]
	s_add_u32 s4, s4, 0x80
	s_addc_u32 s5, s5, 0
	v_mfma_f32_16x16x32_bf16 v[62:65], v[196:199], v[180:183], v[62:65]
	s_add_u32 s6, s6, 0x80
	s_addc_u32 s7, s7, 0
	s_waitcnt lgkmcnt(0)
	v_mfma_f32_16x16x32_bf16 v[2:5], v[152:155], v[136:139], v[2:5]
	ds_read_b128 v[168:171], v225 offset:0
	v_mfma_f32_16x16x32_bf16 v[6:9], v[156:159], v[136:139], v[6:9]
	ds_read_b128 v[172:175], v225 offset:2048
	v_mfma_f32_16x16x32_bf16 v[10:13], v[160:163], v[136:139], v[10:13]
	ds_read_b128 v[176:179], v225 offset:4096
	v_mfma_f32_16x16x32_bf16 v[14:17], v[164:167], v[136:139], v[14:17]
	ds_read_b128 v[180:183], v225 offset:6144
	v_mfma_f32_16x16x32_bf16 v[18:21], v[152:155], v[140:143], v[18:21]
	ds_read_b128 v[184:187], v233 offset:0
	v_mfma_f32_16x16x32_bf16 v[22:25], v[156:159], v[140:143], v[22:25]
	ds_read_b128 v[188:191], v233 offset:2048
	v_mfma_f32_16x16x32_bf16 v[26:29], v[160:163], v[140:143], v[26:29]
	ds_read_b128 v[192:195], v233 offset:4096
	v_mfma_f32_16x16x32_bf16 v[30:33], v[164:167], v[140:143], v[30:33]
	ds_read_b128 v[196:199], v233 offset:6144
	v_mfma_f32_16x16x32_bf16 v[34:37], v[152:155], v[144:147], v[34:37]
	v_mfma_f32_16x16x32_bf16 v[38:41], v[156:159], v[144:147], v[38:41]
	v_mfma_f32_16x16x32_bf16 v[42:45], v[160:163], v[144:147], v[42:45]
	v_mfma_f32_16x16x32_bf16 v[46:49], v[164:167], v[144:147], v[46:49]
	v_mfma_f32_16x16x32_bf16 v[50:53], v[152:155], v[148:151], v[50:53]
	v_mfma_f32_16x16x32_bf16 v[54:57], v[156:159], v[148:151], v[54:57]
	v_mfma_f32_16x16x32_bf16 v[58:61], v[160:163], v[148:151], v[58:61]
	v_mfma_f32_16x16x32_bf16 v[62:65], v[164:167], v[148:151], v[62:65]
	s_waitcnt vmcnt(6) lgkmcnt(0)
	s_barrier
	v_mfma_f32_16x16x32_bf16 v[2:5], v[184:187], v[168:171], v[2:5]
	ds_read_b128 v[136:139], v219 offset:0
	v_mfma_f32_16x16x32_bf16 v[6:9], v[188:191], v[168:171], v[6:9]
	ds_read_b128 v[140:143], v219 offset:2048
	v_mfma_f32_16x16x32_bf16 v[10:13], v[192:195], v[168:171], v[10:13]
	ds_read_b128 v[144:147], v219 offset:4096
	v_mfma_f32_16x16x32_bf16 v[14:17], v[196:199], v[168:171], v[14:17]
	ds_read_b128 v[148:151], v219 offset:6144
	v_mfma_f32_16x16x32_bf16 v[18:21], v[184:187], v[172:175], v[18:21]
	ds_read_b128 v[152:155], v231 offset:0
	v_mfma_f32_16x16x32_bf16 v[22:25], v[188:191], v[172:175], v[22:25]
	ds_read_b128 v[156:159], v231 offset:2048
	v_mfma_f32_16x16x32_bf16 v[26:29], v[192:195], v[172:175], v[26:29]
	ds_read_b128 v[160:163], v231 offset:4096
	v_mfma_f32_16x16x32_bf16 v[30:33], v[196:199], v[172:175], v[30:33]
	ds_read_b128 v[164:167], v231 offset:6144
	s_mov_b32 m0, s8
	v_mfma_f32_16x16x32_bf16 v[34:37], v[184:187], v[176:179], v[34:37]
	global_load_lds_dwordx4 v200, s[4:5]
	s_add_u32 m0, s8, 0x400
	v_mfma_f32_16x16x32_bf16 v[38:41], v[188:191], v[176:179], v[38:41]
	global_load_lds_dwordx4 v201, s[4:5]
	s_add_u32 m0, s8, 0x800
	v_mfma_f32_16x16x32_bf16 v[42:45], v[192:195], v[176:179], v[42:45]
	global_load_lds_dwordx4 v202, s[4:5]
	s_add_u32 m0, s8, 0xc00
	v_mfma_f32_16x16x32_bf16 v[46:49], v[196:199], v[176:179], v[46:49]
	global_load_lds_dwordx4 v203, s[4:5]
	s_mov_b32 m0, s9
	v_mfma_f32_16x16x32_bf16 v[50:53], v[184:187], v[180:183], v[50:53]
	global_load_lds_dwordx4 v204, s[6:7]
	s_add_u32 m0, s9, 0x400
	v_mfma_f32_16x16x32_bf16 v[54:57], v[188:191], v[180:183], v[54:57]
	global_load_lds_dwordx4 v205, s[6:7]
	v_mfma_f32_16x16x32_bf16 v[58:61], v[192:195], v[180:183], v[58:61]
	s_add_u32 s4, s4, 0x80
	s_addc_u32 s5, s5, 0
	v_mfma_f32_16x16x32_bf16 v[62:65], v[196:199], v[180:183], v[62:65]
	s_add_u32 s6, s6, 0x80
	s_addc_u32 s7, s7, 0
	s_waitcnt lgkmcnt(0)
	v_mfma_f32_16x16x32_bf16 v[2:5], v[152:155], v[136:139], v[2:5]
	ds_read_b128 v[168:171], v228 offset:0
	v_mfma_f32_16x16x32_bf16 v[6:9], v[156:159], v[136:139], v[6:9]
	ds_read_b128 v[172:175], v228 offset:2048
	v_mfma_f32_16x16x32_bf16 v[10:13], v[160:163], v[136:139], v[10:13]
	ds_read_b128 v[176:179], v228 offset:4096
	v_mfma_f32_16x16x32_bf16 v[14:17], v[164:167], v[136:139], v[14:17]
	ds_read_b128 v[180:183], v228 offset:6144
	v_mfma_f32_16x16x32_bf16 v[18:21], v[152:155], v[140:143], v[18:21]
	ds_read_b128 v[184:187], v234 offset:0
	v_mfma_f32_16x16x32_bf16 v[22:25], v[156:159], v[140:143], v[22:25]
	ds_read_b128 v[188:191], v234 offset:2048
	v_mfma_f32_16x16x32_bf16 v[26:29], v[160:163], v[140:143], v[26:29]
	ds_read_b128 v[192:195], v234 offset:4096
	v_mfma_f32_16x16x32_bf16 v[30:33], v[164:167], v[140:143], v[30:33]
	ds_read_b128 v[196:199], v234 offset:6144
	v_mfma_f32_16x16x32_bf16 v[34:37], v[152:155], v[144:147], v[34:37]
	v_mfma_f32_16x16x32_bf16 v[38:41], v[156:159], v[144:147], v[38:41]
	v_mfma_f32_16x16x32_bf16 v[42:45], v[160:163], v[144:147], v[42:45]
	v_mfma_f32_16x16x32_bf16 v[46:49], v[164:167], v[144:147], v[46:49]
	v_mfma_f32_16x16x32_bf16 v[50:53], v[152:155], v[148:151], v[50:53]
	v_mfma_f32_16x16x32_bf16 v[54:57], v[156:159], v[148:151], v[54:57]
	v_mfma_f32_16x16x32_bf16 v[58:61], v[160:163], v[148:151], v[58:61]
	v_mfma_f32_16x16x32_bf16 v[62:65], v[164:167], v[148:151], v[62:65]
	s_waitcnt vmcnt(6) lgkmcnt(0)
	s_barrier
	v_mfma_f32_16x16x32_bf16 v[2:5], v[184:187], v[168:171], v[2:5]
	ds_read_b128 v[136:139], v224 offset:0
	v_mfma_f32_16x16x32_bf16 v[6:9], v[188:191], v[168:171], v[6:9]
	ds_read_b128 v[140:143], v224 offset:2048
	v_mfma_f32_16x16x32_bf16 v[10:13], v[192:195], v[168:171], v[10:13]
	ds_read_b128 v[144:147], v224 offset:4096
	v_mfma_f32_16x16x32_bf16 v[14:17], v[196:199], v[168:171], v[14:17]
	ds_read_b128 v[148:151], v224 offset:6144
	v_mfma_f32_16x16x32_bf16 v[18:21], v[184:187], v[172:175], v[18:21]
	ds_read_b128 v[152:155], v232 offset:0
	v_mfma_f32_16x16x32_bf16 v[22:25], v[188:191], v[172:175], v[22:25]
	ds_read_b128 v[156:159], v232 offset:2048
	v_mfma_f32_16x16x32_bf16 v[26:29], v[192:195], v[172:175], v[26:29]
	ds_read_b128 v[160:163], v232 offset:4096
	v_mfma_f32_16x16x32_bf16 v[30:33], v[196:199], v[172:175], v[30:33]
	ds_read_b128 v[164:167], v232 offset:6144
	s_add_u32 m0, s8, 0xc000
	v_mfma_f32_16x16x32_bf16 v[34:37], v[184:187], v[176:179], v[34:37]
	global_load_lds_dwordx4 v200, s[4:5]
	s_add_u32 m0, s8, 0xc400
	v_mfma_f32_16x16x32_bf16 v[38:41], v[188:191], v[176:179], v[38:41]
	global_load_lds_dwordx4 v201, s[4:5]
	s_add_u32 m0, s8, 0xc800
	v_mfma_f32_16x16x32_bf16 v[42:45], v[192:195], v[176:179], v[42:45]
	global_load_lds_dwordx4 v202, s[4:5]
	s_add_u32 m0, s8, 0xcc00
	v_mfma_f32_16x16x32_bf16 v[46:49], v[196:199], v[176:179], v[46:49]
	global_load_lds_dwordx4 v203, s[4:5]
	s_add_u32 m0, s9, 0xc000
	v_mfma_f32_16x16x32_bf16 v[50:53], v[184:187], v[180:183], v[50:53]
	global_load_lds_dwordx4 v204, s[6:7]
	s_add_u32 m0, s9, 0xc400
	v_mfma_f32_16x16x32_bf16 v[54:57], v[188:191], v[180:183], v[54:57]
	global_load_lds_dwordx4 v205, s[6:7]
	v_mfma_f32_16x16x32_bf16 v[58:61], v[192:195], v[180:183], v[58:61]
	s_add_u32 s4, s4, 0x80
	s_addc_u32 s5, s5, 0
	v_mfma_f32_16x16x32_bf16 v[62:65], v[196:199], v[180:183], v[62:65]
	s_add_u32 s6, s6, 0x80
	s_addc_u32 s7, s7, 0
	s_waitcnt lgkmcnt(0)
	v_mfma_f32_16x16x32_bf16 v[2:5], v[152:155], v[136:139], v[2:5]
	ds_read_b128 v[168:171], v229 offset:0
	v_mfma_f32_16x16x32_bf16 v[6:9], v[156:159], v[136:139], v[6:9]
	ds_read_b128 v[172:175], v229 offset:2048
	v_mfma_f32_16x16x32_bf16 v[10:13], v[160:163], v[136:139], v[10:13]
	ds_read_b128 v[176:179], v229 offset:4096
	v_mfma_f32_16x16x32_bf16 v[14:17], v[164:167], v[136:139], v[14:17]
	ds_read_b128 v[180:183], v229 offset:6144
	v_mfma_f32_16x16x32_bf16 v[18:21], v[152:155], v[140:143], v[18:21]
	ds_read_b128 v[184:187], v235 offset:0
	v_mfma_f32_16x16x32_bf16 v[22:25], v[156:159], v[140:143], v[22:25]
	ds_read_b128 v[188:191], v235 offset:2048
	v_mfma_f32_16x16x32_bf16 v[26:29], v[160:163], v[140:143], v[26:29]
	ds_read_b128 v[192:195], v235 offset:4096
	v_mfma_f32_16x16x32_bf16 v[30:33], v[164:167], v[140:143], v[30:33]
	ds_read_b128 v[196:199], v235 offset:6144
	v_mfma_f32_16x16x32_bf16 v[34:37], v[152:155], v[144:147], v[34:37]
	v_mfma_f32_16x16x32_bf16 v[38:41], v[156:159], v[144:147], v[38:41]
	v_mfma_f32_16x16x32_bf16 v[42:45], v[160:163], v[144:147], v[42:45]
	v_mfma_f32_16x16x32_bf16 v[46:49], v[164:167], v[144:147], v[46:49]
	v_mfma_f32_16x16x32_bf16 v[50:53], v[152:155], v[148:151], v[50:53]
	v_mfma_f32_16x16x32_bf16 v[54:57], v[156:159], v[148:151], v[54:57]
	v_mfma_f32_16x16x32_bf16 v[58:61], v[160:163], v[148:151], v[58:61]
	v_mfma_f32_16x16x32_bf16 v[62:65], v[164:167], v[148:151], v[62:65]
	s_waitcnt vmcnt(6) lgkmcnt(0)
	s_barrier
	v_mfma_f32_16x16x32_bf16 v[2:5], v[184:187], v[168:171], v[2:5]
	ds_read_b128 v[136:139], v218 offset:0
	v_mfma_f32_16x16x32_bf16 v[6:9], v[188:191], v[168:171], v[6:9]
	ds_read_b128 v[140:143], v218 offset:2048
	v_mfma_f32_16x16x32_bf16 v[10:13], v[192:195], v[168:171], v[10:13]
	ds_read_b128 v[144:147], v218 offset:4096
	v_mfma_f32_16x16x32_bf16 v[14:17], v[196:199], v[168:171], v[14:17]
	ds_read_b128 v[148:151], v218 offset:6144
	v_mfma_f32_16x16x32_bf16 v[18:21], v[184:187], v[172:175], v[18:21]
	ds_read_b128 v[152:155], v230 offset:0
	v_mfma_f32_16x16x32_bf16 v[22:25], v[188:191], v[172:175], v[22:25]
	ds_read_b128 v[156:159], v230 offset:2048
	v_mfma_f32_16x16x32_bf16 v[26:29], v[192:195], v[172:175], v[26:29]
	ds_read_b128 v[160:163], v230 offset:4096
	v_mfma_f32_16x16x32_bf16 v[30:33], v[196:199], v[172:175], v[30:33]
	ds_read_b128 v[164:167], v230 offset:6144
	s_add_u32 m0, s8, 0x18000
	v_mfma_f32_16x16x32_bf16 v[34:37], v[184:187], v[176:179], v[34:37]
	global_load_lds_dwordx4 v200, s[4:5]
	s_add_u32 m0, s8, 0x18400
	v_mfma_f32_16x16x32_bf16 v[38:41], v[188:191], v[176:179], v[38:41]
	global_load_lds_dwordx4 v201, s[4:5]
	s_add_u32 m0, s8, 0x18800
	v_mfma_f32_16x16x32_bf16 v[42:45], v[192:195], v[176:179], v[42:45]
	global_load_lds_dwordx4 v202, s[4:5]
	s_add_u32 m0, s8, 0x18c00
	v_mfma_f32_16x16x32_bf16 v[46:49], v[196:199], v[176:179], v[46:49]
	global_load_lds_dwordx4 v203, s[4:5]
	s_add_u32 m0, s9, 0x18000
	v_mfma_f32_16x16x32_bf16 v[50:53], v[184:187], v[180:183], v[50:53]
	global_load_lds_dwordx4 v204, s[6:7]
	s_add_u32 m0, s9, 0x18400
	v_mfma_f32_16x16x32_bf16 v[54:57], v[188:191], v[180:183], v[54:57]
	global_load_lds_dwordx4 v205, s[6:7]
	v_mfma_f32_16x16x32_bf16 v[58:61], v[192:195], v[180:183], v[58:61]
	s_add_u32 s4, s4, 0x80
	s_addc_u32 s5, s5, 0
	v_mfma_f32_16x16x32_bf16 v[62:65], v[196:199], v[180:183], v[62:65]
	s_add_u32 s6, s6, 0x80
	s_addc_u32 s7, s7, 0
	s_waitcnt lgkmcnt(0)
	v_mfma_f32_16x16x32_bf16 v[2:5], v[152:155], v[136:139], v[2:5]
	ds_read_b128 v[168:171], v225 offset:0
	v_mfma_f32_16x16x32_bf16 v[6:9], v[156:159], v[136:139], v[6:9]
	ds_read_b128 v[172:175], v225 offset:2048
	v_mfma_f32_16x16x32_bf16 v[10:13], v[160:163], v[136:139], v[10:13]
	ds_read_b128 v[176:179], v225 offset:4096
	v_mfma_f32_16x16x32_bf16 v[14:17], v[164:167], v[136:139], v[14:17]
	ds_read_b128 v[180:183], v225 offset:6144
	v_mfma_f32_16x16x32_bf16 v[18:21], v[152:155], v[140:143], v[18:21]
	ds_read_b128 v[184:187], v233 offset:0
	v_mfma_f32_16x16x32_bf16 v[22:25], v[156:159], v[140:143], v[22:25]
	ds_read_b128 v[188:191], v233 offset:2048
	v_mfma_f32_16x16x32_bf16 v[26:29], v[160:163], v[140:143], v[26:29]
	ds_read_b128 v[192:195], v233 offset:4096
	v_mfma_f32_16x16x32_bf16 v[30:33], v[164:167], v[140:143], v[30:33]
	ds_read_b128 v[196:199], v233 offset:6144
	v_mfma_f32_16x16x32_bf16 v[34:37], v[152:155], v[144:147], v[34:37]
	v_mfma_f32_16x16x32_bf16 v[38:41], v[156:159], v[144:147], v[38:41]
	v_mfma_f32_16x16x32_bf16 v[42:45], v[160:163], v[144:147], v[42:45]
	v_mfma_f32_16x16x32_bf16 v[46:49], v[164:167], v[144:147], v[46:49]
	v_mfma_f32_16x16x32_bf16 v[50:53], v[152:155], v[148:151], v[50:53]
	v_mfma_f32_16x16x32_bf16 v[54:57], v[156:159], v[148:151], v[54:57]
	v_mfma_f32_16x16x32_bf16 v[58:61], v[160:163], v[148:151], v[58:61]
	v_mfma_f32_16x16x32_bf16 v[62:65], v[164:167], v[148:151], v[62:65]
	s_waitcnt vmcnt(6) lgkmcnt(0)
	s_barrier
	v_mfma_f32_16x16x32_bf16 v[2:5], v[184:187], v[168:171], v[2:5]
	ds_read_b128 v[136:139], v219 offset:0
	v_mfma_f32_16x16x32_bf16 v[6:9], v[188:191], v[168:171], v[6:9]
	ds_read_b128 v[140:143], v219 offset:2048
	v_mfma_f32_16x16x32_bf16 v[10:13], v[192:195], v[168:171], v[10:13]
	ds_read_b128 v[144:147], v219 offset:4096
	v_mfma_f32_16x16x32_bf16 v[14:17], v[196:199], v[168:171], v[14:17]
	ds_read_b128 v[148:151], v219 offset:6144
	v_mfma_f32_16x16x32_bf16 v[18:21], v[184:187], v[172:175], v[18:21]
	ds_read_b128 v[152:155], v231 offset:0
	v_mfma_f32_16x16x32_bf16 v[22:25], v[188:191], v[172:175], v[22:25]
	ds_read_b128 v[156:159], v231 offset:2048
	v_mfma_f32_16x16x32_bf16 v[26:29], v[192:195], v[172:175], v[26:29]
	ds_read_b128 v[160:163], v231 offset:4096
	v_mfma_f32_16x16x32_bf16 v[30:33], v[196:199], v[172:175], v[30:33]
	ds_read_b128 v[164:167], v231 offset:6144
	s_mov_b32 m0, s8
	v_mfma_f32_16x16x32_bf16 v[34:37], v[184:187], v[176:179], v[34:37]
	global_load_lds_dwordx4 v200, s[4:5]
	s_add_u32 m0, s8, 0x400
	v_mfma_f32_16x16x32_bf16 v[38:41], v[188:191], v[176:179], v[38:41]
	global_load_lds_dwordx4 v201, s[4:5]
	s_add_u32 m0, s8, 0x800
	v_mfma_f32_16x16x32_bf16 v[42:45], v[192:195], v[176:179], v[42:45]
	global_load_lds_dwordx4 v202, s[4:5]
	s_add_u32 m0, s8, 0xc00
	v_mfma_f32_16x16x32_bf16 v[46:49], v[196:199], v[176:179], v[46:49]
	global_load_lds_dwordx4 v203, s[4:5]
	s_mov_b32 m0, s9
	v_mfma_f32_16x16x32_bf16 v[50:53], v[184:187], v[180:183], v[50:53]
	global_load_lds_dwordx4 v204, s[6:7]
	s_add_u32 m0, s9, 0x400
	v_mfma_f32_16x16x32_bf16 v[54:57], v[188:191], v[180:183], v[54:57]
	global_load_lds_dwordx4 v205, s[6:7]
	v_mfma_f32_16x16x32_bf16 v[58:61], v[192:195], v[180:183], v[58:61]
	s_sub_u32 s4, s4, 0x780
	s_subb_u32 s5, s5, 0
	v_mfma_f32_16x16x32_bf16 v[62:65], v[196:199], v[180:183], v[62:65]
	s_add_u32 s6, s6, 0x3f880
	s_addc_u32 s7, s7, 0
	s_waitcnt lgkmcnt(0)
	v_mfma_f32_16x16x32_bf16 v[2:5], v[152:155], v[136:139], v[2:5]
	ds_read_b128 v[168:171], v228 offset:0
	v_mfma_f32_16x16x32_bf16 v[6:9], v[156:159], v[136:139], v[6:9]
	ds_read_b128 v[172:175], v228 offset:2048
	v_mfma_f32_16x16x32_bf16 v[10:13], v[160:163], v[136:139], v[10:13]
	ds_read_b128 v[176:179], v228 offset:4096
	v_mfma_f32_16x16x32_bf16 v[14:17], v[164:167], v[136:139], v[14:17]
	ds_read_b128 v[180:183], v228 offset:6144
	v_mfma_f32_16x16x32_bf16 v[18:21], v[152:155], v[140:143], v[18:21]
	ds_read_b128 v[184:187], v234 offset:0
	v_mfma_f32_16x16x32_bf16 v[22:25], v[156:159], v[140:143], v[22:25]
	ds_read_b128 v[188:191], v234 offset:2048
	v_mfma_f32_16x16x32_bf16 v[26:29], v[160:163], v[140:143], v[26:29]
	ds_read_b128 v[192:195], v234 offset:4096
	v_mfma_f32_16x16x32_bf16 v[30:33], v[164:167], v[140:143], v[30:33]
	ds_read_b128 v[196:199], v234 offset:6144
	v_mfma_f32_16x16x32_bf16 v[34:37], v[152:155], v[144:147], v[34:37]
	v_mfma_f32_16x16x32_bf16 v[38:41], v[156:159], v[144:147], v[38:41]
	v_mfma_f32_16x16x32_bf16 v[42:45], v[160:163], v[144:147], v[42:45]
	v_mfma_f32_16x16x32_bf16 v[46:49], v[164:167], v[144:147], v[46:49]
	v_mfma_f32_16x16x32_bf16 v[50:53], v[152:155], v[148:151], v[50:53]
	v_mfma_f32_16x16x32_bf16 v[54:57], v[156:159], v[148:151], v[54:57]
	v_mfma_f32_16x16x32_bf16 v[58:61], v[160:163], v[148:151], v[58:61]
	v_mfma_f32_16x16x32_bf16 v[62:65], v[164:167], v[148:151], v[62:65]
	s_waitcnt vmcnt(6) lgkmcnt(0)
	s_barrier
	v_mfma_f32_16x16x32_bf16 v[2:5], v[184:187], v[168:171], v[2:5]
	ds_read_b128 v[136:139], v224 offset:0
	v_mfma_f32_16x16x32_bf16 v[6:9], v[188:191], v[168:171], v[6:9]
	ds_read_b128 v[140:143], v224 offset:2048
	v_mfma_f32_16x16x32_bf16 v[10:13], v[192:195], v[168:171], v[10:13]
	ds_read_b128 v[144:147], v224 offset:4096
	v_mfma_f32_16x16x32_bf16 v[14:17], v[196:199], v[168:171], v[14:17]
	ds_read_b128 v[148:151], v224 offset:6144
	v_mfma_f32_16x16x32_bf16 v[18:21], v[184:187], v[172:175], v[18:21]
	ds_read_b128 v[152:155], v232 offset:0
	v_mfma_f32_16x16x32_bf16 v[22:25], v[188:191], v[172:175], v[22:25]
	ds_read_b128 v[156:159], v232 offset:2048
	v_mfma_f32_16x16x32_bf16 v[26:29], v[192:195], v[172:175], v[26:29]
	ds_read_b128 v[160:163], v232 offset:4096
	v_mfma_f32_16x16x32_bf16 v[30:33], v[196:199], v[172:175], v[30:33]
	ds_read_b128 v[164:167], v232 offset:6144
	v_mfma_f32_16x16x32_bf16 v[34:37], v[184:187], v[176:179], v[34:37]
	v_mfma_f32_16x16x32_bf16 v[38:41], v[188:191], v[176:179], v[38:41]
	v_mfma_f32_16x16x32_bf16 v[42:45], v[192:195], v[176:179], v[42:45]
	v_mfma_f32_16x16x32_bf16 v[46:49], v[196:199], v[176:179], v[46:49]
	v_mfma_f32_16x16x32_bf16 v[50:53], v[184:187], v[180:183], v[50:53]
	v_mfma_f32_16x16x32_bf16 v[54:57], v[188:191], v[180:183], v[54:57]
	v_mfma_f32_16x16x32_bf16 v[58:61], v[192:195], v[180:183], v[58:61]
	v_mfma_f32_16x16x32_bf16 v[62:65], v[196:199], v[180:183], v[62:65]
	s_waitcnt lgkmcnt(0)
	v_mfma_f32_16x16x32_bf16 v[2:5], v[152:155], v[136:139], v[2:5]
	ds_read_b128 v[168:171], v229 offset:0
	v_mfma_f32_16x16x32_bf16 v[6:9], v[156:159], v[136:139], v[6:9]
	ds_read_b128 v[172:175], v229 offset:2048
	v_mfma_f32_16x16x32_bf16 v[10:13], v[160:163], v[136:139], v[10:13]
	ds_read_b128 v[176:179], v229 offset:4096
	v_mfma_f32_16x16x32_bf16 v[14:17], v[164:167], v[136:139], v[14:17]
	ds_read_b128 v[180:183], v229 offset:6144
	v_mfma_f32_16x16x32_bf16 v[18:21], v[152:155], v[140:143], v[18:21]
	ds_read_b128 v[184:187], v235 offset:0
	v_mfma_f32_16x16x32_bf16 v[22:25], v[156:159], v[140:143], v[22:25]
	ds_read_b128 v[188:191], v235 offset:2048
	v_mfma_f32_16x16x32_bf16 v[26:29], v[160:163], v[140:143], v[26:29]
	ds_read_b128 v[192:195], v235 offset:4096
	v_mfma_f32_16x16x32_bf16 v[30:33], v[164:167], v[140:143], v[30:33]
	ds_read_b128 v[196:199], v235 offset:6144
	v_mfma_f32_16x16x32_bf16 v[34:37], v[152:155], v[144:147], v[34:37]
	v_mfma_f32_16x16x32_bf16 v[38:41], v[156:159], v[144:147], v[38:41]
	v_mfma_f32_16x16x32_bf16 v[42:45], v[160:163], v[144:147], v[42:45]
	v_mfma_f32_16x16x32_bf16 v[46:49], v[164:167], v[144:147], v[46:49]
	v_mfma_f32_16x16x32_bf16 v[50:53], v[152:155], v[148:151], v[50:53]
	v_mfma_f32_16x16x32_bf16 v[54:57], v[156:159], v[148:151], v[54:57]
	v_mfma_f32_16x16x32_bf16 v[58:61], v[160:163], v[148:151], v[58:61]
	v_mfma_f32_16x16x32_bf16 v[62:65], v[164:167], v[148:151], v[62:65]
	s_waitcnt vmcnt(0) lgkmcnt(0)
	s_barrier
	v_mfma_f32_16x16x32_bf16 v[2:5], v[184:187], v[168:171], v[2:5]
	ds_read_b128 v[136:139], v218 offset:0
	v_mfma_f32_16x16x32_bf16 v[6:9], v[188:191], v[168:171], v[6:9]
	ds_read_b128 v[140:143], v218 offset:2048
	v_mfma_f32_16x16x32_bf16 v[10:13], v[192:195], v[168:171], v[10:13]
	ds_read_b128 v[144:147], v218 offset:4096
	v_mfma_f32_16x16x32_bf16 v[14:17], v[196:199], v[168:171], v[14:17]
	ds_read_b128 v[148:151], v218 offset:6144
	v_mfma_f32_16x16x32_bf16 v[18:21], v[184:187], v[172:175], v[18:21]
	ds_read_b128 v[152:155], v230 offset:0
	v_mfma_f32_16x16x32_bf16 v[22:25], v[188:191], v[172:175], v[22:25]
	ds_read_b128 v[156:159], v230 offset:2048
	v_mfma_f32_16x16x32_bf16 v[26:29], v[192:195], v[172:175], v[26:29]
	ds_read_b128 v[160:163], v230 offset:4096
	v_mfma_f32_16x16x32_bf16 v[30:33], v[196:199], v[172:175], v[30:33]
	ds_read_b128 v[164:167], v230 offset:6144
	v_mfma_f32_16x16x32_bf16 v[34:37], v[184:187], v[176:179], v[34:37]
	v_mfma_f32_16x16x32_bf16 v[38:41], v[188:191], v[176:179], v[38:41]
	v_mfma_f32_16x16x32_bf16 v[42:45], v[192:195], v[176:179], v[42:45]
	v_mfma_f32_16x16x32_bf16 v[46:49], v[196:199], v[176:179], v[46:49]
	v_mfma_f32_16x16x32_bf16 v[50:53], v[184:187], v[180:183], v[50:53]
	v_mfma_f32_16x16x32_bf16 v[54:57], v[188:191], v[180:183], v[54:57]
	v_mfma_f32_16x16x32_bf16 v[58:61], v[192:195], v[180:183], v[58:61]
	v_mfma_f32_16x16x32_bf16 v[62:65], v[196:199], v[180:183], v[62:65]
	s_waitcnt lgkmcnt(0)
	v_mfma_f32_16x16x32_bf16 v[2:5], v[152:155], v[136:139], v[2:5]
	ds_read_b128 v[168:171], v225 offset:0
	v_mfma_f32_16x16x32_bf16 v[6:9], v[156:159], v[136:139], v[6:9]
	ds_read_b128 v[172:175], v225 offset:2048
	v_mfma_f32_16x16x32_bf16 v[10:13], v[160:163], v[136:139], v[10:13]
	ds_read_b128 v[176:179], v225 offset:4096
	v_mfma_f32_16x16x32_bf16 v[14:17], v[164:167], v[136:139], v[14:17]
	ds_read_b128 v[180:183], v225 offset:6144
	v_mfma_f32_16x16x32_bf16 v[18:21], v[152:155], v[140:143], v[18:21]
	ds_read_b128 v[184:187], v233 offset:0
	v_mfma_f32_16x16x32_bf16 v[22:25], v[156:159], v[140:143], v[22:25]
	ds_read_b128 v[188:191], v233 offset:2048
	v_mfma_f32_16x16x32_bf16 v[26:29], v[160:163], v[140:143], v[26:29]
	ds_read_b128 v[192:195], v233 offset:4096
	v_mfma_f32_16x16x32_bf16 v[30:33], v[164:167], v[140:143], v[30:33]
	ds_read_b128 v[196:199], v233 offset:6144
	v_mfma_f32_16x16x32_bf16 v[34:37], v[152:155], v[144:147], v[34:37]
	v_mfma_f32_16x16x32_bf16 v[38:41], v[156:159], v[144:147], v[38:41]
	v_mfma_f32_16x16x32_bf16 v[42:45], v[160:163], v[144:147], v[42:45]
	v_mfma_f32_16x16x32_bf16 v[46:49], v[164:167], v[144:147], v[46:49]
	v_mfma_f32_16x16x32_bf16 v[50:53], v[152:155], v[148:151], v[50:53]
	v_mfma_f32_16x16x32_bf16 v[54:57], v[156:159], v[148:151], v[54:57]
	v_mfma_f32_16x16x32_bf16 v[58:61], v[160:163], v[148:151], v[58:61]
	v_mfma_f32_16x16x32_bf16 v[62:65], v[164:167], v[148:151], v[62:65]
	s_waitcnt lgkmcnt(0)
	v_mfma_f32_16x16x32_bf16 v[2:5], v[184:187], v[168:171], v[2:5]
	v_mfma_f32_16x16x32_bf16 v[6:9], v[188:191], v[168:171], v[6:9]
	v_mfma_f32_16x16x32_bf16 v[10:13], v[192:195], v[168:171], v[10:13]
	v_mfma_f32_16x16x32_bf16 v[14:17], v[196:199], v[168:171], v[14:17]
	v_mfma_f32_16x16x32_bf16 v[18:21], v[184:187], v[172:175], v[18:21]
	v_mfma_f32_16x16x32_bf16 v[22:25], v[188:191], v[172:175], v[22:25]
	v_mfma_f32_16x16x32_bf16 v[26:29], v[192:195], v[172:175], v[26:29]
	v_mfma_f32_16x16x32_bf16 v[30:33], v[196:199], v[172:175], v[30:33]
	v_mfma_f32_16x16x32_bf16 v[34:37], v[184:187], v[176:179], v[34:37]
	v_mfma_f32_16x16x32_bf16 v[38:41], v[188:191], v[176:179], v[38:41]
	v_mfma_f32_16x16x32_bf16 v[42:45], v[192:195], v[176:179], v[42:45]
	v_mfma_f32_16x16x32_bf16 v[46:49], v[196:199], v[176:179], v[46:49]
	v_mfma_f32_16x16x32_bf16 v[50:53], v[184:187], v[180:183], v[50:53]
	v_mfma_f32_16x16x32_bf16 v[54:57], v[188:191], v[180:183], v[54:57]
	v_mfma_f32_16x16x32_bf16 v[58:61], v[192:195], v[180:183], v[58:61]
	v_mfma_f32_16x16x32_bf16 v[62:65], v[196:199], v[180:183], v[62:65]
	s_nop 7
	s_add_u32 s10, s52, 0x0
	s_addc_u32 s11, s53, 0
	global_store_dwordx4 v237, v[2:5], s[10:11] offset:0 sc1
	global_store_dwordx4 v237, v[6:9], s[10:11] offset:64 sc1
	global_store_dwordx4 v237, v[10:13], s[10:11] offset:128 sc1
	global_store_dwordx4 v237, v[14:17], s[10:11] offset:192 sc1
	s_add_u32 s10, s10, 0x22000
	s_addc_u32 s11, s11, 0
	global_store_dwordx4 v237, v[18:21], s[10:11] offset:0 sc1
	global_store_dwordx4 v237, v[22:25], s[10:11] offset:64 sc1
	global_store_dwordx4 v237, v[26:29], s[10:11] offset:128 sc1
	global_store_dwordx4 v237, v[30:33], s[10:11] offset:192 sc1
	s_add_u32 s10, s10, 0x22000
	s_addc_u32 s11, s11, 0
	global_store_dwordx4 v237, v[34:37], s[10:11] offset:0 sc1
	global_store_dwordx4 v237, v[38:41], s[10:11] offset:64 sc1
	global_store_dwordx4 v237, v[42:45], s[10:11] offset:128 sc1
	global_store_dwordx4 v237, v[46:49], s[10:11] offset:192 sc1
	s_add_u32 s10, s10, 0x22000
	s_addc_u32 s11, s11, 0
	global_store_dwordx4 v237, v[50:53], s[10:11] offset:0 sc1
	global_store_dwordx4 v237, v[54:57], s[10:11] offset:64 sc1
	global_store_dwordx4 v237, v[58:61], s[10:11] offset:128 sc1
	global_store_dwordx4 v237, v[62:65], s[10:11] offset:192 sc1
.La1_done:
	s_waitcnt vmcnt(0)
	s_barrier
	v_readlane_b32 s50, v253, 2
	v_readlane_b32 s51, v253, 3
	s_lshl_b32 s22, s80, 2
	s_add_u32 s22, s22, 16
	s_add_u32 s50, s50, s22
	s_addc_u32 s51, s51, 0
	v_cmp_eq_u32_e32 vcc, 0, v0
	s_and_saveexec_b64 s[52:53], vcc
	v_mov_b32_e32 v1, 1
	global_atomic_add v131, v1, s[50:51]
	s_or_b64 exec, exec, s[52:53]
	v_mov_b32_e32 v238, s20
	v_mov_b32_e32 v239, s21
	v_mov_b32_e32 v1, 0x200f0
	ds_write_b64 v1, v[238:239]
	v_readlane_b32 s60, v254, 32
	v_readlane_b32 s54, v254, 34
	v_readlane_b32 s62, v254, 36
	v_readlane_b32 s70, v254, 38
	v_readlane_b32 s76, v254, 40
	v_readlane_b32 s86, v254, 42
	v_readlane_b32 s94, v254, 44
	v_readlane_b32 s58, v254, 46
	v_readlane_b32 s56, v254, 48
	v_readlane_b32 s61, v254, 33
	v_readlane_b32 s55, v254, 35
	v_readlane_b32 s63, v254, 37
	v_readlane_b32 s71, v254, 39
	v_readlane_b32 s77, v254, 41
	v_readlane_b32 s87, v254, 43
	v_readlane_b32 s95, v254, 45
	v_readlane_b32 s59, v254, 47
	v_readlane_b32 s57, v254, 49
	s_waitcnt lgkmcnt(0)
	s_branch .LBB0_419

.LBB0_472:
	v_mov_b32_e32 v8, v0
	ds_read2_b64 v[2:5], v131 offset0:17 offset1:18
	ds_read_b64 v[6:7], v131 offset:152
	s_mov_b32 s81, s97
	s_lshl_b64 s[0:1], s[80:81], 17
	v_readlane_b32 s4, v253, 34
	s_add_u32 s6, s4, s0
	v_readlane_b32 s0, v253, 35
	s_addc_u32 s7, s0, s1
	s_lshl_b32 s96, s80, 8
	s_waitcnt lgkmcnt(1)
	v_readfirstlane_b32 s1, v2
	s_lshl_b64 s[94:95], s[96:97], 2
	v_readfirstlane_b32 s0, v3
	s_add_u32 s24, s1, s94
	s_addc_u32 s25, s0, s95
	v_readfirstlane_b32 s0, v5
	v_readfirstlane_b32 s1, v4
	ds_read2_b64 v[2:5], v131 offset0:13 offset1:15
	v_and_b32_e32 v9, 15, v8
	v_lshrrev_b32_e32 v1, 2, v8
	v_and_or_b32 v1, v1, 16, v9
	v_bfe_u32 v10, v8, 4, 2
	v_ashrrev_i32_e32 v98, 7, v8
	s_add_u32 s10, s1, s94
	s_waitcnt lgkmcnt(0)
	v_readfirstlane_b32 s5, v2
	v_mul_u32_u24_e32 v2, 0x48, v1
	s_addc_u32 s11, s0, s95
	v_readfirstlane_b32 s1, v6
	v_readfirstlane_b32 s4, v3
	v_lshlrev_b32_e32 v2, 1, v2
	v_lshlrev_b32_e32 v130, 4, v10
	s_movk_i32 s73, 0xf0
	v_lshlrev_b32_e32 v3, 6, v98
	v_readfirstlane_b32 s0, v7
	s_add_u32 s14, s1, s94
	v_add3_u32 v101, s73, v2, v130
	v_or_b32_e32 v2, v3, v9
	v_lshl_or_b32 v6, v10, 2, v3
	v_add_u32_e32 v3, 0x200, v8
	s_addc_u32 s15, s0, s95
	s_lshl_b32 s0, s80, 9
	s_mov_b32 s1, s97
	v_ashrrev_i32_e32 v227, 7, v3
	v_add_u32_e32 v3, 0x400, v8
	s_mov_b32 s8, s0
	s_lshl_b64 s[0:1], s[0:1], 2
	v_ashrrev_i32_e32 v228, 7, v3
	v_add_u32_e32 v3, 0x600, v8
	s_add_u32 s20, s5, s0
	v_ashrrev_i32_e32 v229, 7, v3
	v_add_u32_e32 v3, 0x800, v8
	s_addc_u32 s21, s4, s1
	v_readfirstlane_b32 s5, v4
	v_ashrrev_i32_e32 v230, 7, v3
	v_add_u32_e32 v3, 0xa00, v8
	v_readfirstlane_b32 s4, v5
	s_add_u32 s22, s5, s0
	v_ashrrev_i32_e32 v231, 7, v3
	v_add_u32_e32 v3, 0xc00, v8
	v_writelane_b32 v254, s8, 59
	s_addc_u32 s23, s4, s1
	s_lshl_b64 s[12:13], s[80:81], 2
	v_readlane_b32 s0, v253, 36
	v_ashrrev_i32_e32 v232, 7, v3
	v_add_u32_e32 v3, 0xe00, v8
	v_writelane_b32 v254, s9, 60
	s_add_u32 s8, s0, s12
	v_readlane_b32 s0, v253, 37
	v_ashrrev_i32_e32 v233, 7, v3
	v_ashrrev_i32_e32 v3, 31, v2
	s_addc_u32 s9, s0, s13
	v_cmp_eq_u32_e64 s[0:1], 0, v8
	v_and_b32_e32 v100, 0x7f, v8
	v_lshl_add_u64 v[4:5], s[6:7], 0, v[130:131]
	v_lshlrev_b64 v[8:9], 7, v[2:3]
	v_lshl_add_u64 v[102:103], v[4:5], 0, v[8:9]
	v_or_b32_e32 v8, 16, v2
	v_ashrrev_i32_e32 v9, 31, v8
	v_lshlrev_b64 v[8:9], 7, v[8:9]
	v_lshl_add_u64 v[110:111], v[4:5], 0, v[8:9]
	v_or_b32_e32 v8, 32, v2
	v_or_b32_e32 v2, 48, v2
	v_ashrrev_i32_e32 v7, 31, v6
	v_ashrrev_i32_e32 v9, 31, v8
	v_ashrrev_i32_e32 v3, 31, v2
	v_lshlrev_b64 v[164:165], 2, v[6:7]
	v_lshlrev_b64 v[8:9], 7, v[8:9]
	v_lshlrev_b64 v[2:3], 7, v[2:3]
	v_lshl_add_u64 v[174:175], s[10:11], 0, v[164:165]
	v_readlane_b32 s10, v253, 28
	s_mov_b64 s[52:53], 0x10000
	v_lshl_add_u64 v[118:119], v[4:5], 0, v[8:9]
	v_lshl_add_u64 v[126:127], v[4:5], 0, v[2:3]
	v_readlane_b32 s11, v253, 29
	s_movk_i32 s62, 0x90
	s_mov_b64 s[50:51], 0x8000
	v_lshl_add_u64 v[106:107], v[102:103], 0, s[52:53]
	s_mov_b64 s[70:71], 0x18000
	v_lshl_add_u64 v[114:115], v[110:111], 0, s[52:53]
	v_lshl_add_u64 v[122:123], v[118:119], 0, s[52:53]
	v_lshl_add_u64 v[136:137], v[126:127], 0, s[52:53]
	s_mov_b64 s[52:53], 0x10040
	v_lshl_add_u64 v[182:183], s[10:11], 0, v[130:131]
	v_readlane_b32 s10, v253, 30
	v_lshl_add_u32 v11, v100, 1, v212
	v_cmp_eq_u32_e64 s[6:7], 0, v10
	v_mul_lo_u32 v10, v98, s62
	v_mul_lo_u32 v12, v227, s62
	v_mul_lo_u32 v13, v228, s62
	v_mul_lo_u32 v14, v229, s62
	v_mul_lo_u32 v15, v230, s62
	v_mul_lo_u32 v16, v231, s62
	v_mul_lo_u32 v17, v232, s62
	v_mul_lo_u32 v18, v233, s62
	v_lshl_add_u64 v[104:105], v[102:103], 0, s[50:51]
	v_lshl_add_u64 v[108:109], v[102:103], 0, s[70:71]
	v_lshl_add_u64 v[112:113], v[110:111], 0, s[50:51]
	v_lshl_add_u64 v[116:117], v[110:111], 0, s[70:71]
	v_lshl_add_u64 v[120:121], v[118:119], 0, s[50:51]
	v_lshl_add_u64 v[124:125], v[118:119], 0, s[70:71]
	v_lshl_add_u64 v[128:129], v[126:127], 0, s[50:51]
	v_lshl_add_u64 v[138:139], v[126:127], 0, s[70:71]
	s_mov_b64 s[50:51], 0x8040
	v_lshl_add_u64 v[142:143], v[102:103], 0, s[52:53]
	s_mov_b64 s[70:71], 0x18040
	v_lshl_add_u64 v[148:149], v[110:111], 0, s[52:53]
	v_lshl_add_u64 v[154:155], v[118:119], 0, s[52:53]
	v_lshl_add_u64 v[160:161], v[126:127], 0, s[52:53]
	v_lshl_add_u64 v[166:167], s[24:25], 0, v[164:165]
	v_or_b32_e32 v168, 16, v6
	v_or_b32_e32 v170, 32, v6
	v_or_b32_e32 v172, 48, v6
	v_readlane_b32 s11, v253, 31
	v_readlane_b32 s52, v253, 32
	v_readlane_b32 s24, v253, 39
	v_mov_b32_e32 v134, 0xbdc00
	v_mov_b32_e32 v133, 0xffc00
	v_mov_b32_e32 v132, 0x900
	v_mov_b32_e32 v222, 0x1800
	v_mov_b32_e32 v252, 0xc00
	v_mov_b32_e32 v223, 0xbe800
	v_cmp_lt_u32_e64 s[4:5], 63, v100
	v_ashrrev_i32_e32 v99, 31, v98
	v_lshl_add_u64 v[140:141], v[102:103], 0, s[50:51]
	v_lshl_add_u64 v[144:145], v[102:103], 0, s[70:71]
	v_lshl_add_u64 v[146:147], v[110:111], 0, s[50:51]
	v_lshl_add_u64 v[150:151], v[110:111], 0, s[70:71]
	v_lshl_add_u64 v[152:153], v[118:119], 0, s[50:51]
	v_lshl_add_u64 v[156:157], v[118:119], 0, s[70:71]
	v_lshl_add_u64 v[158:159], v[126:127], 0, s[50:51]
	v_lshl_add_u64 v[162:163], v[126:127], 0, s[70:71]
	v_ashrrev_i32_e32 v169, 31, v168
	v_ashrrev_i32_e32 v171, 31, v170
	v_ashrrev_i32_e32 v173, 31, v172
	v_add_u32_e32 v234, v11, v10
	v_add_u32_e32 v235, v11, v12
	v_add_u32_e32 v236, v11, v13
	v_add_u32_e32 v237, v11, v14
	v_add_u32_e32 v238, v11, v15
	v_add_u32_e32 v239, v11, v16
	v_add_u32_e32 v240, v11, v17
	v_add_u32_e32 v241, v11, v18
	v_mov_b32_e32 v242, 0
	v_lshl_add_u64 v[176:177], s[14:15], 0, v[164:165]
	v_lshl_add_u64 v[178:179], s[20:21], 0, v[164:165]
	v_lshl_add_u64 v[180:181], s[22:23], 0, v[164:165]
	v_lshl_add_u64 v[184:185], s[10:11], 0, v[130:131]
	v_readlane_b32 s53, v253, 33
	v_readlane_b32 s25, v253, 40
	v_readlane_b32 s50, v253, 42
	v_lshrrev_b32_e32 v255, 6, v0
	v_bfe_u32 v34, v0, 4, 2
	v_lshlrev_b32_e32 v255, 10, v255
	v_lshl_add_u32 v255, v34, 8, v255
	v_add_u32_e32 v255, 0x40f0, v255
	global_load_dwordx4 v[34:37], v[178:179], off
	global_load_dwordx4 v[38:41], v[178:179], off offset:64
	global_load_dwordx4 v[42:45], v[178:179], off offset:128
	global_load_dwordx4 v[46:49], v[178:179], off offset:192
	global_load_dwordx4 v[50:53], v[178:179], off offset:1024
	global_load_dwordx4 v[54:57], v[178:179], off offset:1088
	global_load_dwordx4 v[58:61], v[178:179], off offset:1152
	global_load_dwordx4 v[62:65], v[178:179], off offset:1216
	s_waitcnt vmcnt(0)
	ds_write_b128 v255, v[34:37]
	ds_write_b128 v255, v[38:41] offset:16
	ds_write_b128 v255, v[42:45] offset:32
	ds_write_b128 v255, v[46:49] offset:48
	ds_write_b128 v255, v[50:53] offset:64
	ds_write_b128 v255, v[54:57] offset:80
	ds_write_b128 v255, v[58:61] offset:96
	ds_write_b128 v255, v[62:65] offset:112
	global_load_dwordx4 v[34:37], v[180:181], off
	global_load_dwordx4 v[38:41], v[180:181], off offset:64
	global_load_dwordx4 v[42:45], v[180:181], off offset:128
	global_load_dwordx4 v[46:49], v[180:181], off offset:192
	global_load_dwordx4 v[50:53], v[180:181], off offset:1024
	global_load_dwordx4 v[54:57], v[180:181], off offset:1088
	global_load_dwordx4 v[58:61], v[180:181], off offset:1152
	global_load_dwordx4 v[62:65], v[180:181], off offset:1216
	s_waitcnt vmcnt(0)
	ds_write_b128 v255, v[34:37] offset:128
	ds_write_b128 v255, v[38:41] offset:144
	ds_write_b128 v255, v[42:45] offset:160
	ds_write_b128 v255, v[46:49] offset:176
	ds_write_b128 v255, v[50:53] offset:192
	ds_write_b128 v255, v[54:57] offset:208
	ds_write_b128 v255, v[58:61] offset:224
	ds_write_b128 v255, v[62:65] offset:240
	s_waitcnt lgkmcnt(0)
	s_cmp_lt_u32 s2, 64
	s_cbranch_scc1 .Ldf_b0skip
	s_branch .LBB0_474
.LBB0_473:
	s_or_b64 exec, exec, s[10:11]
	s_waitcnt vmcnt(0)
	s_barrier
	v_readfirstlane_b32 s14, v243
	s_and_b32 s14, s14, 0xffffffe0
	s_lshr_b32 s15, s14, 8
	s_sub_u32 s20, s14, 0x1000
	s_lshr_b32 s20, s20, 10
	s_add_u32 s20, s20, 16
	s_cmp_lt_u32 s14, 0x1000
	s_cselect_b32 s15, s15, s20
	s_lshl_b32 s14, s80, 5
	s_add_u32 s15, s15, s14
	s_add_u32 s15, s15, 8
	s_lshl_b32 s15, s15, 2
	v_readlane_b32 s20, v253, 2
	v_readlane_b32 s21, v253, 3
	s_nop 0
	s_add_u32 s20, s20, s15
	s_addc_u32 s21, s21, 0
	v_cmp_eq_u32_e32 vcc, 0, v0
	s_and_saveexec_b64 s[10:11], vcc
	v_mov_b32_e32 v2, 1
	global_atomic_add v131, v2, s[20:21]
	s_or_b64 exec, exec, s[10:11]

.LBB0_480:
	v_cmp_lt_i32_e32 vcc, s90, v2
	s_cbranch_vccnz .LBB0_515
	v_add_u32_e32 v2, 0x80, v2
	v_and_b32_e32 v2, 0xff, v2
	v_lshlrev_b32_e32 v10, 5, v2
	v_add_u32_e32 v4, v10, v98
	s_waitcnt lgkmcnt(0)
	v_mov_b64_e32 v[2:3], s[28:29]
	v_mad_i64_i32 v[2:3], s[10:11], v4, s36, v[2:3]
	v_lshlrev_b32_e32 v130, 2, v100
	v_lshl_add_u64 v[2:3], v[2:3], 0, v[130:131]
	v_add_co_u32_e32 v2, vcc, 0x1000, v2
	s_nop 1
	v_addc_co_u32_e32 v3, vcc, 0, v3, vcc
	s_barrier
	v_add_u32_e32 v4, v10, v98
	v_mov_b64_e32 v[42:43], s[28:29]
	v_mad_i64_i32 v[42:43], s[10:11], v4, s36, v[42:43]
	v_lshl_add_u64 v[42:43], v[42:43], 0, v[130:131]
	v_add_co_u32_e32 v42, vcc, 0x1000, v42
	s_nop 1
	v_addc_co_u32_e32 v43, vcc, 0, v43, vcc
	global_load_dword v34, v[42:43], off offset:1024
	v_add_u32_e32 v4, v10, v227
	v_mov_b64_e32 v[42:43], s[28:29]
	v_mad_i64_i32 v[42:43], s[10:11], v4, s36, v[42:43]
	v_lshl_add_u64 v[42:43], v[42:43], 0, v[130:131]
	v_add_co_u32_e32 v42, vcc, 0x1000, v42
	s_nop 1
	v_addc_co_u32_e32 v43, vcc, 0, v43, vcc
	global_load_dword v35, v[42:43], off offset:1024
	v_add_u32_e32 v4, v10, v228
	v_mov_b64_e32 v[42:43], s[28:29]
	v_mad_i64_i32 v[42:43], s[10:11], v4, s36, v[42:43]
	v_lshl_add_u64 v[42:43], v[42:43], 0, v[130:131]
	v_add_co_u32_e32 v42, vcc, 0x1000, v42
	s_nop 1
	v_addc_co_u32_e32 v43, vcc, 0, v43, vcc
	global_load_dword v36, v[42:43], off offset:1024
	v_add_u32_e32 v4, v10, v229
	v_mov_b64_e32 v[42:43], s[28:29]
	v_mad_i64_i32 v[42:43], s[10:11], v4, s36, v[42:43]
	v_lshl_add_u64 v[42:43], v[42:43], 0, v[130:131]
	v_add_co_u32_e32 v42, vcc, 0x1000, v42
	s_nop 1
	v_addc_co_u32_e32 v43, vcc, 0, v43, vcc
	global_load_dword v37, v[42:43], off offset:1024
	v_add_u32_e32 v4, v10, v230
	v_mov_b64_e32 v[42:43], s[28:29]
	v_mad_i64_i32 v[42:43], s[10:11], v4, s36, v[42:43]
	v_lshl_add_u64 v[42:43], v[42:43], 0, v[130:131]
	v_add_co_u32_e32 v42, vcc, 0x1000, v42
	s_nop 1
	v_addc_co_u32_e32 v43, vcc, 0, v43, vcc
	global_load_dword v38, v[42:43], off offset:1024
	v_add_u32_e32 v4, v10, v231
	v_mov_b64_e32 v[42:43], s[28:29]
	v_mad_i64_i32 v[42:43], s[10:11], v4, s36, v[42:43]
	v_lshl_add_u64 v[42:43], v[42:43], 0, v[130:131]
	v_add_co_u32_e32 v42, vcc, 0x1000, v42
	s_nop 1
	v_addc_co_u32_e32 v43, vcc, 0, v43, vcc
	global_load_dword v39, v[42:43], off offset:1024
	v_add_u32_e32 v4, v10, v232
	v_mov_b64_e32 v[42:43], s[28:29]
	v_mad_i64_i32 v[42:43], s[10:11], v4, s36, v[42:43]
	v_lshl_add_u64 v[42:43], v[42:43], 0, v[130:131]
	v_add_co_u32_e32 v42, vcc, 0x1000, v42
	s_nop 1
	v_addc_co_u32_e32 v43, vcc, 0, v43, vcc
	global_load_dword v40, v[42:43], off offset:1024
	v_add_u32_e32 v4, v10, v233
	v_mov_b64_e32 v[42:43], s[28:29]
	v_mad_i64_i32 v[42:43], s[10:11], v4, s36, v[42:43]
	v_lshl_add_u64 v[42:43], v[42:43], 0, v[130:131]
	v_add_co_u32_e32 v42, vcc, 0x1000, v42
	s_nop 1
	v_addc_co_u32_e32 v43, vcc, 0, v43, vcc
	global_load_dword v41, v[42:43], off offset:1024
	s_waitcnt vmcnt(7)
	v_mov_b32_e32 v2, v34
	s_and_saveexec_b64 s[10:11], s[4:5]
	s_xor_b64 s[10:11], exec, s[10:11]
	s_cbranch_execz .LBB0_483
	s_waitcnt vmcnt(0)
	v_cvt_pk_bf16_f32 v2, v2, v131
	ds_write_b16 v234, v2 offset:4480

.LBB0_513:
	s_or_b64 exec, exec, s[10:11]
	s_waitcnt lgkmcnt(0)
	s_barrier
	ds_read_b128 v[192:195], v101
	ds_read_b128 v[196:199], v101 offset:64
	ds_read_b128 v[244:247], v101 offset:4608
	ds_read_b128 v[248:251], v101 offset:4672
	global_load_dwordx4 v[94:97], v[102:103], off
	global_load_dwordx4 v[82:85], v[104:105], off
	global_load_dwordx4 v[90:93], v[106:107], off
	global_load_dwordx4 v[62:65], v[112:113], off
	global_load_dwordx4 v[18:21], v[126:127], off
	global_load_dwordx4 v[70:73], v[110:111], off
	global_load_dwordx4 v[42:45], v[118:119], off
	global_load_dwordx4 v[34:37], v[120:121], off
	global_load_dwordx4 v[2:5], v[128:129], off
	global_load_dwordx4 v[50:53], v[108:109], off
	global_load_dwordx4 v[38:41], v[122:123], off
	global_load_dwordx4 v[66:69], v[114:115], off
	global_load_dwordx4 v[30:33], v[124:125], off
	global_load_dwordx4 v[58:61], v[116:117], off
	global_load_dwordx4 v[14:17], v[136:137], off
	global_load_dwordx4 v[6:9], v[138:139], off
	global_load_dwordx4 v[22:25], v[102:103], off offset:64
	global_load_dwordx4 v[26:29], v[140:141], off
	global_load_dwordx4 v[46:49], v[142:143], off
	global_load_dwordx4 v[54:57], v[146:147], off
	global_load_dwordx4 v[74:77], v[126:127], off offset:64
	global_load_dwordx4 v[78:81], v[110:111], off offset:64
	global_load_dwordx4 v[86:89], v[118:119], off offset:64
	global_load_dwordx4 v[186:189], v[152:153], off
	v_or_b32_e32 v243, v10, v1
	v_cmp_gt_i32_e32 vcc, s37, v243
	v_cndmask_b32_e32 v11, v213, v214, vcc
	s_waitcnt lgkmcnt(0)
	s_waitcnt vmcnt(23)
	v_mfma_f32_16x16x32_bf16 v[94:97], v[94:97], v[192:195], 0
	s_waitcnt vmcnt(22)
	v_mfma_f32_16x16x32_bf16 v[82:85], v[82:85], v[192:195], 0
	s_waitcnt vmcnt(21)
	v_mfma_f32_16x16x32_bf16 v[90:93], v[90:93], v[244:247], 0
	s_waitcnt vmcnt(20)
	v_mfma_f32_16x16x32_bf16 v[62:65], v[62:65], v[192:195], 0
	s_waitcnt vmcnt(19)
	v_mfma_f32_16x16x32_bf16 v[18:21], v[18:21], v[192:195], 0
	s_waitcnt vmcnt(18)
	v_mfma_f32_16x16x32_bf16 v[70:73], v[70:73], v[192:195], 0
	s_waitcnt vmcnt(17)
	v_mfma_f32_16x16x32_bf16 v[42:45], v[42:45], v[192:195], 0
	s_waitcnt vmcnt(16)
	v_mfma_f32_16x16x32_bf16 v[34:37], v[34:37], v[192:195], 0
	s_waitcnt vmcnt(15)
	v_mfma_f32_16x16x32_bf16 v[2:5], v[2:5], v[192:195], 0
	s_waitcnt vmcnt(14)
	v_mfma_f32_16x16x32_bf16 v[50:53], v[50:53], v[244:247], 0
	s_waitcnt vmcnt(13)
	v_mfma_f32_16x16x32_bf16 v[38:41], v[38:41], v[244:247], 0
	s_waitcnt vmcnt(12)
	v_mfma_f32_16x16x32_bf16 v[66:69], v[66:69], v[244:247], 0
	s_waitcnt vmcnt(11)
	v_mfma_f32_16x16x32_bf16 v[30:33], v[30:33], v[244:247], 0
	s_waitcnt vmcnt(10)
	v_mfma_f32_16x16x32_bf16 v[58:61], v[58:61], v[244:247], 0
	s_waitcnt vmcnt(9)
	v_mfma_f32_16x16x32_bf16 v[14:17], v[14:17], v[244:247], 0
	s_waitcnt vmcnt(8)
	v_mfma_f32_16x16x32_bf16 v[6:9], v[6:9], v[244:247], 0
	s_waitcnt vmcnt(7)
	v_mfma_f32_16x16x32_bf16 v[94:97], v[22:25], v[196:199], v[94:97]
	global_load_dwordx4 v[22:25], v[158:159], off
	s_waitcnt vmcnt(7)
	v_mfma_f32_16x16x32_bf16 v[82:85], v[26:29], v[196:199], v[82:85]
	global_load_dwordx4 v[26:29], v[144:145], off
	s_waitcnt vmcnt(7)
	v_mfma_f32_16x16x32_bf16 v[90:93], v[46:49], v[248:251], v[90:93]
	global_load_dwordx4 v[46:49], v[154:155], off
	s_waitcnt vmcnt(7)
	v_mfma_f32_16x16x32_bf16 v[62:65], v[54:57], v[196:199], v[62:65]
	global_load_dwordx4 v[54:57], v[148:149], off
	s_waitcnt vmcnt(7)
	v_mfma_f32_16x16x32_bf16 v[18:21], v[74:77], v[196:199], v[18:21]
	global_load_dwordx4 v[74:77], v[156:157], off
	s_waitcnt vmcnt(7)
	v_mfma_f32_16x16x32_bf16 v[70:73], v[78:81], v[196:199], v[70:73]
	global_load_dwordx4 v[78:81], v[150:151], off
	s_waitcnt vmcnt(7)
	v_mfma_f32_16x16x32_bf16 v[42:45], v[86:89], v[196:199], v[42:45]
	global_load_dwordx4 v[86:89], v[160:161], off
	s_waitcnt vmcnt(7)
	v_mfma_f32_16x16x32_bf16 v[34:37], v[186:189], v[196:199], v[34:37]
	global_load_dwordx4 v[186:189], v[162:163], off
	s_waitcnt vmcnt(7)
	v_mfma_f32_16x16x32_bf16 v[2:5], v[22:25], v[196:199], v[2:5]
	s_waitcnt vmcnt(6)
	v_mfma_f32_16x16x32_bf16 v[50:53], v[26:29], v[248:251], v[50:53]
	s_waitcnt vmcnt(5)
	v_mfma_f32_16x16x32_bf16 v[38:41], v[46:49], v[248:251], v[38:41]
	s_waitcnt vmcnt(4)
	v_mfma_f32_16x16x32_bf16 v[66:69], v[54:57], v[248:251], v[66:69]
	s_waitcnt vmcnt(3)
	v_mfma_f32_16x16x32_bf16 v[30:33], v[74:77], v[248:251], v[30:33]
	s_waitcnt vmcnt(2)
	v_mfma_f32_16x16x32_bf16 v[58:61], v[78:81], v[248:251], v[58:61]
	s_waitcnt vmcnt(1)
	v_mfma_f32_16x16x32_bf16 v[14:17], v[86:89], v[248:251], v[14:17]
	s_waitcnt vmcnt(0)
	v_mfma_f32_16x16x32_bf16 v[6:9], v[186:189], v[248:251], v[6:9]
	v_cndmask_b32_e32 v12, v215, v216, vcc
	v_bitop3_b32 v130, v12, v10, v1 bitop3:0xe0
	v_mov_b64_e32 v[12:13], s[28:29]
	v_cndmask_b32_e64 v22, 10, 8, vcc
	v_and_b32_e32 v10, v11, v10
	v_mad_i64_i32 v[12:13], s[10:11], v243, s36, v[12:13]
	v_lshlrev_b64 v[22:23], v22, v[98:99]
	v_ashrrev_i32_e32 v11, 31, v10
	v_lshl_add_u64 v[22:23], v[22:23], 0, v[130:131]
	v_lshl_add_u64 v[190:191], v[12:13], 0, s[92:93]
	v_lshl_add_u64 v[204:205], v[10:11], 2, v[22:23]
	v_lshl_add_u64 v[10:11], v[190:191], 0, v[164:165]
	v_lshl_add_u64 v[188:189], v[12:13], 0, v[164:165]
	global_load_dwordx4 v[86:89], v[10:11], off
	global_load_dwordx4 v[46:49], v[188:189], off offset:3072
	flat_load_dwordx4 v[192:195], v[166:167]
	flat_load_dwordx4 v[196:199], v[166:167] offset:64
	global_load_dwordx4 v[54:57], v[188:189], off offset:3136
	global_load_dwordx4 v[26:29], v[188:189], off offset:3200
	flat_load_dwordx4 v[244:247], v[166:167] offset:128
	global_load_dwordx4 v[10:13], v[188:189], off offset:3264
	flat_load_dwordx4 v[248:251], v[166:167] offset:192
	global_load_dwordx4 v[74:77], v[188:189], off offset:2048
	flat_load_dwordx4 v[78:81], v[174:175]
	flat_load_dwordx4 v[22:25], v[176:177]
	v_mad_u64_u32 v[186:187], s[10:11], v204, s66, v[182:183]
	v_mad_i32_i24 v187, v205, s66, v187
	s_mov_b32 s10, 0x800000
	s_waitcnt vmcnt(0)
	global_store_dwordx4 v[186:187], v[86:89], off offset:512 sc1
	s_waitcnt lgkmcnt(0)
	s_nop 0
	v_pk_mul_f32 v[86:87], v[48:49], v[194:195]
	v_pk_mul_f32 v[224:225], v[46:47], v[192:193]
	v_pk_mul_f32 v[88:89], v[86:87], v[86:87]
	v_pk_mul_f32 v[192:193], v[224:225], v[224:225]
	v_pk_mul_f32 v[200:201], v[56:57], v[198:199]
	v_pk_mov_b32 v[194:195], v[192:193], v[88:89] op_sel:[1,0]
	v_mov_b32_e32 v193, v89
	v_pk_mul_f32 v[202:203], v[54:55], v[196:197]
	v_pk_add_f32 v[88:89], v[194:195], v[192:193]
	v_pk_mul_f32 v[192:193], v[200:201], v[200:201]
	v_pk_mul_f32 v[194:195], v[202:203], v[202:203]
	v_pk_mul_f32 v[198:199], v[26:27], v[244:245]
	v_pk_mov_b32 v[196:197], v[194:195], v[192:193] op_sel:[1,0]
	v_mov_b32_e32 v195, v193
	v_pk_add_f32 v[218:219], v[196:197], v[194:195]
	v_pk_mul_f32 v[194:195], v[10:11], v[248:249]
	v_pk_add_f32 v[88:89], v[88:89], v[88:89] op_sel:[0,1] op_sel_hi:[1,0]
	v_pk_add_f32 v[218:219], v[218:219], v[218:219] op_sel:[0,1] op_sel_hi:[1,0]
	v_pk_mul_f32 v[196:197], v[28:29], v[246:247]
	v_mul_f32_e32 v89, v194, v194
	v_mul_f32_e32 v219, v195, v195
	v_mul_f32_e32 v130, v199, v199
	v_pk_add_f32 v[88:89], v[88:89], v[218:219]
	v_pk_fma_f32 v[218:219], v[198:199], v[198:199], v[130:131] op_sel_hi:[1,1,0]
	v_mul_f32_e32 v130, v197, v197
	v_pk_mul_f32 v[192:193], v[12:13], v[250:251]
	v_pk_fma_f32 v[244:245], v[196:197], v[196:197], v[130:131] op_sel_hi:[1,1,0]
	v_mul_f32_e32 v219, v192, v192
	v_mul_f32_e32 v245, v193, v193
	v_pk_add_f32 v[218:219], v[218:219], v[244:245]
	v_xor_b32_e32 v130, 16, v217
	v_pk_add_f32 v[88:89], v[88:89], v[218:219]
	s_nop 0
	v_add_f32_e32 v88, v88, v89
	v_and_b32_e32 v89, 64, v217
	v_add_u32_e32 v89, 64, v89
	v_cmp_lt_i32_e32 vcc, v130, v89
	s_nop 1
	v_cndmask_b32_e32 v130, v217, v130, vcc
	v_lshlrev_b32_e32 v244, 2, v130
	ds_bpermute_b32 v130, v244, v88
	s_waitcnt lgkmcnt(0)
	v_add_f32_e32 v88, v88, v130
	v_xor_b32_e32 v130, 32, v217
	v_cmp_lt_i32_e32 vcc, v130, v89
	s_nop 1
	v_cndmask_b32_e32 v89, v217, v130, vcc
	v_lshlrev_b32_e32 v245, 2, v89
	ds_bpermute_b32 v89, v245, v88
	s_waitcnt lgkmcnt(0)
	v_add_f32_e32 v88, v88, v89
	v_add_f32_e32 v88, 0x2b8cbccc, v88
	v_mul_f32_e32 v89, 0x4b800000, v88
	v_cmp_gt_f32_e32 vcc, s10, v88
	s_nop 1
	v_cndmask_b32_e32 v88, v88, v89, vcc
	v_rsq_f32_e32 v88, v88
	s_nop 0
	v_mul_f32_e32 v89, 0x45800000, v88
	v_cndmask_b32_e32 v130, v88, v89, vcc
	v_pk_mul_f32 v[88:89], v[86:87], v[130:131] op_sel_hi:[1,0]
	v_pk_mul_f32 v[86:87], v[224:225], v[130:131] op_sel_hi:[1,0]
	global_store_dwordx4 v[186:187], v[74:77], off sc1
	global_store_dwordx4 v[186:187], v[86:89], off offset:256 sc1
	ds_read_b128 v[246:249], v255
	s_waitcnt lgkmcnt(0)
	v_add_f32_e32 v218, v94, v246
	v_add_f32_e32 v219, v95, v247
	v_add_f32_e32 v224, v96, v248
	v_add_f32_e32 v96, v97, v249
	ds_read_b128 v[246:249], v255 offset:128
	v_mul_f32_e32 v97, 0xbfb8aa3b, v218
	v_exp_f32_e32 v97, v97
	v_mad_u64_u32 v[94:95], s[10:11], v204, s66, v[184:185]
	v_mad_i32_i24 v95, v205, s66, v95
	v_add_f32_e32 v97, 1.0, v97
	s_nop 1
	v_mul_f32_e32 v224, 0xbfb8aa3b, v224
	v_exp_f32_e32 v224, v224
	v_mul_f32_e32 v96, 0xbfb8aa3b, v96
	s_nop 3
	v_add_f32_e32 v224, 1.0, v224
	v_exp_f32_e32 v96, v96
	s_waitcnt lgkmcnt(0)
	v_add_f32_e32 v90, v90, v246
	s_nop 3
	v_mul_f32_e32 v205, 0xbfb8aa3b, v219
	v_exp_f32_e32 v205, v205
	v_add_f32_e32 v91, v91, v247
	v_mul_f32_e32 v90, 0xbfb8aa3b, v90
	v_mul_f32_e32 v91, 0xbfb8aa3b, v91
	v_add_f32_e32 v205, 1.0, v205
	s_nop 1
	v_exp_f32_e32 v90, v90
	v_exp_f32_e32 v91, v91
	v_add_f32_e32 v92, v92, v248
	s_nop 6
	v_pk_add_f32 v[90:91], v[90:91], 1.0 op_sel_hi:[1,0]
	s_nop 2
	v_add_f32_e32 v93, v93, v249
	v_add_f32_e32 v96, 1.0, v96
	v_rcp_f32_e32 v204, v97
	s_nop 0
	v_mul_f32_e32 v97, s45, v204
	s_nop 7
	v_mul_f32_e32 v97, 0x3fb8aa3b, v97
	v_rcp_f32_e32 v218, v205
	s_nop 0
	v_mul_f32_e32 v204, s45, v218
	v_mul_f32_e32 v204, 0x3fb8aa3b, v204
	s_nop 7
	s_nop 0
	s_nop 7
	s_nop 0
	s_nop 7
	v_exp_f32_e32 v246, v97
	v_rcp_f32_e32 v248, v224
	s_nop 0
	v_mul_f32_e32 v97, s45, v248
	v_rcp_f32_e32 v249, v96
	s_nop 0
	v_mul_f32_e32 v96, s45, v249
	v_mul_f32_e32 v97, 0x3fb8aa3b, v97
	v_mul_f32_e32 v96, 0x3fb8aa3b, v96
	v_exp_f32_e32 v248, v97
	v_exp_f32_e32 v249, v96
	v_rcp_f32_e32 v97, v91
	s_nop 0
	v_rcp_f32_e32 v96, v90
	s_nop 0
	v_mul_f32_e32 v90, 0xbfb8aa3b, v92
	v_mul_f32_e32 v91, 0xbfb8aa3b, v93
	v_exp_f32_e32 v90, v90
	v_exp_f32_e32 v91, v91
	v_exp_f32_e32 v247, v204
	v_pk_add_f32 v[90:91], v[90:91], 1.0 op_sel_hi:[1,0]
	s_nop 0
	s_nop 1
	global_store_dwordx4 v[94:95], v[246:249], off sc1
	s_nop 7
	s_nop 0
	s_nop 7
	v_rcp_f32_e32 v205, v91
	s_nop 0
	v_rcp_f32_e32 v204, v90
	s_nop 0
	v_xor_b32_e32 v91, 0x80000000, v97
	v_xor_b32_e32 v90, 0x80000000, v96
	v_xor_b32_e32 v93, 0x80000000, v205
	v_xor_b32_e32 v92, 0x80000000, v204
	v_pk_mul_f32 v[92:93], v[88:89], v[92:93]
	v_pk_mul_f32 v[90:91], v[86:87], v[90:91]
	global_store_dwordx4 v[94:95], v[90:93], off offset:256 sc1
	s_nop 1
	v_pk_add_f32 v[90:91], v[96:97], -1.0 op_sel_hi:[1,0]
	v_pk_add_f32 v[92:93], v[204:205], -1.0 op_sel_hi:[1,0]
	v_pk_fma_f32 v[90:91], v[78:79], v[90:91], 1.0 op_sel_hi:[1,1,0]
	v_pk_fma_f32 v[92:93], v[80:81], v[92:93], 1.0 op_sel_hi:[1,1,0]
	v_pk_mul_f32 v[90:91], v[46:47], v[90:91]
	v_pk_mul_f32 v[92:93], v[48:49], v[92:93]
	global_store_dwordx4 v[94:95], v[90:93], off offset:512 sc1
	ds_read_b128 v[246:249], v255 offset:64
	s_waitcnt lgkmcnt(0)
	v_add_f32_e32 v96, v82, v246
	v_add_f32_e32 v97, v83, v247
	v_add_f32_e32 v204, v84, v248
	v_add_f32_e32 v205, v85, v249
	ds_read_b128 v[82:85], v255 offset:192
	s_waitcnt lgkmcnt(0)
	v_add_f32_e32 v50, v50, v82
	v_mul_f32_e32 v82, 0xbfb8aa3b, v96
	v_exp_f32_e32 v82, v82
	v_add_f32_e32 v52, v52, v84
	v_add_f32_e32 v51, v51, v83
	v_add_f32_e32 v53, v53, v85
	v_add_f32_e32 v84, 1.0, v82
	s_nop 1
	v_mul_f32_e32 v50, 0xbfb8aa3b, v50
	v_mul_f32_e32 v51, 0xbfb8aa3b, v51
	v_exp_f32_e32 v50, v50
	s_nop 7
	v_mul_f32_e32 v82, 0xbfb8aa3b, v97
	v_exp_f32_e32 v82, v82
	v_exp_f32_e32 v51, v51
	v_mul_f32_e32 v52, 0xbfb8aa3b, v52
	v_mul_f32_e32 v53, 0xbfb8aa3b, v53
	v_add_f32_e32 v96, 1.0, v82
	s_nop 1
	v_pk_add_f32 v[50:51], v[50:51], 1.0 op_sel_hi:[1,0]
	v_exp_f32_e32 v52, v52
	v_exp_f32_e32 v53, v53
	s_nop 7
	v_pk_add_f32 v[52:53], v[52:53], 1.0 op_sel_hi:[1,0]
	s_nop 7
	v_rcp_f32_e32 v51, v51
	s_nop 0
	v_mul_f32_e32 v82, 0xbfb8aa3b, v204
	v_exp_f32_e32 v82, v82
	s_nop 6
	v_add_f32_e32 v204, 1.0, v82
	s_nop 1
	v_rcp_f32_e32 v50, v50
	s_nop 0
	s_nop 0
	s_nop 0
	s_nop 7
	v_mul_f32_e32 v82, 0xbfb8aa3b, v205
	v_exp_f32_e32 v82, v82
	s_nop 0
	v_add_f32_e32 v205, 1.0, v82
	s_nop 1
	s_nop 0
	s_nop 7
	s_nop 0
	s_nop 7
	v_rcp_f32_e32 v53, v53
	s_nop 0
	s_mov_b32 s10, 0x1800000
	s_nop 7
	v_rcp_f32_e32 v52, v52
	s_nop 0
	v_pk_add_f32 v[82:83], v[50:51], -1.0 op_sel_hi:[1,0]
	v_xor_b32_e32 v51, 0x80000000, v51
	v_pk_fma_f32 v[78:79], v[78:79], v[82:83], 1.0 op_sel_hi:[1,1,0]
	v_pk_add_f32 v[82:83], v[52:53], -1.0 op_sel_hi:[1,0]
	v_pk_mul_f32 v[46:47], v[46:47], v[78:79]
	v_pk_fma_f32 v[80:81], v[80:81], v[82:83], 1.0 op_sel_hi:[1,1,0]
	v_rcp_f32_e32 v85, v84
	s_nop 0
	v_mul_f32_e32 v78, s45, v85
	v_pk_mul_f32 v[48:49], v[48:49], v[80:81]
	v_rcp_f32_e32 v97, v96
	s_nop 0
	v_mul_f32_e32 v79, s45, v97
	v_rcp_f32_e32 v218, v204
	s_nop 0
	v_mul_f32_e32 v80, s45, v218
	v_rcp_f32_e32 v219, v205
	s_nop 0
	v_mul_f32_e32 v81, s45, v219
	v_mul_f32_e32 v78, 0x3fb8aa3b, v78
	v_mul_f32_e32 v79, 0x3fb8aa3b, v79
	v_mul_f32_e32 v80, 0x3fb8aa3b, v80
	v_mul_f32_e32 v81, 0x3fb8aa3b, v81
	v_exp_f32_e32 v78, v78
	v_exp_f32_e32 v79, v79
	v_exp_f32_e32 v80, v80
	v_exp_f32_e32 v81, v81
	v_add_co_u32_e32 v82, vcc, s10, v94
	v_xor_b32_e32 v50, 0x80000000, v50
	v_xor_b32_e32 v53, 0x80000000, v53
	v_xor_b32_e32 v52, 0x80000000, v52
	v_addc_co_u32_e32 v83, vcc, 0, v95, vcc
	v_pk_mul_f32 v[52:53], v[88:89], v[52:53]
	v_pk_mul_f32 v[50:51], v[86:87], v[50:51]
	global_store_dwordx4 v[82:83], v[78:81], off sc1
	global_store_dwordx4 v[82:83], v[50:53], off offset:256 sc1
	v_mul_f32_e32 v88, v74, v46
	v_mul_f32_e32 v89, v75, v47
	global_store_dwordx4 v[82:83], v[46:49], off offset:512 sc1
	v_mul_f32_e32 v84, v74, v90
	v_mul_f32_e32 v85, v75, v91
	v_lshl_add_u64 v[46:47], v[168:169], 2, v[190:191]
	v_mul_f32_e32 v86, v76, v92
	v_mul_f32_e32 v87, v77, v93
	v_mul_f32_e32 v90, v76, v48
	v_mul_f32_e32 v91, v77, v49
	global_load_dwordx4 v[74:77], v[46:47], off
	s_nop 0
	global_load_dwordx4 v[46:49], v[188:189], off offset:2112
	flat_load_dwordx4 v[78:81], v[174:175] offset:64
	flat_load_dwordx4 v[50:53], v[176:177] offset:64
	s_waitcnt vmcnt(0)
	global_store_dwordx4 v[186:187], v[74:77], off offset:576 sc1
	s_nop 1
	v_pk_mul_f32 v[76:77], v[200:201], v[130:131] op_sel_hi:[1,0]
	v_pk_mul_f32 v[74:75], v[202:203], v[130:131] op_sel_hi:[1,0]
	global_store_dwordx4 v[186:187], v[46:49], off offset:64 sc1
	global_store_dwordx4 v[186:187], v[74:77], off offset:320 sc1
	ds_read_b128 v[200:203], v255 offset:16
	s_waitcnt lgkmcnt(0)
	v_add_f32_e32 v92, v70, v200
	v_add_f32_e32 v93, v71, v201
	v_add_f32_e32 v96, v72, v202
	v_add_f32_e32 v97, v73, v203
	ds_read_b128 v[70:73], v255 offset:144
	s_waitcnt lgkmcnt(0)
	v_add_f32_e32 v72, v68, v72
	v_mul_f32_e32 v68, 0xbfb8aa3b, v92
	v_exp_f32_e32 v68, v68
	v_add_f32_e32 v73, v69, v73
	v_add_f32_e32 v66, v66, v70
	v_add_f32_e32 v67, v67, v71
	v_add_f32_e32 v68, 1.0, v68
	s_nop 1
	v_mul_f32_e32 v66, 0xbfb8aa3b, v66
	v_mul_f32_e32 v67, 0xbfb8aa3b, v67
	v_exp_f32_e32 v66, v66
	s_nop 7
	v_mul_f32_e32 v70, 0xbfb8aa3b, v93
	v_exp_f32_e32 v70, v70
	v_exp_f32_e32 v67, v67
	v_add_f32_e32 v92, 1.0, v70
	s_nop 1
	s_nop 0
	s_nop 7
	v_pk_add_f32 v[70:71], v[66:67], 1.0 op_sel_hi:[1,0]
	s_nop 0
	s_nop 1
	s_nop 0
	s_nop 7
	v_rcp_f32_e32 v71, v71
	s_nop 0
	s_nop 7
	v_mul_f32_e32 v66, 0xbfb8aa3b, v96
	v_exp_f32_e32 v66, v66
	v_rcp_f32_e32 v70, v70
	s_nop 0
	v_add_f32_e32 v96, 1.0, v66
	s_nop 1
	s_nop 0
	s_nop 7
	v_mul_f32_e32 v66, 0xbfb8aa3b, v97
	v_exp_f32_e32 v66, v66
	s_nop 0
	v_add_f32_e32 v97, 1.0, v66
	s_nop 1
	s_nop 0
	s_nop 7
	v_rcp_f32_e32 v69, v68
	s_nop 0
	v_mul_f32_e32 v66, s45, v69
	v_rcp_f32_e32 v93, v92
	s_nop 0
	v_mul_f32_e32 v67, s45, v93
	v_rcp_f32_e32 v202, v96
	s_nop 0
	v_mul_f32_e32 v68, s45, v202
	v_rcp_f32_e32 v203, v97
	s_nop 0
	v_mul_f32_e32 v69, s45, v203
	v_mul_f32_e32 v66, 0x3fb8aa3b, v66
	v_mul_f32_e32 v67, 0x3fb8aa3b, v67
	v_mul_f32_e32 v68, 0x3fb8aa3b, v68
	v_mul_f32_e32 v69, 0x3fb8aa3b, v69
	v_exp_f32_e32 v66, v66
	v_exp_f32_e32 v67, v67
	v_exp_f32_e32 v68, v68
	v_exp_f32_e32 v69, v69
	global_store_dwordx4 v[94:95], v[66:69], off offset:64 sc1
	s_nop 1
	v_mul_f32_e32 v66, 0xbfb8aa3b, v72
	v_mul_f32_e32 v67, 0xbfb8aa3b, v73
	v_exp_f32_e32 v66, v66
	v_exp_f32_e32 v67, v67
	s_nop 0
	v_pk_add_f32 v[66:67], v[66:67], 1.0 op_sel_hi:[1,0]
	s_nop 0
	s_nop 1
	s_nop 0
	s_nop 7
	s_nop 0
	s_nop 7
	v_rcp_f32_e32 v73, v67
	s_nop 0
	v_rcp_f32_e32 v72, v66
	s_nop 0
	v_xor_b32_e32 v67, 0x80000000, v71
	v_xor_b32_e32 v66, 0x80000000, v70
	v_xor_b32_e32 v69, 0x80000000, v73
	v_xor_b32_e32 v68, 0x80000000, v72
	v_pk_mul_f32 v[68:69], v[76:77], v[68:69]
	v_pk_mul_f32 v[66:67], v[74:75], v[66:67]
	global_store_dwordx4 v[94:95], v[66:69], off offset:320 sc1
	s_nop 1
	v_pk_add_f32 v[66:67], v[70:71], -1.0 op_sel_hi:[1,0]
	v_pk_add_f32 v[68:69], v[72:73], -1.0 op_sel_hi:[1,0]
	v_pk_fma_f32 v[66:67], v[78:79], v[66:67], 1.0 op_sel_hi:[1,1,0]
	v_pk_fma_f32 v[68:69], v[80:81], v[68:69], 1.0 op_sel_hi:[1,1,0]
	v_pk_mul_f32 v[66:67], v[54:55], v[66:67]
	v_pk_mul_f32 v[68:69], v[56:57], v[68:69]
	global_store_dwordx4 v[94:95], v[66:69], off offset:576 sc1
	ds_read_b128 v[70:73], v255 offset:80
	s_waitcnt lgkmcnt(0)
	v_add_f32_e32 v70, v62, v70
	v_add_f32_e32 v71, v63, v71
	v_add_f32_e32 v72, v64, v72
	v_add_f32_e32 v73, v65, v73
	ds_read_b128 v[62:65], v255 offset:208
	s_waitcnt lgkmcnt(0)
	v_add_f32_e32 v58, v58, v62
	v_mul_f32_e32 v62, 0xbfb8aa3b, v70
	v_exp_f32_e32 v62, v62
	v_add_f32_e32 v59, v59, v63
	v_add_f32_e32 v60, v60, v64
	v_add_f32_e32 v61, v61, v65
	v_add_f32_e32 v70, 1.0, v62
	s_nop 1
	v_mul_f32_e32 v58, 0xbfb8aa3b, v58
	v_mul_f32_e32 v59, 0xbfb8aa3b, v59
	v_exp_f32_e32 v58, v58
	s_nop 7
	v_mul_f32_e32 v62, 0xbfb8aa3b, v71
	v_exp_f32_e32 v62, v62
	v_exp_f32_e32 v59, v59
	v_mul_f32_e32 v60, 0xbfb8aa3b, v60
	v_mul_f32_e32 v61, 0xbfb8aa3b, v61
	v_add_f32_e32 v71, 1.0, v62
	s_nop 1
	v_pk_add_f32 v[58:59], v[58:59], 1.0 op_sel_hi:[1,0]
	v_exp_f32_e32 v60, v60
	v_exp_f32_e32 v61, v61
	s_nop 7
	v_pk_add_f32 v[60:61], v[60:61], 1.0 op_sel_hi:[1,0]
	s_nop 7
	v_rcp_f32_e32 v59, v59
	s_nop 0
	v_mul_f32_e32 v62, 0xbfb8aa3b, v72
	v_exp_f32_e32 v62, v62
	s_nop 6
	v_add_f32_e32 v72, 1.0, v62
	s_nop 1
	v_rcp_f32_e32 v58, v58
	s_nop 0
	s_nop 0
	s_nop 0
	s_nop 7
	v_mul_f32_e32 v62, 0xbfb8aa3b, v73
	v_exp_f32_e32 v62, v62
	s_nop 0
	v_add_f32_e32 v73, 1.0, v62
	s_nop 1
	s_nop 0
	s_nop 7
	s_nop 0
	s_nop 7
	v_rcp_f32_e32 v61, v61
	s_nop 0
	s_nop 7
	v_rcp_f32_e32 v60, v60
	s_nop 0
	v_pk_add_f32 v[62:63], v[58:59], -1.0 op_sel_hi:[1,0]
	v_pk_add_f32 v[64:65], v[60:61], -1.0 op_sel_hi:[1,0]
	v_pk_fma_f32 v[62:63], v[78:79], v[62:63], 1.0 op_sel_hi:[1,1,0]
	v_pk_fma_f32 v[64:65], v[80:81], v[64:65], 1.0 op_sel_hi:[1,1,0]
	v_pk_mul_f32 v[54:55], v[54:55], v[62:63]
	v_pk_mul_f32 v[56:57], v[56:57], v[64:65]
	v_rcp_f32_e32 v92, v70
	s_nop 0
	v_mul_f32_e32 v62, s45, v92
	v_rcp_f32_e32 v93, v71
	s_nop 0
	v_mul_f32_e32 v63, s45, v93
	v_rcp_f32_e32 v96, v72
	s_nop 0
	v_mul_f32_e32 v64, s45, v96
	v_rcp_f32_e32 v97, v73
	s_nop 0
	v_mul_f32_e32 v65, s45, v97
	v_mul_f32_e32 v62, 0x3fb8aa3b, v62
	v_mul_f32_e32 v63, 0x3fb8aa3b, v63
	v_mul_f32_e32 v64, 0x3fb8aa3b, v64
	v_mul_f32_e32 v65, 0x3fb8aa3b, v65
	v_exp_f32_e32 v62, v62
	v_exp_f32_e32 v63, v63
	v_exp_f32_e32 v64, v64
	v_exp_f32_e32 v65, v65
	v_xor_b32_e32 v59, 0x80000000, v59
	v_xor_b32_e32 v58, 0x80000000, v58
	v_xor_b32_e32 v61, 0x80000000, v61
	v_xor_b32_e32 v60, 0x80000000, v60
	v_pk_mul_f32 v[58:59], v[74:75], v[58:59]
	v_pk_mul_f32 v[60:61], v[76:77], v[60:61]
	global_store_dwordx4 v[82:83], v[62:65], off offset:64 sc1
	global_store_dwordx4 v[82:83], v[58:61], off offset:320 sc1
	global_store_dwordx4 v[82:83], v[54:57], off offset:576 sc1
	s_nop 0
	v_lshl_add_u64 v[58:59], v[170:171], 2, v[190:191]
	global_load_dwordx4 v[70:73], v[58:59], off
	s_nop 0
	global_load_dwordx4 v[58:61], v[188:189], off offset:2176
	flat_load_dwordx4 v[74:77], v[174:175] offset:128
	flat_load_dwordx4 v[62:65], v[176:177] offset:128
	s_waitcnt vmcnt(0)
	global_store_dwordx4 v[186:187], v[70:73], off offset:640 sc1
	s_nop 1
	v_pk_mul_f32 v[72:73], v[196:197], v[130:131] op_sel_hi:[1,0]
	v_pk_mul_f32 v[70:71], v[198:199], v[130:131] op_sel_hi:[1,0]
	global_store_dwordx4 v[186:187], v[58:61], off offset:128 sc1
	global_store_dwordx4 v[186:187], v[70:73], off offset:384 sc1
	ds_read_b128 v[78:81], v255 offset:32
	s_waitcnt lgkmcnt(0)
	v_add_f32_e32 v78, v42, v78
	v_add_f32_e32 v79, v43, v79
	v_add_f32_e32 v80, v44, v80
	v_add_f32_e32 v81, v45, v81
	ds_read_b128 v[42:45], v255 offset:160
	s_waitcnt lgkmcnt(0)
	v_add_f32_e32 v44, v40, v44
	v_mul_f32_e32 v40, 0xbfb8aa3b, v78
	v_exp_f32_e32 v40, v40
	v_add_f32_e32 v45, v41, v45
	v_add_f32_e32 v38, v38, v42
	v_add_f32_e32 v39, v39, v43
	v_add_f32_e32 v40, 1.0, v40
	s_nop 1
	v_mul_f32_e32 v38, 0xbfb8aa3b, v38
	v_mul_f32_e32 v39, 0xbfb8aa3b, v39
	v_exp_f32_e32 v38, v38
	s_nop 7
	v_mul_f32_e32 v42, 0xbfb8aa3b, v79
	v_exp_f32_e32 v42, v42
	v_exp_f32_e32 v39, v39
	v_add_f32_e32 v78, 1.0, v42
	s_nop 1
	s_nop 0
	s_nop 7
	v_pk_add_f32 v[42:43], v[38:39], 1.0 op_sel_hi:[1,0]
	s_nop 0
	s_nop 1
	s_nop 0
	s_nop 7
	v_rcp_f32_e32 v43, v43
	s_nop 0
	s_nop 7
	v_mul_f32_e32 v38, 0xbfb8aa3b, v80
	v_exp_f32_e32 v38, v38
	v_rcp_f32_e32 v42, v42
	s_nop 0
	v_add_f32_e32 v80, 1.0, v38
	s_nop 1
	s_nop 0
	s_nop 7
	v_mul_f32_e32 v38, 0xbfb8aa3b, v81
	v_exp_f32_e32 v38, v38
	s_nop 0
	v_add_f32_e32 v81, 1.0, v38
	s_nop 1
	s_nop 0
	s_nop 7
	v_rcp_f32_e32 v41, v40
	s_nop 0
	v_mul_f32_e32 v38, s45, v41
	v_rcp_f32_e32 v79, v78
	s_nop 0
	v_mul_f32_e32 v39, s45, v79
	v_rcp_f32_e32 v96, v80
	s_nop 0
	v_mul_f32_e32 v40, s45, v96
	v_rcp_f32_e32 v97, v81
	s_nop 0
	v_mul_f32_e32 v41, s45, v97
	v_mul_f32_e32 v38, 0x3fb8aa3b, v38
	v_mul_f32_e32 v39, 0x3fb8aa3b, v39
	v_mul_f32_e32 v40, 0x3fb8aa3b, v40
	v_mul_f32_e32 v41, 0x3fb8aa3b, v41
	v_exp_f32_e32 v38, v38
	v_exp_f32_e32 v39, v39
	v_exp_f32_e32 v40, v40
	v_exp_f32_e32 v41, v41
	global_store_dwordx4 v[94:95], v[38:41], off offset:128 sc1
	s_nop 1
	v_mul_f32_e32 v38, 0xbfb8aa3b, v44
	v_mul_f32_e32 v39, 0xbfb8aa3b, v45
	v_exp_f32_e32 v38, v38
	v_exp_f32_e32 v39, v39
	s_nop 0
	v_pk_add_f32 v[38:39], v[38:39], 1.0 op_sel_hi:[1,0]
	s_nop 0
	s_nop 1
	s_nop 0
	s_nop 7
	s_nop 0
	s_nop 7
	v_rcp_f32_e32 v45, v39
	s_nop 0
	v_rcp_f32_e32 v44, v38
	s_nop 0
	v_xor_b32_e32 v39, 0x80000000, v43
	v_xor_b32_e32 v38, 0x80000000, v42
	v_xor_b32_e32 v41, 0x80000000, v45
	v_xor_b32_e32 v40, 0x80000000, v44
	v_pk_mul_f32 v[40:41], v[72:73], v[40:41]
	v_pk_mul_f32 v[38:39], v[70:71], v[38:39]
	global_store_dwordx4 v[94:95], v[38:41], off offset:384 sc1
	s_nop 1
	v_pk_add_f32 v[38:39], v[42:43], -1.0 op_sel_hi:[1,0]
	v_pk_add_f32 v[40:41], v[44:45], -1.0 op_sel_hi:[1,0]
	v_pk_fma_f32 v[38:39], v[74:75], v[38:39], 1.0 op_sel_hi:[1,1,0]
	v_pk_fma_f32 v[40:41], v[76:77], v[40:41], 1.0 op_sel_hi:[1,1,0]
	v_pk_mul_f32 v[38:39], v[26:27], v[38:39]
	v_pk_mul_f32 v[40:41], v[28:29], v[40:41]
	global_store_dwordx4 v[94:95], v[38:41], off offset:640 sc1
	ds_read_b128 v[42:45], v255 offset:96
	s_waitcnt lgkmcnt(0)
	v_add_f32_e32 v42, v34, v42
	v_add_f32_e32 v43, v35, v43
	v_add_f32_e32 v44, v36, v44
	v_add_f32_e32 v45, v37, v45
	ds_read_b128 v[34:37], v255 offset:224
	s_waitcnt lgkmcnt(0)
	v_add_f32_e32 v30, v30, v34
	v_mul_f32_e32 v34, 0xbfb8aa3b, v42
	v_exp_f32_e32 v34, v34
	v_add_f32_e32 v31, v31, v35
	v_add_f32_e32 v32, v32, v36
	v_add_f32_e32 v33, v33, v37
	v_add_f32_e32 v42, 1.0, v34
	s_nop 1
	v_mul_f32_e32 v30, 0xbfb8aa3b, v30
	v_mul_f32_e32 v31, 0xbfb8aa3b, v31
	v_exp_f32_e32 v30, v30
	s_nop 7
	v_mul_f32_e32 v34, 0xbfb8aa3b, v43
	v_exp_f32_e32 v34, v34
	v_exp_f32_e32 v31, v31
	v_mul_f32_e32 v32, 0xbfb8aa3b, v32
	v_mul_f32_e32 v33, 0xbfb8aa3b, v33
	v_add_f32_e32 v43, 1.0, v34
	s_nop 1
	v_pk_add_f32 v[30:31], v[30:31], 1.0 op_sel_hi:[1,0]
	v_exp_f32_e32 v32, v32
	v_exp_f32_e32 v33, v33
	s_nop 7
	v_pk_add_f32 v[32:33], v[32:33], 1.0 op_sel_hi:[1,0]
	s_nop 7
	v_rcp_f32_e32 v31, v31
	s_nop 0
	v_mul_f32_e32 v34, 0xbfb8aa3b, v44
	v_exp_f32_e32 v34, v34
	s_nop 6
	v_add_f32_e32 v44, 1.0, v34
	s_nop 1
	v_rcp_f32_e32 v30, v30
	s_nop 0
	s_nop 0
	s_nop 0
	s_nop 7
	v_mul_f32_e32 v34, 0xbfb8aa3b, v45
	v_exp_f32_e32 v34, v34
	s_nop 0
	v_add_f32_e32 v45, 1.0, v34
	s_nop 1
	s_nop 0
	s_nop 7
	s_nop 0
	s_nop 7
	v_rcp_f32_e32 v33, v33
	s_nop 0
	s_nop 7
	v_rcp_f32_e32 v32, v32
	s_nop 0
	v_pk_add_f32 v[34:35], v[30:31], -1.0 op_sel_hi:[1,0]
	v_pk_add_f32 v[36:37], v[32:33], -1.0 op_sel_hi:[1,0]
	v_pk_fma_f32 v[34:35], v[74:75], v[34:35], 1.0 op_sel_hi:[1,1,0]
	v_pk_fma_f32 v[36:37], v[76:77], v[36:37], 1.0 op_sel_hi:[1,1,0]
	v_pk_mul_f32 v[74:75], v[26:27], v[34:35]
	v_pk_mul_f32 v[76:77], v[28:29], v[36:37]
	v_xor_b32_e32 v27, 0x80000000, v31
	v_xor_b32_e32 v26, 0x80000000, v30
	v_xor_b32_e32 v29, 0x80000000, v33
	v_xor_b32_e32 v28, 0x80000000, v32
	v_rcp_f32_e32 v78, v42
	s_nop 0
	v_mul_f32_e32 v30, s45, v78
	v_rcp_f32_e32 v79, v43
	s_nop 0
	v_mul_f32_e32 v31, s45, v79
	v_rcp_f32_e32 v80, v44
	s_nop 0
	v_mul_f32_e32 v32, s45, v80
	v_rcp_f32_e32 v81, v45
	s_nop 0
	v_mul_f32_e32 v33, s45, v81
	v_mul_f32_e32 v30, 0x3fb8aa3b, v30
	v_mul_f32_e32 v31, 0x3fb8aa3b, v31
	v_mul_f32_e32 v32, 0x3fb8aa3b, v32
	v_mul_f32_e32 v33, 0x3fb8aa3b, v33
	v_exp_f32_e32 v30, v30
	v_exp_f32_e32 v31, v31
	v_exp_f32_e32 v32, v32
	v_exp_f32_e32 v33, v33
	v_pk_mul_f32 v[28:29], v[72:73], v[28:29]
	v_pk_mul_f32 v[26:27], v[70:71], v[26:27]
	global_store_dwordx4 v[82:83], v[30:33], off offset:128 sc1
	global_store_dwordx4 v[82:83], v[26:29], off offset:384 sc1
	global_store_dwordx4 v[82:83], v[74:77], off offset:640 sc1
	v_lshl_add_u64 v[30:31], v[172:173], 2, v[190:191]
	global_load_dwordx4 v[70:73], v[30:31], off
	s_nop 0
	global_load_dwordx4 v[30:33], v[188:189], off offset:2240
	flat_load_dwordx4 v[42:45], v[174:175] offset:192
	flat_load_dwordx4 v[34:37], v[176:177] offset:192
	v_pk_mul_f32 v[28:29], v[192:193], v[130:131] op_sel_hi:[1,0]
	v_pk_mul_f32 v[26:27], v[194:195], v[130:131] op_sel_hi:[1,0]
	s_waitcnt vmcnt(0)
	global_store_dwordx4 v[186:187], v[70:73], off offset:704 sc1
	global_store_dwordx4 v[186:187], v[30:33], off offset:192 sc1
	global_store_dwordx4 v[186:187], v[26:29], off offset:448 sc1
	ds_read_b128 v[70:73], v255 offset:48
	s_waitcnt lgkmcnt(0)
	v_add_f32_e32 v70, v18, v70
	v_add_f32_e32 v71, v19, v71
	v_add_f32_e32 v72, v20, v72
	v_add_f32_e32 v73, v21, v73
	ds_read_b128 v[18:21], v255 offset:176
	s_waitcnt lgkmcnt(0)
	v_add_f32_e32 v15, v15, v19
	v_add_f32_e32 v19, v16, v20
	v_mul_f32_e32 v16, 0xbfb8aa3b, v70
	v_exp_f32_e32 v16, v16
	v_add_f32_e32 v78, v17, v21
	v_add_f32_e32 v14, v14, v18
	v_fma_f32 v18, v22, v84, 0
	v_add_f32_e32 v16, 1.0, v16
	s_nop 1
	v_fmac_f32_e32 v18, v23, v85
	v_fmac_f32_e32 v18, v24, v86
	v_fmac_f32_e32 v18, v25, v87
	s_nop 2
	v_fmac_f32_e32 v18, v22, v88
	s_nop 0
	v_fmac_f32_e32 v18, v23, v89
	s_nop 3
	v_mul_f32_e32 v20, 0xbfb8aa3b, v71
	v_exp_f32_e32 v20, v20
	v_mul_f32_e32 v14, 0xbfb8aa3b, v14
	v_mul_f32_e32 v15, 0xbfb8aa3b, v15
	v_fmac_f32_e32 v18, v24, v90
	v_add_f32_e32 v22, 1.0, v20
	s_nop 1
	v_exp_f32_e32 v14, v14
	v_exp_f32_e32 v15, v15
	v_fmac_f32_e32 v18, v25, v91
	s_nop 7
	v_pk_add_f32 v[20:21], v[14:15], 1.0 op_sel_hi:[1,0]
	s_nop 0
	s_nop 1
	s_nop 0
	s_nop 7
	v_rcp_f32_e32 v21, v21
	s_nop 0
	s_nop 7
	v_mul_f32_e32 v14, 0xbfb8aa3b, v72
	v_exp_f32_e32 v14, v14
	v_rcp_f32_e32 v20, v20
	s_nop 0
	v_add_f32_e32 v70, 1.0, v14
	s_nop 1
	s_nop 0
	s_nop 7
	v_mul_f32_e32 v14, 0xbfb8aa3b, v73
	v_exp_f32_e32 v14, v14
	s_nop 0
	v_add_f32_e32 v72, 1.0, v14
	s_nop 1
	s_nop 0
	s_nop 7
	v_rcp_f32_e32 v17, v16
	s_nop 0
	v_mul_f32_e32 v14, s45, v17
	v_rcp_f32_e32 v23, v22
	s_nop 0
	v_mul_f32_e32 v15, s45, v23
	v_rcp_f32_e32 v71, v70
	s_nop 0
	v_mul_f32_e32 v16, s45, v71
	v_rcp_f32_e32 v73, v72
	s_nop 0
	v_mul_f32_e32 v17, s45, v73
	v_mul_f32_e32 v14, 0x3fb8aa3b, v14
	v_mul_f32_e32 v15, 0x3fb8aa3b, v15
	v_mul_f32_e32 v16, 0x3fb8aa3b, v16
	v_mul_f32_e32 v17, 0x3fb8aa3b, v17
	v_exp_f32_e32 v14, v14
	v_exp_f32_e32 v15, v15
	v_exp_f32_e32 v16, v16
	v_exp_f32_e32 v17, v17
	global_store_dwordx4 v[94:95], v[14:17], off offset:192 sc1
	s_nop 1
	v_mul_f32_e32 v14, 0xbfb8aa3b, v19
	v_mul_f32_e32 v15, 0xbfb8aa3b, v78
	v_exp_f32_e32 v14, v14
	v_exp_f32_e32 v15, v15
	s_nop 0
	v_pk_add_f32 v[14:15], v[14:15], 1.0 op_sel_hi:[1,0]
	s_nop 0
	s_nop 1
	s_nop 0
	s_nop 7
	s_nop 0
	s_nop 7
	v_rcp_f32_e32 v23, v15
	s_nop 0
	v_rcp_f32_e32 v22, v14
	s_nop 0
	v_xor_b32_e32 v15, 0x80000000, v21
	v_xor_b32_e32 v14, 0x80000000, v20
	v_xor_b32_e32 v17, 0x80000000, v23
	v_xor_b32_e32 v16, 0x80000000, v22
	v_pk_mul_f32 v[16:17], v[28:29], v[16:17]
	v_pk_mul_f32 v[14:15], v[26:27], v[14:15]
	global_store_dwordx4 v[94:95], v[14:17], off offset:448 sc1
	v_mul_f32_e32 v19, v46, v66
	v_fmac_f32_e32 v18, v50, v19
	v_pk_add_f32 v[14:15], v[20:21], -1.0 op_sel_hi:[1,0]
	v_mul_f32_e32 v19, v47, v67
	v_pk_fma_f32 v[14:15], v[42:43], v[14:15], 1.0 op_sel_hi:[1,1,0]
	v_fmac_f32_e32 v18, v51, v19
	v_pk_mul_f32 v[20:21], v[10:11], v[14:15]
	v_pk_add_f32 v[14:15], v[22:23], -1.0 op_sel_hi:[1,0]
	v_mul_f32_e32 v19, v48, v68
	v_pk_fma_f32 v[14:15], v[44:45], v[14:15], 1.0 op_sel_hi:[1,1,0]
	v_fmac_f32_e32 v18, v52, v19
	v_pk_mul_f32 v[22:23], v[12:13], v[14:15]
	global_store_dwordx4 v[94:95], v[20:23], off offset:704 sc1
	ds_read_b128 v[14:17], v255 offset:112
	v_mul_f32_e32 v19, v49, v69
	ds_read_b128 v[66:69], v255 offset:240
	v_fmac_f32_e32 v18, v53, v19
	v_mul_f32_e32 v19, v46, v54
	v_fmac_f32_e32 v18, v50, v19
	v_mul_f32_e32 v19, v47, v55
	v_fmac_f32_e32 v18, v51, v19
	v_mul_f32_e32 v19, v48, v56
	v_fmac_f32_e32 v18, v52, v19
	v_mul_f32_e32 v19, v49, v57
	v_fmac_f32_e32 v18, v53, v19
	v_mul_f32_e32 v19, v58, v38
	v_fmac_f32_e32 v18, v62, v19
	v_mul_f32_e32 v19, v59, v39
	v_fmac_f32_e32 v18, v63, v19
	v_mul_f32_e32 v19, v60, v40
	v_fmac_f32_e32 v18, v64, v19
	v_mul_f32_e32 v19, v61, v41
	v_fmac_f32_e32 v18, v65, v19
	v_mul_f32_e32 v19, v58, v74
	v_fmac_f32_e32 v18, v62, v19
	v_mul_f32_e32 v19, v59, v75
	v_fmac_f32_e32 v18, v63, v19
	v_mul_f32_e32 v19, v60, v76
	v_fmac_f32_e32 v18, v64, v19
	v_mul_f32_e32 v19, v61, v77
	v_fmac_f32_e32 v18, v65, v19
	v_mul_f32_e32 v19, v30, v20
	v_fmac_f32_e32 v18, v34, v19
	s_waitcnt lgkmcnt(0)
	v_add_f32_e32 v2, v2, v14
	v_mul_f32_e32 v2, 0xbfb8aa3b, v2
	v_exp_f32_e32 v2, v2
	v_mul_f32_e32 v14, v31, v21
	v_fmac_f32_e32 v18, v35, v14
	v_mul_f32_e32 v14, v32, v22
	v_add_f32_e32 v2, 1.0, v2
	s_nop 1
	v_add_f32_e32 v3, v3, v15
	v_fmac_f32_e32 v18, v36, v14
	v_mul_f32_e32 v14, v33, v23
	v_mul_f32_e32 v3, 0xbfb8aa3b, v3
	v_fmac_f32_e32 v18, v37, v14
	s_nop 0
	v_exp_f32_e32 v3, v3
	s_nop 4
	v_add_f32_e32 v15, 1.0, v3
	s_nop 0
	v_div_scale_f32 v19, s[10:11], v15, v15, s45
	s_nop 0
	v_rcp_f32_e32 v20, v19
	v_rcp_f32_e32 v14, v2
	s_nop 0
	v_mul_f32_e32 v2, s45, v14
	v_mul_f32_e32 v2, 0x3fb8aa3b, v2
	v_exp_f32_e32 v14, v2
	v_fma_f32 v3, -v19, v20, 1.0
	v_add_f32_e32 v2, v6, v66
	v_fmac_f32_e32 v20, v3, v20
	v_div_scale_f32 v6, vcc, s45, v15, s45
	v_mul_f32_e32 v21, v6, v20
	v_fma_f32 v3, -v19, v21, v6
	v_fmac_f32_e32 v21, v3, v20
	v_add_f32_e32 v3, v7, v67
	v_mul_f32_e32 v2, 0xbfb8aa3b, v2
	v_mul_f32_e32 v3, 0xbfb8aa3b, v3
	v_exp_f32_e32 v2, v2
	v_exp_f32_e32 v3, v3
	v_fma_f32 v6, -v19, v21, v6
	v_div_fmas_f32 v6, v6, v20, v21
	v_div_fixup_f32 v6, v6, v15, s45
	v_pk_add_f32 v[2:3], v[2:3], 1.0 op_sel_hi:[1,0]
	v_mul_f32_e32 v6, 0x3fb8aa3b, v6
	s_nop 1
	v_exp_f32_e32 v15, v6
	v_add_f32_e32 v4, v4, v16
	v_mul_f32_e32 v4, 0xbfb8aa3b, v4
	s_nop 7
	v_rcp_f32_e32 v3, v3
	s_nop 0
	v_exp_f32_e32 v4, v4
	s_nop 7
	v_rcp_f32_e32 v2, v2
	s_nop 0
	v_pk_add_f32 v[6:7], v[2:3], -1.0 op_sel_hi:[1,0]
	v_add_f32_e32 v4, 1.0, v4
	v_pk_fma_f32 v[6:7], v[42:43], v[6:7], 1.0 op_sel_hi:[1,1,0]
	v_add_f32_e32 v5, v5, v17
	v_pk_mul_f32 v[6:7], v[10:11], v[6:7]
	s_nop 1
	v_mul_f32_e32 v10, v30, v6
	v_fmac_f32_e32 v18, v34, v10
	v_mul_f32_e32 v10, v31, v7
	v_fmac_f32_e32 v18, v35, v10
	s_nop 3
	v_mul_f32_e32 v5, 0xbfb8aa3b, v5
	s_nop 0
	v_exp_f32_e32 v5, v5
	s_nop 2
	v_rcp_f32_e32 v10, v4
	s_nop 0
	v_mul_f32_e32 v4, s45, v10
	v_add_f32_e32 v10, 1.0, v5
	v_div_scale_f32 v11, s[10:11], v10, v10, s45
	v_rcp_f32_e32 v17, v11
	v_mul_f32_e32 v4, 0x3fb8aa3b, v4
	v_exp_f32_e32 v16, v4
	v_add_f32_e32 v4, v8, v68
	v_fma_f32 v5, -v11, v17, 1.0
	v_fmac_f32_e32 v17, v5, v17
	v_div_scale_f32 v8, vcc, s45, v10, s45
	v_mul_f32_e32 v19, v8, v17
	v_fma_f32 v5, -v11, v19, v8
	v_fmac_f32_e32 v19, v5, v17
	v_add_f32_e32 v5, v9, v69
	v_mul_f32_e32 v4, 0xbfb8aa3b, v4
	v_mul_f32_e32 v5, 0xbfb8aa3b, v5
	v_exp_f32_e32 v4, v4
	v_exp_f32_e32 v5, v5
	v_fma_f32 v8, -v11, v19, v8
	v_div_fmas_f32 v8, v8, v17, v19
	v_div_fixup_f32 v8, v8, v10, s45
	v_pk_add_f32 v[4:5], v[4:5], 1.0 op_sel_hi:[1,0]
	v_mul_f32_e32 v8, 0x3fb8aa3b, v8
	s_nop 1
	v_exp_f32_e32 v17, v8
	s_nop 7
	v_rcp_f32_e32 v5, v5
	s_nop 0
	s_nop 7
	v_rcp_f32_e32 v4, v4
	s_nop 0
	v_pk_add_f32 v[8:9], v[4:5], -1.0 op_sel_hi:[1,0]
	v_xor_b32_e32 v11, 0x80000000, v3
	v_pk_fma_f32 v[8:9], v[44:45], v[8:9], 1.0 op_sel_hi:[1,1,0]
	s_nop 0
	v_pk_mul_f32 v[8:9], v[12:13], v[8:9]
	s_nop 0
	v_mul_f32_e32 v10, v32, v8
	v_fmac_f32_e32 v18, v36, v10
	v_mul_f32_e32 v3, v33, v9
	v_fmac_f32_e32 v18, v37, v3
	ds_bpermute_b32 v19, v244, v18
	v_xor_b32_e32 v10, 0x80000000, v2
	v_xor_b32_e32 v3, 0x80000000, v5
	v_xor_b32_e32 v2, 0x80000000, v4
	v_pk_mul_f32 v[12:13], v[28:29], v[2:3]
	s_waitcnt lgkmcnt(0)
	v_add_f32_e32 v2, v18, v19
	ds_bpermute_b32 v3, v245, v2
	v_pk_mul_f32 v[10:11], v[26:27], v[10:11]
	global_store_dwordx4 v[82:83], v[14:17], off offset:192 sc1
	global_store_dwordx4 v[82:83], v[10:13], off offset:448 sc1
	global_store_dwordx4 v[82:83], v[6:9], off offset:704 sc1
	s_and_saveexec_b64 s[10:11], s[6:7]
	s_cbranch_execz .LBB0_473
	s_waitcnt lgkmcnt(0)
	v_add_f32_e32 v4, v2, v3
	v_lshl_add_u32 v2, v243, 2, v98
	v_ashrrev_i32_e32 v3, 31, v2
	v_lshl_add_u64 v[2:3], v[2:3], 2, s[52:53]
	global_store_dword v[2:3], v4, off sc1
	s_branch .LBB0_473

.Ldf_b0skip:
	s_waitcnt vmcnt(0)
	s_waitcnt lgkmcnt(0)
	s_barrier
	s_mov_b64 s[0:1], exec
	v_readlane_b32 s4, v253, 0
	v_readlane_b32 s5, v253, 1
	s_and_b64 s[4:5], s[0:1], s[4:5]
	s_mov_b64 exec, s[4:5]
	s_branch .LBB0_568
	s_getreg_b32 s4, hwreg(HW_REG_XCC_ID, 0, 4)
	s_and_b32 s10, s4, 15
	v_readlane_b32 s4, v254, 25
	s_waitcnt vmcnt(0) expcnt(0) lgkmcnt(0)
	s_nop 0
	v_mov_b32_e32 v1, s4
	ds_read_b32 v3, v1
	v_readlane_b32 s4, v254, 23
	s_waitcnt lgkmcnt(0)
	v_cmp_ne_u32_e32 vcc, 0, v3
	v_mov_b32_e32 v1, s4
	ds_read_b32 v2, v1
	s_cbranch_vccnz .LBB0_532
	v_readlane_b32 s6, v253, 5
	v_readlane_b32 s7, v253, 6
	s_load_dwordx2 s[4:5], s[6:7], 0x4
	s_mov_b32 s14, 1
	s_waitcnt lgkmcnt(0)
	s_mul_i32 s11, s4, s65
	s_mul_i32 s11, s11, s5
	s_branch .LBB0_520

.Lsc_decoded:
	s_bfe_u32 s24, s20, 0x10001
	s_cmp_eq_u32 s0, 4
	s_cbranch_scc0 .Lsc_nopoll
	s_lshr_b32 s1, s21, 2
	s_add_u32 s4, s1, 16
	s_cmp_lt_u32 s71, 64
	s_cselect_b32 s1, s4, s1
	s_cselect_b32 s5, 32, 8
	s_lshl_b32 s4, s80, 5
	s_add_u32 s1, s1, s4
	s_add_u32 s1, s1, 8
	s_lshl_b32 s1, s1, 2
	v_readlane_b32 s6, v253, 2
	v_readlane_b32 s7, v253, 3
	s_nop 0
	s_add_u32 s6, s6, s1
	s_addc_u32 s7, s7, 0
	s_mov_b32 s4, 0
.Lsc_poll:
	global_load_dword v2, v131, s[6:7] sc1
	s_waitcnt vmcnt(0)
	v_readfirstlane_b32 s1, v2
	s_cmp_ge_u32 s1, s5
	s_cbranch_scc1 .Lsc_polled
	s_sleep 16
	s_add_u32 s4, s4, 1
	s_cmp_lt_u32 s4, 0x1388
	s_cbranch_scc1 .Lsc_poll

.Lsc_nopoll:
	s_barrier
	s_cmp_ge_u32 s0, 4
	s_cbranch_scc1 .Lsc_loader
	s_and_b32 s22, s20, 1
	s_lshl_b32 s22, s22, 5
	s_lshl_b32 s1, s0, 3
	s_add_u32 s22, s22, s1
	v_and_b32_e32 v116, 15, v0
	v_bfe_u32 v117, v0, 4, 2
	v_lshlrev_b32_e32 v111, 4, v116
	v_add_u32_e32 v118, s22, v117
	v_add_u32_e32 v111, 0xf0, v111
	v_lshlrev_b32_e32 v112, 2, v118
	v_add_u32_e32 v112, 0x2f0, v112
	v_lshlrev_b32_e32 v114, 8, v118
	v_lshl_add_u32 v114, v116, 4, v114
	s_lshr_b32 s1, s21, 2
	s_and_b32 s4, s21, 3
	s_lshl_b32 s1, s1, 1
	s_add_u32 s1, s1, s80
	s_lshl_b32 s1, s1, 1
	s_add_u32 s1, s1, s24
	s_lshl_b32 s1, s1, 2
	s_add_u32 s1, s1, s4
	s_lshl_b32 s1, s1, 14
	s_cmp_lt_u32 s71, 64
	s_cbranch_scc0 .Lsc_ctx_init
	ds_read_b64 v[120:121], v131 offset:32
	s_waitcnt lgkmcnt(0)
	v_readfirstlane_b32 s4, v120
	v_readfirstlane_b32 s5, v121
	s_nop 3
	s_add_u32 s4, s4, s1
	s_addc_u32 s5, s5, 0
	s_nop 3
	global_load_dwordx4 v[2:5], v114, s[4:5]
	global_load_dwordx4 v[6:9], v114, s[4:5] offset:1024
	s_lshl_b32 s6, s21, 2
	s_lshr_b32 s6, s21, 2
	s_lshl_b32 s6, s6, 20
	s_add_u32 s6, s6, 0x400000
	s_branch .Lsc_init_done

.Lsc_done:
.LBB0_597:
	v_readlane_b32 s0, v253, 53
	s_add_u32 s4, s0, s12
	v_readlane_b32 s0, v253, 54
	s_addc_u32 s5, s0, s13
	v_writelane_b32 v254, s4, 61
	s_lshl_b32 s0, s80, 2
	s_lshl_b32 s96, s80, 14
	v_writelane_b32 v254, s5, 62
	v_writelane_b32 v254, s0, 63
	s_lshl_b64 s[0:1], s[96:97], 2
	v_cmp_eq_u32_e64 s[8:9], 0, v1
	v_writelane_b32 v255, s0, 0
	v_readlane_b32 s79, v254, 50
	v_mov_b64_e32 v[132:133], 0x1ff
	v_writelane_b32 v255, s1, 1
	v_mov_b64_e32 v[134:135], 0x200
	v_readfirstlane_b32 s0, v0
	s_cmp_lt_u32 s0, 64
	s_cbranch_scc0 .Ldf_qgo
	v_readlane_b32 s4, v253, 2
	v_readlane_b32 s5, v253, 3
	s_lshl_b32 s1, s80, 2
	s_add_u32 s1, s1, 16
	s_add_u32 s4, s4, s1
	s_addc_u32 s5, s5, 0
	s_mov_b32 s6, 0
.Ldf_qpoll:
	global_load_dword v2, v131, s[4:5] sc1
	s_waitcnt vmcnt(0)
	v_readfirstlane_b32 s1, v2
	s_cmpk_ge_u32 s1, 0xa0
	s_cbranch_scc1 .Ldf_qok
	s_sleep 16
	s_add_u32 s6, s6, 1
	s_cmp_lt_u32 s6, 0x1388
	s_cbranch_scc1 .Ldf_qpoll
.Ldf_qok:
	buffer_inv sc1
	s_waitcnt vmcnt(0)
.Ldf_qgo:
	s_waitcnt lgkmcnt(0)
	s_barrier
	s_branch .LBB0_601
.LBB0_598:
	v_add_u32_e32 v2, s53, v101
	v_ashrrev_i32_e32 v3, 31, v2
	v_or_b32_e32 v1, s60, v103
	v_lshlrev_b64 v[2:3], 11, v[2:3]
	v_lshl_add_u64 v[4:5], s[30:31], 0, v[2:3]
	v_lshlrev_b32_e32 v130, 1, v1
	v_lshl_add_u64 v[4:5], v[4:5], 0, v[130:131]
	global_load_dwordx2 v[6:7], v[4:5], off offset:1024
	ds_bpermute_b32 v1, v105, v118
	v_readlane_b32 s60, v254, 32
	v_readlane_b32 s54, v254, 34
	v_readlane_b32 s58, v254, 46
	v_readlane_b32 s56, v254, 48
	s_waitcnt lgkmcnt(0)
	v_add_f32_e32 v1, v118, v1
	ds_bpermute_b32 v8, v119, v1
	v_readlane_b32 s52, v253, 32
	v_readlane_b32 s61, v254, 33
	v_readlane_b32 s55, v254, 35
	v_readlane_b32 s59, v254, 47
	s_waitcnt lgkmcnt(0)
	v_add_f32_e32 v1, v1, v8
	v_add_f32_e32 v1, v107, v1
	v_div_scale_f32 v8, s[0:1], v1, v1, 1.0
	v_rcp_f32_e32 v9, v8
	s_waitcnt vmcnt(0)
	v_div_scale_f32 v10, vcc, 1.0, v1, 1.0
	v_readlane_b32 s0, v253, 55
	v_fma_f32 v11, -v8, v9, 1.0
	v_fmac_f32_e32 v9, v11, v9
	v_mul_f32_e32 v11, v10, v9
	v_fma_f32 v12, -v8, v11, v10
	v_fmac_f32_e32 v11, v12, v9
	v_fma_f32 v8, -v8, v11, v10
	v_div_fmas_f32 v8, v8, v9, v11
	v_div_fixup_f32 v1, v8, v1, 1.0
	v_mul_f32_e32 v8, v54, v1
	v_mul_f32_e32 v9, v55, v1
	v_mul_f32_e32 v10, v56, v1
	v_mul_f32_e32 v11, v57, v1
	v_readlane_b32 s1, v253, 56
	v_readlane_b32 s57, v254, 49
	v_readlane_b32 s53, v253, 33
	v_lshl_add_u64 v[2:3], s[0:1], 0, v[2:3]
	v_lshl_add_u64 v[2:3], v[2:3], 0, v[130:131]
	v_readlane_b32 s79, v254, 50
	s_mov_b32 s64, s44
	s_movk_i32 s73, 0xf0
	s_movk_i32 s62, 0x90
	v_lshlrev_b32_e32 v12, 16, v6
	v_and_b32_e32 v6, 0xffff0000, v6
	v_lshlrev_b32_e32 v13, 16, v7
	v_and_b32_e32 v7, 0xffff0000, v7
	v_mul_f32_e32 v8, v8, v12
	v_mul_f32_e32 v6, v9, v6
	v_mul_f32_e32 v9, v10, v13
	v_mul_f32_e32 v7, v11, v7
	v_cvt_pk_bf16_f32 v6, v8, v6
	v_cvt_pk_bf16_f32 v7, v9, v7
	global_load_dwordx2 v[8:9], v[4:5], off offset:1056
	v_mul_f32_e32 v10, v46, v1
	v_mul_f32_e32 v11, v47, v1
	v_mul_f32_e32 v12, v48, v1
	v_mul_f32_e32 v13, v49, v1
	global_store_dwordx2 v[2:3], v[6:7], off offset:1024
	s_waitcnt vmcnt(1)
	v_lshlrev_b32_e32 v6, 16, v8
	v_and_b32_e32 v7, 0xffff0000, v8
	v_lshlrev_b32_e32 v8, 16, v9
	v_and_b32_e32 v9, 0xffff0000, v9
	v_mul_f32_e32 v6, v10, v6
	v_mul_f32_e32 v7, v11, v7
	v_mul_f32_e32 v8, v12, v8
	v_mul_f32_e32 v9, v13, v9
	v_cvt_pk_bf16_f32 v6, v6, v7
	v_cvt_pk_bf16_f32 v7, v8, v9
	global_load_dwordx2 v[8:9], v[4:5], off offset:1088
	v_mul_f32_e32 v10, v42, v1
	v_mul_f32_e32 v11, v43, v1
	global_store_dwordx2 v[2:3], v[6:7], off offset:1056
	v_mul_f32_e32 v12, v44, v1
	v_mul_f32_e32 v13, v45, v1
	s_waitcnt vmcnt(1)
	v_lshlrev_b32_e32 v6, 16, v8
	v_and_b32_e32 v7, 0xffff0000, v8
	v_lshlrev_b32_e32 v8, 16, v9
	v_and_b32_e32 v9, 0xffff0000, v9
	v_mul_f32_e32 v6, v10, v6
	v_mul_f32_e32 v7, v11, v7
	v_mul_f32_e32 v8, v12, v8
	v_mul_f32_e32 v9, v13, v9
	v_cvt_pk_bf16_f32 v6, v6, v7
	v_cvt_pk_bf16_f32 v7, v8, v9
	global_load_dwordx2 v[4:5], v[4:5], off offset:1120
	v_mul_f32_e32 v9, v51, v1
	global_store_dwordx2 v[2:3], v[6:7], off offset:1088
	v_mul_f32_e32 v8, v50, v1
	v_mul_f32_e32 v10, v52, v1
	v_mul_f32_e32 v1, v53, v1
	s_waitcnt vmcnt(1)
	v_lshlrev_b32_e32 v6, 16, v4
	v_and_b32_e32 v4, 0xffff0000, v4
	v_lshlrev_b32_e32 v7, 16, v5
	v_and_b32_e32 v5, 0xffff0000, v5
	v_mul_f32_e32 v4, v9, v4
	v_mul_f32_e32 v6, v8, v6
	v_mul_f32_e32 v7, v10, v7
	v_mul_f32_e32 v1, v1, v5
	v_cvt_pk_bf16_f32 v4, v6, v4
	v_cvt_pk_bf16_f32 v5, v7, v1
	global_store_dwordx2 v[2:3], v[4:5], off offset:1120
